# v sweep: counted waits per row (vmcnt 19/18/17/16 before rows 0..3 of a batch) instead of one wait for the whole batch
# baseline (speedup 1.0000x reference)
.LV_t0_s0:
	s_cmp_ge_u32 s21, s20
	s_cbranch_scc1 .LV_done
	s_waitcnt lgkmcnt(0)
	buffer_load_dwordx4 v[192:195], v[232:233], s[60:63], 0 idxen offen
	buffer_load_dwordx4 v[196:199], v[234:235], s[60:63], 0 idxen offen
	buffer_load_dwordx4 v[200:203], v[236:237], s[60:63], 0 idxen offen
	buffer_load_dwordx4 v[204:207], v[238:239], s[60:63], 0 idxen offen
	ds_read_b32 v232, v213 offset:80
	ds_read_b32 v234, v213 offset:84
	ds_read_b32 v236, v213 offset:88
	ds_read_b32 v238, v213 offset:92
	ds_read_b128 v[252:255], v213 offset:5008
	s_waitcnt vmcnt(19)
	v_cvt_pk_f32_fp8_e32 v[224:225], v128
	v_cvt_pk_f32_fp8_sdwa v[226:227], v128 src0_sel:WORD_1
	v_cvt_pk_f32_fp8_e32 v[228:229], v129
	v_cvt_pk_f32_fp8_sdwa v[230:231], v129 src0_sel:WORD_1
	v_pk_fma_f32 v[0:1], v[224:225], v[248:249], v[0:1] op_sel_hi:[1,0,1]
	v_pk_fma_f32 v[2:3], v[226:227], v[248:249], v[2:3] op_sel_hi:[1,0,1]
	v_pk_fma_f32 v[4:5], v[228:229], v[248:249], v[4:5] op_sel_hi:[1,0,1]
	v_pk_fma_f32 v[6:7], v[230:231], v[248:249], v[6:7] op_sel_hi:[1,0,1]
	v_cvt_pk_f32_fp8_e32 v[224:225], v130
	v_cvt_pk_f32_fp8_sdwa v[226:227], v130 src0_sel:WORD_1
	v_cvt_pk_f32_fp8_e32 v[228:229], v131
	v_cvt_pk_f32_fp8_sdwa v[230:231], v131 src0_sel:WORD_1
	v_pk_fma_f32 v[8:9], v[224:225], v[248:249], v[8:9] op_sel_hi:[1,0,1]
	v_pk_fma_f32 v[10:11], v[226:227], v[248:249], v[10:11] op_sel_hi:[1,0,1]
	v_pk_fma_f32 v[12:13], v[228:229], v[248:249], v[12:13] op_sel_hi:[1,0,1]
	v_pk_fma_f32 v[14:15], v[230:231], v[248:249], v[14:15] op_sel_hi:[1,0,1]
	s_waitcnt vmcnt(18)
	v_cvt_pk_f32_fp8_e32 v[224:225], v132
	v_cvt_pk_f32_fp8_sdwa v[226:227], v132 src0_sel:WORD_1
	v_cvt_pk_f32_fp8_e32 v[228:229], v133
	v_cvt_pk_f32_fp8_sdwa v[230:231], v133 src0_sel:WORD_1
	v_pk_fma_f32 v[0:1], v[224:225], v[248:249], v[0:1] op_sel:[0,1,0] op_sel_hi:[1,1,1]
	v_pk_fma_f32 v[2:3], v[226:227], v[248:249], v[2:3] op_sel:[0,1,0] op_sel_hi:[1,1,1]
	v_pk_fma_f32 v[4:5], v[228:229], v[248:249], v[4:5] op_sel:[0,1,0] op_sel_hi:[1,1,1]
	v_pk_fma_f32 v[6:7], v[230:231], v[248:249], v[6:7] op_sel:[0,1,0] op_sel_hi:[1,1,1]
	v_cvt_pk_f32_fp8_e32 v[224:225], v134
	v_cvt_pk_f32_fp8_sdwa v[226:227], v134 src0_sel:WORD_1
	v_cvt_pk_f32_fp8_e32 v[228:229], v135
	v_cvt_pk_f32_fp8_sdwa v[230:231], v135 src0_sel:WORD_1
	v_pk_fma_f32 v[8:9], v[224:225], v[248:249], v[8:9] op_sel:[0,1,0] op_sel_hi:[1,1,1]
	v_pk_fma_f32 v[10:11], v[226:227], v[248:249], v[10:11] op_sel:[0,1,0] op_sel_hi:[1,1,1]
	v_pk_fma_f32 v[12:13], v[228:229], v[248:249], v[12:13] op_sel:[0,1,0] op_sel_hi:[1,1,1]
	v_pk_fma_f32 v[14:15], v[230:231], v[248:249], v[14:15] op_sel:[0,1,0] op_sel_hi:[1,1,1]
	s_waitcnt vmcnt(17)
	v_cvt_pk_f32_fp8_e32 v[224:225], v136
	v_cvt_pk_f32_fp8_sdwa v[226:227], v136 src0_sel:WORD_1
	v_cvt_pk_f32_fp8_e32 v[228:229], v137
	v_cvt_pk_f32_fp8_sdwa v[230:231], v137 src0_sel:WORD_1
	v_pk_fma_f32 v[0:1], v[224:225], v[250:251], v[0:1] op_sel_hi:[1,0,1]
	v_pk_fma_f32 v[2:3], v[226:227], v[250:251], v[2:3] op_sel_hi:[1,0,1]
	v_pk_fma_f32 v[4:5], v[228:229], v[250:251], v[4:5] op_sel_hi:[1,0,1]
	v_pk_fma_f32 v[6:7], v[230:231], v[250:251], v[6:7] op_sel_hi:[1,0,1]
	v_cvt_pk_f32_fp8_e32 v[224:225], v138
	v_cvt_pk_f32_fp8_sdwa v[226:227], v138 src0_sel:WORD_1
	v_cvt_pk_f32_fp8_e32 v[228:229], v139
	v_cvt_pk_f32_fp8_sdwa v[230:231], v139 src0_sel:WORD_1
	v_pk_fma_f32 v[8:9], v[224:225], v[250:251], v[8:9] op_sel_hi:[1,0,1]
	v_pk_fma_f32 v[10:11], v[226:227], v[250:251], v[10:11] op_sel_hi:[1,0,1]
	v_pk_fma_f32 v[12:13], v[228:229], v[250:251], v[12:13] op_sel_hi:[1,0,1]
	v_pk_fma_f32 v[14:15], v[230:231], v[250:251], v[14:15] op_sel_hi:[1,0,1]
	s_waitcnt vmcnt(16)
	v_cvt_pk_f32_fp8_e32 v[224:225], v140
	v_cvt_pk_f32_fp8_sdwa v[226:227], v140 src0_sel:WORD_1
	v_cvt_pk_f32_fp8_e32 v[228:229], v141
	v_cvt_pk_f32_fp8_sdwa v[230:231], v141 src0_sel:WORD_1
	v_pk_fma_f32 v[0:1], v[224:225], v[250:251], v[0:1] op_sel:[0,1,0] op_sel_hi:[1,1,1]
	v_pk_fma_f32 v[2:3], v[226:227], v[250:251], v[2:3] op_sel:[0,1,0] op_sel_hi:[1,1,1]
	v_pk_fma_f32 v[4:5], v[228:229], v[250:251], v[4:5] op_sel:[0,1,0] op_sel_hi:[1,1,1]
	v_pk_fma_f32 v[6:7], v[230:231], v[250:251], v[6:7] op_sel:[0,1,0] op_sel_hi:[1,1,1]
	v_cvt_pk_f32_fp8_e32 v[224:225], v142
	v_cvt_pk_f32_fp8_sdwa v[226:227], v142 src0_sel:WORD_1
	v_cvt_pk_f32_fp8_e32 v[228:229], v143
	v_cvt_pk_f32_fp8_sdwa v[230:231], v143 src0_sel:WORD_1
	v_pk_fma_f32 v[8:9], v[224:225], v[250:251], v[8:9] op_sel:[0,1,0] op_sel_hi:[1,1,1]
	v_pk_fma_f32 v[10:11], v[226:227], v[250:251], v[10:11] op_sel:[0,1,0] op_sel_hi:[1,1,1]
	v_pk_fma_f32 v[12:13], v[228:229], v[250:251], v[12:13] op_sel:[0,1,0] op_sel_hi:[1,1,1]
	v_pk_fma_f32 v[14:15], v[230:231], v[250:251], v[14:15] op_sel:[0,1,0] op_sel_hi:[1,1,1]
	s_sub_i32 s90, s90, 1
	s_cmp_eq_u32 s90, 0
	s_cbranch_scc1 .LV_sw1
.LV_t0_s1:
	s_waitcnt lgkmcnt(0)
	buffer_load_dwordx4 v[128:131], v[232:233], s[60:63], 0 idxen offen
	buffer_load_dwordx4 v[132:135], v[234:235], s[60:63], 0 idxen offen
	buffer_load_dwordx4 v[136:139], v[236:237], s[60:63], 0 idxen offen
	buffer_load_dwordx4 v[140:143], v[238:239], s[60:63], 0 idxen offen
	ds_read_b32 v232, v213 offset:96
	ds_read_b32 v234, v213 offset:100
	ds_read_b32 v236, v213 offset:104
	ds_read_b32 v238, v213 offset:108
	ds_read_b128 v[248:251], v213 offset:5024
	s_waitcnt vmcnt(19)
	v_cvt_pk_f32_fp8_e32 v[224:225], v144
	v_cvt_pk_f32_fp8_sdwa v[226:227], v144 src0_sel:WORD_1
	v_cvt_pk_f32_fp8_e32 v[228:229], v145
	v_cvt_pk_f32_fp8_sdwa v[230:231], v145 src0_sel:WORD_1
	v_pk_fma_f32 v[0:1], v[224:225], v[252:253], v[0:1] op_sel_hi:[1,0,1]
	v_pk_fma_f32 v[2:3], v[226:227], v[252:253], v[2:3] op_sel_hi:[1,0,1]
	v_pk_fma_f32 v[4:5], v[228:229], v[252:253], v[4:5] op_sel_hi:[1,0,1]
	v_pk_fma_f32 v[6:7], v[230:231], v[252:253], v[6:7] op_sel_hi:[1,0,1]
	v_cvt_pk_f32_fp8_e32 v[224:225], v146
	v_cvt_pk_f32_fp8_sdwa v[226:227], v146 src0_sel:WORD_1
	v_cvt_pk_f32_fp8_e32 v[228:229], v147
	v_cvt_pk_f32_fp8_sdwa v[230:231], v147 src0_sel:WORD_1
	v_pk_fma_f32 v[8:9], v[224:225], v[252:253], v[8:9] op_sel_hi:[1,0,1]
	v_pk_fma_f32 v[10:11], v[226:227], v[252:253], v[10:11] op_sel_hi:[1,0,1]
	v_pk_fma_f32 v[12:13], v[228:229], v[252:253], v[12:13] op_sel_hi:[1,0,1]
	v_pk_fma_f32 v[14:15], v[230:231], v[252:253], v[14:15] op_sel_hi:[1,0,1]
	s_waitcnt vmcnt(18)
	v_cvt_pk_f32_fp8_e32 v[224:225], v148
	v_cvt_pk_f32_fp8_sdwa v[226:227], v148 src0_sel:WORD_1
	v_cvt_pk_f32_fp8_e32 v[228:229], v149
	v_cvt_pk_f32_fp8_sdwa v[230:231], v149 src0_sel:WORD_1
	v_pk_fma_f32 v[0:1], v[224:225], v[252:253], v[0:1] op_sel:[0,1,0] op_sel_hi:[1,1,1]
	v_pk_fma_f32 v[2:3], v[226:227], v[252:253], v[2:3] op_sel:[0,1,0] op_sel_hi:[1,1,1]
	v_pk_fma_f32 v[4:5], v[228:229], v[252:253], v[4:5] op_sel:[0,1,0] op_sel_hi:[1,1,1]
	v_pk_fma_f32 v[6:7], v[230:231], v[252:253], v[6:7] op_sel:[0,1,0] op_sel_hi:[1,1,1]
	v_cvt_pk_f32_fp8_e32 v[224:225], v150
	v_cvt_pk_f32_fp8_sdwa v[226:227], v150 src0_sel:WORD_1
	v_cvt_pk_f32_fp8_e32 v[228:229], v151
	v_cvt_pk_f32_fp8_sdwa v[230:231], v151 src0_sel:WORD_1
	v_pk_fma_f32 v[8:9], v[224:225], v[252:253], v[8:9] op_sel:[0,1,0] op_sel_hi:[1,1,1]
	v_pk_fma_f32 v[10:11], v[226:227], v[252:253], v[10:11] op_sel:[0,1,0] op_sel_hi:[1,1,1]
	v_pk_fma_f32 v[12:13], v[228:229], v[252:253], v[12:13] op_sel:[0,1,0] op_sel_hi:[1,1,1]
	v_pk_fma_f32 v[14:15], v[230:231], v[252:253], v[14:15] op_sel:[0,1,0] op_sel_hi:[1,1,1]
	s_waitcnt vmcnt(17)
	v_cvt_pk_f32_fp8_e32 v[224:225], v152
	v_cvt_pk_f32_fp8_sdwa v[226:227], v152 src0_sel:WORD_1
	v_cvt_pk_f32_fp8_e32 v[228:229], v153
	v_cvt_pk_f32_fp8_sdwa v[230:231], v153 src0_sel:WORD_1
	v_pk_fma_f32 v[0:1], v[224:225], v[254:255], v[0:1] op_sel_hi:[1,0,1]
	v_pk_fma_f32 v[2:3], v[226:227], v[254:255], v[2:3] op_sel_hi:[1,0,1]
	v_pk_fma_f32 v[4:5], v[228:229], v[254:255], v[4:5] op_sel_hi:[1,0,1]
	v_pk_fma_f32 v[6:7], v[230:231], v[254:255], v[6:7] op_sel_hi:[1,0,1]
	v_cvt_pk_f32_fp8_e32 v[224:225], v154
	v_cvt_pk_f32_fp8_sdwa v[226:227], v154 src0_sel:WORD_1
	v_cvt_pk_f32_fp8_e32 v[228:229], v155
	v_cvt_pk_f32_fp8_sdwa v[230:231], v155 src0_sel:WORD_1
	v_pk_fma_f32 v[8:9], v[224:225], v[254:255], v[8:9] op_sel_hi:[1,0,1]
	v_pk_fma_f32 v[10:11], v[226:227], v[254:255], v[10:11] op_sel_hi:[1,0,1]
	v_pk_fma_f32 v[12:13], v[228:229], v[254:255], v[12:13] op_sel_hi:[1,0,1]
	v_pk_fma_f32 v[14:15], v[230:231], v[254:255], v[14:15] op_sel_hi:[1,0,1]
	s_waitcnt vmcnt(16)
	v_cvt_pk_f32_fp8_e32 v[224:225], v156
	v_cvt_pk_f32_fp8_sdwa v[226:227], v156 src0_sel:WORD_1
	v_cvt_pk_f32_fp8_e32 v[228:229], v157
	v_cvt_pk_f32_fp8_sdwa v[230:231], v157 src0_sel:WORD_1
	v_pk_fma_f32 v[0:1], v[224:225], v[254:255], v[0:1] op_sel:[0,1,0] op_sel_hi:[1,1,1]
	v_pk_fma_f32 v[2:3], v[226:227], v[254:255], v[2:3] op_sel:[0,1,0] op_sel_hi:[1,1,1]
	v_pk_fma_f32 v[4:5], v[228:229], v[254:255], v[4:5] op_sel:[0,1,0] op_sel_hi:[1,1,1]
	v_pk_fma_f32 v[6:7], v[230:231], v[254:255], v[6:7] op_sel:[0,1,0] op_sel_hi:[1,1,1]
	v_cvt_pk_f32_fp8_e32 v[224:225], v158
	v_cvt_pk_f32_fp8_sdwa v[226:227], v158 src0_sel:WORD_1
	v_cvt_pk_f32_fp8_e32 v[228:229], v159
	v_cvt_pk_f32_fp8_sdwa v[230:231], v159 src0_sel:WORD_1
	v_pk_fma_f32 v[8:9], v[224:225], v[254:255], v[8:9] op_sel:[0,1,0] op_sel_hi:[1,1,1]
	v_pk_fma_f32 v[10:11], v[226:227], v[254:255], v[10:11] op_sel:[0,1,0] op_sel_hi:[1,1,1]
	v_pk_fma_f32 v[12:13], v[228:229], v[254:255], v[12:13] op_sel:[0,1,0] op_sel_hi:[1,1,1]
	v_pk_fma_f32 v[14:15], v[230:231], v[254:255], v[14:15] op_sel:[0,1,0] op_sel_hi:[1,1,1]
	s_sub_i32 s90, s90, 1
	s_cmp_eq_u32 s90, 0
	s_cbranch_scc1 .LV_sw2
.LV_t0_s2:
	s_waitcnt lgkmcnt(0)
	buffer_load_dwordx4 v[144:147], v[232:233], s[60:63], 0 idxen offen
	buffer_load_dwordx4 v[148:151], v[234:235], s[60:63], 0 idxen offen
	buffer_load_dwordx4 v[152:155], v[236:237], s[60:63], 0 idxen offen
	buffer_load_dwordx4 v[156:159], v[238:239], s[60:63], 0 idxen offen
	ds_read_b32 v232, v213 offset:112
	ds_read_b32 v234, v213 offset:116
	ds_read_b32 v236, v213 offset:120
	ds_read_b32 v238, v213 offset:124
	ds_read_b128 v[252:255], v213 offset:5040
	s_waitcnt vmcnt(19)
	v_cvt_pk_f32_fp8_e32 v[224:225], v160
	v_cvt_pk_f32_fp8_sdwa v[226:227], v160 src0_sel:WORD_1
	v_cvt_pk_f32_fp8_e32 v[228:229], v161
	v_cvt_pk_f32_fp8_sdwa v[230:231], v161 src0_sel:WORD_1
	v_pk_fma_f32 v[0:1], v[224:225], v[248:249], v[0:1] op_sel_hi:[1,0,1]
	v_pk_fma_f32 v[2:3], v[226:227], v[248:249], v[2:3] op_sel_hi:[1,0,1]
	v_pk_fma_f32 v[4:5], v[228:229], v[248:249], v[4:5] op_sel_hi:[1,0,1]
	v_pk_fma_f32 v[6:7], v[230:231], v[248:249], v[6:7] op_sel_hi:[1,0,1]
	v_cvt_pk_f32_fp8_e32 v[224:225], v162
	v_cvt_pk_f32_fp8_sdwa v[226:227], v162 src0_sel:WORD_1
	v_cvt_pk_f32_fp8_e32 v[228:229], v163
	v_cvt_pk_f32_fp8_sdwa v[230:231], v163 src0_sel:WORD_1
	v_pk_fma_f32 v[8:9], v[224:225], v[248:249], v[8:9] op_sel_hi:[1,0,1]
	v_pk_fma_f32 v[10:11], v[226:227], v[248:249], v[10:11] op_sel_hi:[1,0,1]
	v_pk_fma_f32 v[12:13], v[228:229], v[248:249], v[12:13] op_sel_hi:[1,0,1]
	v_pk_fma_f32 v[14:15], v[230:231], v[248:249], v[14:15] op_sel_hi:[1,0,1]
	s_waitcnt vmcnt(18)
	v_cvt_pk_f32_fp8_e32 v[224:225], v164
	v_cvt_pk_f32_fp8_sdwa v[226:227], v164 src0_sel:WORD_1
	v_cvt_pk_f32_fp8_e32 v[228:229], v165
	v_cvt_pk_f32_fp8_sdwa v[230:231], v165 src0_sel:WORD_1
	v_pk_fma_f32 v[0:1], v[224:225], v[248:249], v[0:1] op_sel:[0,1,0] op_sel_hi:[1,1,1]
	v_pk_fma_f32 v[2:3], v[226:227], v[248:249], v[2:3] op_sel:[0,1,0] op_sel_hi:[1,1,1]
	v_pk_fma_f32 v[4:5], v[228:229], v[248:249], v[4:5] op_sel:[0,1,0] op_sel_hi:[1,1,1]
	v_pk_fma_f32 v[6:7], v[230:231], v[248:249], v[6:7] op_sel:[0,1,0] op_sel_hi:[1,1,1]
	v_cvt_pk_f32_fp8_e32 v[224:225], v166
	v_cvt_pk_f32_fp8_sdwa v[226:227], v166 src0_sel:WORD_1
	v_cvt_pk_f32_fp8_e32 v[228:229], v167
	v_cvt_pk_f32_fp8_sdwa v[230:231], v167 src0_sel:WORD_1
	v_pk_fma_f32 v[8:9], v[224:225], v[248:249], v[8:9] op_sel:[0,1,0] op_sel_hi:[1,1,1]
	v_pk_fma_f32 v[10:11], v[226:227], v[248:249], v[10:11] op_sel:[0,1,0] op_sel_hi:[1,1,1]
	v_pk_fma_f32 v[12:13], v[228:229], v[248:249], v[12:13] op_sel:[0,1,0] op_sel_hi:[1,1,1]
	v_pk_fma_f32 v[14:15], v[230:231], v[248:249], v[14:15] op_sel:[0,1,0] op_sel_hi:[1,1,1]
	s_waitcnt vmcnt(17)
	v_cvt_pk_f32_fp8_e32 v[224:225], v168
	v_cvt_pk_f32_fp8_sdwa v[226:227], v168 src0_sel:WORD_1
	v_cvt_pk_f32_fp8_e32 v[228:229], v169
	v_cvt_pk_f32_fp8_sdwa v[230:231], v169 src0_sel:WORD_1
	v_pk_fma_f32 v[0:1], v[224:225], v[250:251], v[0:1] op_sel_hi:[1,0,1]
	v_pk_fma_f32 v[2:3], v[226:227], v[250:251], v[2:3] op_sel_hi:[1,0,1]
	v_pk_fma_f32 v[4:5], v[228:229], v[250:251], v[4:5] op_sel_hi:[1,0,1]
	v_pk_fma_f32 v[6:7], v[230:231], v[250:251], v[6:7] op_sel_hi:[1,0,1]
	v_cvt_pk_f32_fp8_e32 v[224:225], v170
	v_cvt_pk_f32_fp8_sdwa v[226:227], v170 src0_sel:WORD_1
	v_cvt_pk_f32_fp8_e32 v[228:229], v171
	v_cvt_pk_f32_fp8_sdwa v[230:231], v171 src0_sel:WORD_1
	v_pk_fma_f32 v[8:9], v[224:225], v[250:251], v[8:9] op_sel_hi:[1,0,1]
	v_pk_fma_f32 v[10:11], v[226:227], v[250:251], v[10:11] op_sel_hi:[1,0,1]
	v_pk_fma_f32 v[12:13], v[228:229], v[250:251], v[12:13] op_sel_hi:[1,0,1]
	v_pk_fma_f32 v[14:15], v[230:231], v[250:251], v[14:15] op_sel_hi:[1,0,1]
	s_waitcnt vmcnt(16)
	v_cvt_pk_f32_fp8_e32 v[224:225], v172
	v_cvt_pk_f32_fp8_sdwa v[226:227], v172 src0_sel:WORD_1
	v_cvt_pk_f32_fp8_e32 v[228:229], v173
	v_cvt_pk_f32_fp8_sdwa v[230:231], v173 src0_sel:WORD_1
	v_pk_fma_f32 v[0:1], v[224:225], v[250:251], v[0:1] op_sel:[0,1,0] op_sel_hi:[1,1,1]
	v_pk_fma_f32 v[2:3], v[226:227], v[250:251], v[2:3] op_sel:[0,1,0] op_sel_hi:[1,1,1]
	v_pk_fma_f32 v[4:5], v[228:229], v[250:251], v[4:5] op_sel:[0,1,0] op_sel_hi:[1,1,1]
	v_pk_fma_f32 v[6:7], v[230:231], v[250:251], v[6:7] op_sel:[0,1,0] op_sel_hi:[1,1,1]
	v_cvt_pk_f32_fp8_e32 v[224:225], v174
	v_cvt_pk_f32_fp8_sdwa v[226:227], v174 src0_sel:WORD_1
	v_cvt_pk_f32_fp8_e32 v[228:229], v175
	v_cvt_pk_f32_fp8_sdwa v[230:231], v175 src0_sel:WORD_1
	v_pk_fma_f32 v[8:9], v[224:225], v[250:251], v[8:9] op_sel:[0,1,0] op_sel_hi:[1,1,1]
	v_pk_fma_f32 v[10:11], v[226:227], v[250:251], v[10:11] op_sel:[0,1,0] op_sel_hi:[1,1,1]
	v_pk_fma_f32 v[12:13], v[228:229], v[250:251], v[12:13] op_sel:[0,1,0] op_sel_hi:[1,1,1]
	v_pk_fma_f32 v[14:15], v[230:231], v[250:251], v[14:15] op_sel:[0,1,0] op_sel_hi:[1,1,1]
	s_sub_i32 s90, s90, 1
	s_cmp_eq_u32 s90, 0
	s_cbranch_scc1 .LV_sw3
.LV_t0_s3:
	s_waitcnt lgkmcnt(0)
	buffer_load_dwordx4 v[160:163], v[232:233], s[60:63], 0 idxen offen
	buffer_load_dwordx4 v[164:167], v[234:235], s[60:63], 0 idxen offen
	buffer_load_dwordx4 v[168:171], v[236:237], s[60:63], 0 idxen offen
	buffer_load_dwordx4 v[172:175], v[238:239], s[60:63], 0 idxen offen
	ds_read_b32 v232, v213 offset:128
	ds_read_b32 v234, v213 offset:132
	ds_read_b32 v236, v213 offset:136
	ds_read_b32 v238, v213 offset:140
	ds_read_b128 v[208:211], v213 offset:5056
	s_waitcnt vmcnt(19)
	v_cvt_pk_f32_fp8_e32 v[224:225], v176
	v_cvt_pk_f32_fp8_sdwa v[226:227], v176 src0_sel:WORD_1
	v_cvt_pk_f32_fp8_e32 v[228:229], v177
	v_cvt_pk_f32_fp8_sdwa v[230:231], v177 src0_sel:WORD_1
	v_pk_fma_f32 v[0:1], v[224:225], v[252:253], v[0:1] op_sel_hi:[1,0,1]
	v_pk_fma_f32 v[2:3], v[226:227], v[252:253], v[2:3] op_sel_hi:[1,0,1]
	v_pk_fma_f32 v[4:5], v[228:229], v[252:253], v[4:5] op_sel_hi:[1,0,1]
	v_pk_fma_f32 v[6:7], v[230:231], v[252:253], v[6:7] op_sel_hi:[1,0,1]
	v_cvt_pk_f32_fp8_e32 v[224:225], v178
	v_cvt_pk_f32_fp8_sdwa v[226:227], v178 src0_sel:WORD_1
	v_cvt_pk_f32_fp8_e32 v[228:229], v179
	v_cvt_pk_f32_fp8_sdwa v[230:231], v179 src0_sel:WORD_1
	v_pk_fma_f32 v[8:9], v[224:225], v[252:253], v[8:9] op_sel_hi:[1,0,1]
	v_pk_fma_f32 v[10:11], v[226:227], v[252:253], v[10:11] op_sel_hi:[1,0,1]
	v_pk_fma_f32 v[12:13], v[228:229], v[252:253], v[12:13] op_sel_hi:[1,0,1]
	v_pk_fma_f32 v[14:15], v[230:231], v[252:253], v[14:15] op_sel_hi:[1,0,1]
	s_waitcnt vmcnt(18)
	v_cvt_pk_f32_fp8_e32 v[224:225], v180
	v_cvt_pk_f32_fp8_sdwa v[226:227], v180 src0_sel:WORD_1
	v_cvt_pk_f32_fp8_e32 v[228:229], v181
	v_cvt_pk_f32_fp8_sdwa v[230:231], v181 src0_sel:WORD_1
	v_pk_fma_f32 v[0:1], v[224:225], v[252:253], v[0:1] op_sel:[0,1,0] op_sel_hi:[1,1,1]
	v_pk_fma_f32 v[2:3], v[226:227], v[252:253], v[2:3] op_sel:[0,1,0] op_sel_hi:[1,1,1]
	v_pk_fma_f32 v[4:5], v[228:229], v[252:253], v[4:5] op_sel:[0,1,0] op_sel_hi:[1,1,1]
	v_pk_fma_f32 v[6:7], v[230:231], v[252:253], v[6:7] op_sel:[0,1,0] op_sel_hi:[1,1,1]
	v_cvt_pk_f32_fp8_e32 v[224:225], v182
	v_cvt_pk_f32_fp8_sdwa v[226:227], v182 src0_sel:WORD_1
	v_cvt_pk_f32_fp8_e32 v[228:229], v183
	v_cvt_pk_f32_fp8_sdwa v[230:231], v183 src0_sel:WORD_1
	v_pk_fma_f32 v[8:9], v[224:225], v[252:253], v[8:9] op_sel:[0,1,0] op_sel_hi:[1,1,1]
	v_pk_fma_f32 v[10:11], v[226:227], v[252:253], v[10:11] op_sel:[0,1,0] op_sel_hi:[1,1,1]
	v_pk_fma_f32 v[12:13], v[228:229], v[252:253], v[12:13] op_sel:[0,1,0] op_sel_hi:[1,1,1]
	v_pk_fma_f32 v[14:15], v[230:231], v[252:253], v[14:15] op_sel:[0,1,0] op_sel_hi:[1,1,1]
	s_waitcnt vmcnt(17)
	v_cvt_pk_f32_fp8_e32 v[224:225], v184
	v_cvt_pk_f32_fp8_sdwa v[226:227], v184 src0_sel:WORD_1
	v_cvt_pk_f32_fp8_e32 v[228:229], v185
	v_cvt_pk_f32_fp8_sdwa v[230:231], v185 src0_sel:WORD_1
	v_pk_fma_f32 v[0:1], v[224:225], v[254:255], v[0:1] op_sel_hi:[1,0,1]
	v_pk_fma_f32 v[2:3], v[226:227], v[254:255], v[2:3] op_sel_hi:[1,0,1]
	v_pk_fma_f32 v[4:5], v[228:229], v[254:255], v[4:5] op_sel_hi:[1,0,1]
	v_pk_fma_f32 v[6:7], v[230:231], v[254:255], v[6:7] op_sel_hi:[1,0,1]
	v_cvt_pk_f32_fp8_e32 v[224:225], v186
	v_cvt_pk_f32_fp8_sdwa v[226:227], v186 src0_sel:WORD_1
	v_cvt_pk_f32_fp8_e32 v[228:229], v187
	v_cvt_pk_f32_fp8_sdwa v[230:231], v187 src0_sel:WORD_1
	v_pk_fma_f32 v[8:9], v[224:225], v[254:255], v[8:9] op_sel_hi:[1,0,1]
	v_pk_fma_f32 v[10:11], v[226:227], v[254:255], v[10:11] op_sel_hi:[1,0,1]
	v_pk_fma_f32 v[12:13], v[228:229], v[254:255], v[12:13] op_sel_hi:[1,0,1]
	v_pk_fma_f32 v[14:15], v[230:231], v[254:255], v[14:15] op_sel_hi:[1,0,1]
	s_waitcnt vmcnt(16)
	v_cvt_pk_f32_fp8_e32 v[224:225], v188
	v_cvt_pk_f32_fp8_sdwa v[226:227], v188 src0_sel:WORD_1
	v_cvt_pk_f32_fp8_e32 v[228:229], v189
	v_cvt_pk_f32_fp8_sdwa v[230:231], v189 src0_sel:WORD_1
	v_pk_fma_f32 v[0:1], v[224:225], v[254:255], v[0:1] op_sel:[0,1,0] op_sel_hi:[1,1,1]
	v_pk_fma_f32 v[2:3], v[226:227], v[254:255], v[2:3] op_sel:[0,1,0] op_sel_hi:[1,1,1]
	v_pk_fma_f32 v[4:5], v[228:229], v[254:255], v[4:5] op_sel:[0,1,0] op_sel_hi:[1,1,1]
	v_pk_fma_f32 v[6:7], v[230:231], v[254:255], v[6:7] op_sel:[0,1,0] op_sel_hi:[1,1,1]
	v_cvt_pk_f32_fp8_e32 v[224:225], v190
	v_cvt_pk_f32_fp8_sdwa v[226:227], v190 src0_sel:WORD_1
	v_cvt_pk_f32_fp8_e32 v[228:229], v191
	v_cvt_pk_f32_fp8_sdwa v[230:231], v191 src0_sel:WORD_1
	v_pk_fma_f32 v[8:9], v[224:225], v[254:255], v[8:9] op_sel:[0,1,0] op_sel_hi:[1,1,1]
	v_pk_fma_f32 v[10:11], v[226:227], v[254:255], v[10:11] op_sel:[0,1,0] op_sel_hi:[1,1,1]
	v_pk_fma_f32 v[12:13], v[228:229], v[254:255], v[12:13] op_sel:[0,1,0] op_sel_hi:[1,1,1]
	v_pk_fma_f32 v[14:15], v[230:231], v[254:255], v[14:15] op_sel:[0,1,0] op_sel_hi:[1,1,1]
	s_sub_i32 s90, s90, 1
	s_cmp_eq_u32 s90, 0
	s_cbranch_scc1 .LV_sw4
.LV_t0_s4:
	s_waitcnt lgkmcnt(0)
	buffer_load_dwordx4 v[176:179], v[232:233], s[60:63], 0 idxen offen
	buffer_load_dwordx4 v[180:183], v[234:235], s[60:63], 0 idxen offen
	buffer_load_dwordx4 v[184:187], v[236:237], s[60:63], 0 idxen offen
	buffer_load_dwordx4 v[188:191], v[238:239], s[60:63], 0 idxen offen
	ds_read_b32 v232, v213 offset:144
	ds_read_b32 v234, v213 offset:148
	ds_read_b32 v236, v213 offset:152
	ds_read_b32 v238, v213 offset:156
	ds_read_b128 v[248:251], v213 offset:5072
	s_waitcnt vmcnt(19)
	v_cvt_pk_f32_fp8_e32 v[224:225], v192
	v_cvt_pk_f32_fp8_sdwa v[226:227], v192 src0_sel:WORD_1
	v_cvt_pk_f32_fp8_e32 v[228:229], v193
	v_cvt_pk_f32_fp8_sdwa v[230:231], v193 src0_sel:WORD_1
	v_pk_fma_f32 v[0:1], v[224:225], v[208:209], v[0:1] op_sel_hi:[1,0,1]
	v_pk_fma_f32 v[2:3], v[226:227], v[208:209], v[2:3] op_sel_hi:[1,0,1]
	v_pk_fma_f32 v[4:5], v[228:229], v[208:209], v[4:5] op_sel_hi:[1,0,1]
	v_pk_fma_f32 v[6:7], v[230:231], v[208:209], v[6:7] op_sel_hi:[1,0,1]
	v_cvt_pk_f32_fp8_e32 v[224:225], v194
	v_cvt_pk_f32_fp8_sdwa v[226:227], v194 src0_sel:WORD_1
	v_cvt_pk_f32_fp8_e32 v[228:229], v195
	v_cvt_pk_f32_fp8_sdwa v[230:231], v195 src0_sel:WORD_1
	v_pk_fma_f32 v[8:9], v[224:225], v[208:209], v[8:9] op_sel_hi:[1,0,1]
	v_pk_fma_f32 v[10:11], v[226:227], v[208:209], v[10:11] op_sel_hi:[1,0,1]
	v_pk_fma_f32 v[12:13], v[228:229], v[208:209], v[12:13] op_sel_hi:[1,0,1]
	v_pk_fma_f32 v[14:15], v[230:231], v[208:209], v[14:15] op_sel_hi:[1,0,1]
	s_waitcnt vmcnt(18)
	v_cvt_pk_f32_fp8_e32 v[224:225], v196
	v_cvt_pk_f32_fp8_sdwa v[226:227], v196 src0_sel:WORD_1
	v_cvt_pk_f32_fp8_e32 v[228:229], v197
	v_cvt_pk_f32_fp8_sdwa v[230:231], v197 src0_sel:WORD_1
	v_pk_fma_f32 v[0:1], v[224:225], v[208:209], v[0:1] op_sel:[0,1,0] op_sel_hi:[1,1,1]
	v_pk_fma_f32 v[2:3], v[226:227], v[208:209], v[2:3] op_sel:[0,1,0] op_sel_hi:[1,1,1]
	v_pk_fma_f32 v[4:5], v[228:229], v[208:209], v[4:5] op_sel:[0,1,0] op_sel_hi:[1,1,1]
	v_pk_fma_f32 v[6:7], v[230:231], v[208:209], v[6:7] op_sel:[0,1,0] op_sel_hi:[1,1,1]
	v_cvt_pk_f32_fp8_e32 v[224:225], v198
	v_cvt_pk_f32_fp8_sdwa v[226:227], v198 src0_sel:WORD_1
	v_cvt_pk_f32_fp8_e32 v[228:229], v199
	v_cvt_pk_f32_fp8_sdwa v[230:231], v199 src0_sel:WORD_1
	v_pk_fma_f32 v[8:9], v[224:225], v[208:209], v[8:9] op_sel:[0,1,0] op_sel_hi:[1,1,1]
	v_pk_fma_f32 v[10:11], v[226:227], v[208:209], v[10:11] op_sel:[0,1,0] op_sel_hi:[1,1,1]
	v_pk_fma_f32 v[12:13], v[228:229], v[208:209], v[12:13] op_sel:[0,1,0] op_sel_hi:[1,1,1]
	v_pk_fma_f32 v[14:15], v[230:231], v[208:209], v[14:15] op_sel:[0,1,0] op_sel_hi:[1,1,1]
	s_waitcnt vmcnt(17)
	v_cvt_pk_f32_fp8_e32 v[224:225], v200
	v_cvt_pk_f32_fp8_sdwa v[226:227], v200 src0_sel:WORD_1
	v_cvt_pk_f32_fp8_e32 v[228:229], v201
	v_cvt_pk_f32_fp8_sdwa v[230:231], v201 src0_sel:WORD_1
	v_pk_fma_f32 v[0:1], v[224:225], v[210:211], v[0:1] op_sel_hi:[1,0,1]
	v_pk_fma_f32 v[2:3], v[226:227], v[210:211], v[2:3] op_sel_hi:[1,0,1]
	v_pk_fma_f32 v[4:5], v[228:229], v[210:211], v[4:5] op_sel_hi:[1,0,1]
	v_pk_fma_f32 v[6:7], v[230:231], v[210:211], v[6:7] op_sel_hi:[1,0,1]
	v_cvt_pk_f32_fp8_e32 v[224:225], v202
	v_cvt_pk_f32_fp8_sdwa v[226:227], v202 src0_sel:WORD_1
	v_cvt_pk_f32_fp8_e32 v[228:229], v203
	v_cvt_pk_f32_fp8_sdwa v[230:231], v203 src0_sel:WORD_1
	v_pk_fma_f32 v[8:9], v[224:225], v[210:211], v[8:9] op_sel_hi:[1,0,1]
	v_pk_fma_f32 v[10:11], v[226:227], v[210:211], v[10:11] op_sel_hi:[1,0,1]
	v_pk_fma_f32 v[12:13], v[228:229], v[210:211], v[12:13] op_sel_hi:[1,0,1]
	v_pk_fma_f32 v[14:15], v[230:231], v[210:211], v[14:15] op_sel_hi:[1,0,1]
	s_waitcnt vmcnt(16)
	v_cvt_pk_f32_fp8_e32 v[224:225], v204
	v_cvt_pk_f32_fp8_sdwa v[226:227], v204 src0_sel:WORD_1
	v_cvt_pk_f32_fp8_e32 v[228:229], v205
	v_cvt_pk_f32_fp8_sdwa v[230:231], v205 src0_sel:WORD_1
	v_pk_fma_f32 v[0:1], v[224:225], v[210:211], v[0:1] op_sel:[0,1,0] op_sel_hi:[1,1,1]
	v_pk_fma_f32 v[2:3], v[226:227], v[210:211], v[2:3] op_sel:[0,1,0] op_sel_hi:[1,1,1]
	v_pk_fma_f32 v[4:5], v[228:229], v[210:211], v[4:5] op_sel:[0,1,0] op_sel_hi:[1,1,1]
	v_pk_fma_f32 v[6:7], v[230:231], v[210:211], v[6:7] op_sel:[0,1,0] op_sel_hi:[1,1,1]
	v_cvt_pk_f32_fp8_e32 v[224:225], v206
	v_cvt_pk_f32_fp8_sdwa v[226:227], v206 src0_sel:WORD_1
	v_cvt_pk_f32_fp8_e32 v[228:229], v207
	v_cvt_pk_f32_fp8_sdwa v[230:231], v207 src0_sel:WORD_1
	v_pk_fma_f32 v[8:9], v[224:225], v[210:211], v[8:9] op_sel:[0,1,0] op_sel_hi:[1,1,1]
	v_pk_fma_f32 v[10:11], v[226:227], v[210:211], v[10:11] op_sel:[0,1,0] op_sel_hi:[1,1,1]
	v_pk_fma_f32 v[12:13], v[228:229], v[210:211], v[12:13] op_sel:[0,1,0] op_sel_hi:[1,1,1]
	v_pk_fma_f32 v[14:15], v[230:231], v[210:211], v[14:15] op_sel:[0,1,0] op_sel_hi:[1,1,1]
	v_add_u32_e32 v213, 80, v213
	s_add_i32 s21, s21, 5
	s_sub_i32 s90, s90, 1
	s_cmp_eq_u32 s90, 0
	s_cbranch_scc1 .LV_sw0
	s_branch .LV_t0_s0
.LV_t1_s0:
	s_cmp_ge_u32 s21, s20
	s_cbranch_scc1 .LV_done
	s_waitcnt lgkmcnt(0)
	buffer_load_dwordx4 v[192:195], v[232:233], s[60:63], 0 idxen offen
	buffer_load_dwordx4 v[196:199], v[234:235], s[60:63], 0 idxen offen
	buffer_load_dwordx4 v[200:203], v[236:237], s[60:63], 0 idxen offen
	buffer_load_dwordx4 v[204:207], v[238:239], s[60:63], 0 idxen offen
	ds_read_b32 v232, v213 offset:80
	ds_read_b32 v234, v213 offset:84
	ds_read_b32 v236, v213 offset:88
	ds_read_b32 v238, v213 offset:92
	ds_read_b128 v[252:255], v213 offset:5008
	s_waitcnt vmcnt(19)
	v_cvt_pk_f32_fp8_e32 v[224:225], v128
	v_cvt_pk_f32_fp8_sdwa v[226:227], v128 src0_sel:WORD_1
	v_cvt_pk_f32_fp8_e32 v[228:229], v129
	v_cvt_pk_f32_fp8_sdwa v[230:231], v129 src0_sel:WORD_1
	v_pk_fma_f32 v[16:17], v[224:225], v[248:249], v[16:17] op_sel_hi:[1,0,1]
	v_pk_fma_f32 v[18:19], v[226:227], v[248:249], v[18:19] op_sel_hi:[1,0,1]
	v_pk_fma_f32 v[20:21], v[228:229], v[248:249], v[20:21] op_sel_hi:[1,0,1]
	v_pk_fma_f32 v[22:23], v[230:231], v[248:249], v[22:23] op_sel_hi:[1,0,1]
	v_cvt_pk_f32_fp8_e32 v[224:225], v130
	v_cvt_pk_f32_fp8_sdwa v[226:227], v130 src0_sel:WORD_1
	v_cvt_pk_f32_fp8_e32 v[228:229], v131
	v_cvt_pk_f32_fp8_sdwa v[230:231], v131 src0_sel:WORD_1
	v_pk_fma_f32 v[24:25], v[224:225], v[248:249], v[24:25] op_sel_hi:[1,0,1]
	v_pk_fma_f32 v[26:27], v[226:227], v[248:249], v[26:27] op_sel_hi:[1,0,1]
	v_pk_fma_f32 v[28:29], v[228:229], v[248:249], v[28:29] op_sel_hi:[1,0,1]
	v_pk_fma_f32 v[30:31], v[230:231], v[248:249], v[30:31] op_sel_hi:[1,0,1]
	s_waitcnt vmcnt(18)
	v_cvt_pk_f32_fp8_e32 v[224:225], v132
	v_cvt_pk_f32_fp8_sdwa v[226:227], v132 src0_sel:WORD_1
	v_cvt_pk_f32_fp8_e32 v[228:229], v133
	v_cvt_pk_f32_fp8_sdwa v[230:231], v133 src0_sel:WORD_1
	v_pk_fma_f32 v[16:17], v[224:225], v[248:249], v[16:17] op_sel:[0,1,0] op_sel_hi:[1,1,1]
	v_pk_fma_f32 v[18:19], v[226:227], v[248:249], v[18:19] op_sel:[0,1,0] op_sel_hi:[1,1,1]
	v_pk_fma_f32 v[20:21], v[228:229], v[248:249], v[20:21] op_sel:[0,1,0] op_sel_hi:[1,1,1]
	v_pk_fma_f32 v[22:23], v[230:231], v[248:249], v[22:23] op_sel:[0,1,0] op_sel_hi:[1,1,1]
	v_cvt_pk_f32_fp8_e32 v[224:225], v134
	v_cvt_pk_f32_fp8_sdwa v[226:227], v134 src0_sel:WORD_1
	v_cvt_pk_f32_fp8_e32 v[228:229], v135
	v_cvt_pk_f32_fp8_sdwa v[230:231], v135 src0_sel:WORD_1
	v_pk_fma_f32 v[24:25], v[224:225], v[248:249], v[24:25] op_sel:[0,1,0] op_sel_hi:[1,1,1]
	v_pk_fma_f32 v[26:27], v[226:227], v[248:249], v[26:27] op_sel:[0,1,0] op_sel_hi:[1,1,1]
	v_pk_fma_f32 v[28:29], v[228:229], v[248:249], v[28:29] op_sel:[0,1,0] op_sel_hi:[1,1,1]
	v_pk_fma_f32 v[30:31], v[230:231], v[248:249], v[30:31] op_sel:[0,1,0] op_sel_hi:[1,1,1]
	s_waitcnt vmcnt(17)
	v_cvt_pk_f32_fp8_e32 v[224:225], v136
	v_cvt_pk_f32_fp8_sdwa v[226:227], v136 src0_sel:WORD_1
	v_cvt_pk_f32_fp8_e32 v[228:229], v137
	v_cvt_pk_f32_fp8_sdwa v[230:231], v137 src0_sel:WORD_1
	v_pk_fma_f32 v[16:17], v[224:225], v[250:251], v[16:17] op_sel_hi:[1,0,1]
	v_pk_fma_f32 v[18:19], v[226:227], v[250:251], v[18:19] op_sel_hi:[1,0,1]
	v_pk_fma_f32 v[20:21], v[228:229], v[250:251], v[20:21] op_sel_hi:[1,0,1]
	v_pk_fma_f32 v[22:23], v[230:231], v[250:251], v[22:23] op_sel_hi:[1,0,1]
	v_cvt_pk_f32_fp8_e32 v[224:225], v138
	v_cvt_pk_f32_fp8_sdwa v[226:227], v138 src0_sel:WORD_1
	v_cvt_pk_f32_fp8_e32 v[228:229], v139
	v_cvt_pk_f32_fp8_sdwa v[230:231], v139 src0_sel:WORD_1
	v_pk_fma_f32 v[24:25], v[224:225], v[250:251], v[24:25] op_sel_hi:[1,0,1]
	v_pk_fma_f32 v[26:27], v[226:227], v[250:251], v[26:27] op_sel_hi:[1,0,1]
	v_pk_fma_f32 v[28:29], v[228:229], v[250:251], v[28:29] op_sel_hi:[1,0,1]
	v_pk_fma_f32 v[30:31], v[230:231], v[250:251], v[30:31] op_sel_hi:[1,0,1]
	s_waitcnt vmcnt(16)
	v_cvt_pk_f32_fp8_e32 v[224:225], v140
	v_cvt_pk_f32_fp8_sdwa v[226:227], v140 src0_sel:WORD_1
	v_cvt_pk_f32_fp8_e32 v[228:229], v141
	v_cvt_pk_f32_fp8_sdwa v[230:231], v141 src0_sel:WORD_1
	v_pk_fma_f32 v[16:17], v[224:225], v[250:251], v[16:17] op_sel:[0,1,0] op_sel_hi:[1,1,1]
	v_pk_fma_f32 v[18:19], v[226:227], v[250:251], v[18:19] op_sel:[0,1,0] op_sel_hi:[1,1,1]
	v_pk_fma_f32 v[20:21], v[228:229], v[250:251], v[20:21] op_sel:[0,1,0] op_sel_hi:[1,1,1]
	v_pk_fma_f32 v[22:23], v[230:231], v[250:251], v[22:23] op_sel:[0,1,0] op_sel_hi:[1,1,1]
	v_cvt_pk_f32_fp8_e32 v[224:225], v142
	v_cvt_pk_f32_fp8_sdwa v[226:227], v142 src0_sel:WORD_1
	v_cvt_pk_f32_fp8_e32 v[228:229], v143
	v_cvt_pk_f32_fp8_sdwa v[230:231], v143 src0_sel:WORD_1
	v_pk_fma_f32 v[24:25], v[224:225], v[250:251], v[24:25] op_sel:[0,1,0] op_sel_hi:[1,1,1]
	v_pk_fma_f32 v[26:27], v[226:227], v[250:251], v[26:27] op_sel:[0,1,0] op_sel_hi:[1,1,1]
	v_pk_fma_f32 v[28:29], v[228:229], v[250:251], v[28:29] op_sel:[0,1,0] op_sel_hi:[1,1,1]
	v_pk_fma_f32 v[30:31], v[230:231], v[250:251], v[30:31] op_sel:[0,1,0] op_sel_hi:[1,1,1]
	s_sub_i32 s90, s90, 1
	s_cmp_eq_u32 s90, 0
	s_cbranch_scc1 .LV_sw1
.LV_t1_s1:
	s_waitcnt lgkmcnt(0)
	buffer_load_dwordx4 v[128:131], v[232:233], s[60:63], 0 idxen offen
	buffer_load_dwordx4 v[132:135], v[234:235], s[60:63], 0 idxen offen
	buffer_load_dwordx4 v[136:139], v[236:237], s[60:63], 0 idxen offen
	buffer_load_dwordx4 v[140:143], v[238:239], s[60:63], 0 idxen offen
	ds_read_b32 v232, v213 offset:96
	ds_read_b32 v234, v213 offset:100
	ds_read_b32 v236, v213 offset:104
	ds_read_b32 v238, v213 offset:108
	ds_read_b128 v[248:251], v213 offset:5024
	s_waitcnt vmcnt(19)
	v_cvt_pk_f32_fp8_e32 v[224:225], v144
	v_cvt_pk_f32_fp8_sdwa v[226:227], v144 src0_sel:WORD_1
	v_cvt_pk_f32_fp8_e32 v[228:229], v145
	v_cvt_pk_f32_fp8_sdwa v[230:231], v145 src0_sel:WORD_1
	v_pk_fma_f32 v[16:17], v[224:225], v[252:253], v[16:17] op_sel_hi:[1,0,1]
	v_pk_fma_f32 v[18:19], v[226:227], v[252:253], v[18:19] op_sel_hi:[1,0,1]
	v_pk_fma_f32 v[20:21], v[228:229], v[252:253], v[20:21] op_sel_hi:[1,0,1]
	v_pk_fma_f32 v[22:23], v[230:231], v[252:253], v[22:23] op_sel_hi:[1,0,1]
	v_cvt_pk_f32_fp8_e32 v[224:225], v146
	v_cvt_pk_f32_fp8_sdwa v[226:227], v146 src0_sel:WORD_1
	v_cvt_pk_f32_fp8_e32 v[228:229], v147
	v_cvt_pk_f32_fp8_sdwa v[230:231], v147 src0_sel:WORD_1
	v_pk_fma_f32 v[24:25], v[224:225], v[252:253], v[24:25] op_sel_hi:[1,0,1]
	v_pk_fma_f32 v[26:27], v[226:227], v[252:253], v[26:27] op_sel_hi:[1,0,1]
	v_pk_fma_f32 v[28:29], v[228:229], v[252:253], v[28:29] op_sel_hi:[1,0,1]
	v_pk_fma_f32 v[30:31], v[230:231], v[252:253], v[30:31] op_sel_hi:[1,0,1]
	s_waitcnt vmcnt(18)
	v_cvt_pk_f32_fp8_e32 v[224:225], v148
	v_cvt_pk_f32_fp8_sdwa v[226:227], v148 src0_sel:WORD_1
	v_cvt_pk_f32_fp8_e32 v[228:229], v149
	v_cvt_pk_f32_fp8_sdwa v[230:231], v149 src0_sel:WORD_1
	v_pk_fma_f32 v[16:17], v[224:225], v[252:253], v[16:17] op_sel:[0,1,0] op_sel_hi:[1,1,1]
	v_pk_fma_f32 v[18:19], v[226:227], v[252:253], v[18:19] op_sel:[0,1,0] op_sel_hi:[1,1,1]
	v_pk_fma_f32 v[20:21], v[228:229], v[252:253], v[20:21] op_sel:[0,1,0] op_sel_hi:[1,1,1]
	v_pk_fma_f32 v[22:23], v[230:231], v[252:253], v[22:23] op_sel:[0,1,0] op_sel_hi:[1,1,1]
	v_cvt_pk_f32_fp8_e32 v[224:225], v150
	v_cvt_pk_f32_fp8_sdwa v[226:227], v150 src0_sel:WORD_1
	v_cvt_pk_f32_fp8_e32 v[228:229], v151
	v_cvt_pk_f32_fp8_sdwa v[230:231], v151 src0_sel:WORD_1
	v_pk_fma_f32 v[24:25], v[224:225], v[252:253], v[24:25] op_sel:[0,1,0] op_sel_hi:[1,1,1]
	v_pk_fma_f32 v[26:27], v[226:227], v[252:253], v[26:27] op_sel:[0,1,0] op_sel_hi:[1,1,1]
	v_pk_fma_f32 v[28:29], v[228:229], v[252:253], v[28:29] op_sel:[0,1,0] op_sel_hi:[1,1,1]
	v_pk_fma_f32 v[30:31], v[230:231], v[252:253], v[30:31] op_sel:[0,1,0] op_sel_hi:[1,1,1]
	s_waitcnt vmcnt(17)
	v_cvt_pk_f32_fp8_e32 v[224:225], v152
	v_cvt_pk_f32_fp8_sdwa v[226:227], v152 src0_sel:WORD_1
	v_cvt_pk_f32_fp8_e32 v[228:229], v153
	v_cvt_pk_f32_fp8_sdwa v[230:231], v153 src0_sel:WORD_1
	v_pk_fma_f32 v[16:17], v[224:225], v[254:255], v[16:17] op_sel_hi:[1,0,1]
	v_pk_fma_f32 v[18:19], v[226:227], v[254:255], v[18:19] op_sel_hi:[1,0,1]
	v_pk_fma_f32 v[20:21], v[228:229], v[254:255], v[20:21] op_sel_hi:[1,0,1]
	v_pk_fma_f32 v[22:23], v[230:231], v[254:255], v[22:23] op_sel_hi:[1,0,1]
	v_cvt_pk_f32_fp8_e32 v[224:225], v154
	v_cvt_pk_f32_fp8_sdwa v[226:227], v154 src0_sel:WORD_1
	v_cvt_pk_f32_fp8_e32 v[228:229], v155
	v_cvt_pk_f32_fp8_sdwa v[230:231], v155 src0_sel:WORD_1
	v_pk_fma_f32 v[24:25], v[224:225], v[254:255], v[24:25] op_sel_hi:[1,0,1]
	v_pk_fma_f32 v[26:27], v[226:227], v[254:255], v[26:27] op_sel_hi:[1,0,1]
	v_pk_fma_f32 v[28:29], v[228:229], v[254:255], v[28:29] op_sel_hi:[1,0,1]
	v_pk_fma_f32 v[30:31], v[230:231], v[254:255], v[30:31] op_sel_hi:[1,0,1]
	s_waitcnt vmcnt(16)
	v_cvt_pk_f32_fp8_e32 v[224:225], v156
	v_cvt_pk_f32_fp8_sdwa v[226:227], v156 src0_sel:WORD_1
	v_cvt_pk_f32_fp8_e32 v[228:229], v157
	v_cvt_pk_f32_fp8_sdwa v[230:231], v157 src0_sel:WORD_1
	v_pk_fma_f32 v[16:17], v[224:225], v[254:255], v[16:17] op_sel:[0,1,0] op_sel_hi:[1,1,1]
	v_pk_fma_f32 v[18:19], v[226:227], v[254:255], v[18:19] op_sel:[0,1,0] op_sel_hi:[1,1,1]
	v_pk_fma_f32 v[20:21], v[228:229], v[254:255], v[20:21] op_sel:[0,1,0] op_sel_hi:[1,1,1]
	v_pk_fma_f32 v[22:23], v[230:231], v[254:255], v[22:23] op_sel:[0,1,0] op_sel_hi:[1,1,1]
	v_cvt_pk_f32_fp8_e32 v[224:225], v158
	v_cvt_pk_f32_fp8_sdwa v[226:227], v158 src0_sel:WORD_1
	v_cvt_pk_f32_fp8_e32 v[228:229], v159
	v_cvt_pk_f32_fp8_sdwa v[230:231], v159 src0_sel:WORD_1
	v_pk_fma_f32 v[24:25], v[224:225], v[254:255], v[24:25] op_sel:[0,1,0] op_sel_hi:[1,1,1]
	v_pk_fma_f32 v[26:27], v[226:227], v[254:255], v[26:27] op_sel:[0,1,0] op_sel_hi:[1,1,1]
	v_pk_fma_f32 v[28:29], v[228:229], v[254:255], v[28:29] op_sel:[0,1,0] op_sel_hi:[1,1,1]
	v_pk_fma_f32 v[30:31], v[230:231], v[254:255], v[30:31] op_sel:[0,1,0] op_sel_hi:[1,1,1]
	s_sub_i32 s90, s90, 1
	s_cmp_eq_u32 s90, 0
	s_cbranch_scc1 .LV_sw2
.LV_t1_s2:
	s_waitcnt lgkmcnt(0)
	buffer_load_dwordx4 v[144:147], v[232:233], s[60:63], 0 idxen offen
	buffer_load_dwordx4 v[148:151], v[234:235], s[60:63], 0 idxen offen
	buffer_load_dwordx4 v[152:155], v[236:237], s[60:63], 0 idxen offen
	buffer_load_dwordx4 v[156:159], v[238:239], s[60:63], 0 idxen offen
	ds_read_b32 v232, v213 offset:112
	ds_read_b32 v234, v213 offset:116
	ds_read_b32 v236, v213 offset:120
	ds_read_b32 v238, v213 offset:124
	ds_read_b128 v[252:255], v213 offset:5040
	s_waitcnt vmcnt(19)
	v_cvt_pk_f32_fp8_e32 v[224:225], v160
	v_cvt_pk_f32_fp8_sdwa v[226:227], v160 src0_sel:WORD_1
	v_cvt_pk_f32_fp8_e32 v[228:229], v161
	v_cvt_pk_f32_fp8_sdwa v[230:231], v161 src0_sel:WORD_1
	v_pk_fma_f32 v[16:17], v[224:225], v[248:249], v[16:17] op_sel_hi:[1,0,1]
	v_pk_fma_f32 v[18:19], v[226:227], v[248:249], v[18:19] op_sel_hi:[1,0,1]
	v_pk_fma_f32 v[20:21], v[228:229], v[248:249], v[20:21] op_sel_hi:[1,0,1]
	v_pk_fma_f32 v[22:23], v[230:231], v[248:249], v[22:23] op_sel_hi:[1,0,1]
	v_cvt_pk_f32_fp8_e32 v[224:225], v162
	v_cvt_pk_f32_fp8_sdwa v[226:227], v162 src0_sel:WORD_1
	v_cvt_pk_f32_fp8_e32 v[228:229], v163
	v_cvt_pk_f32_fp8_sdwa v[230:231], v163 src0_sel:WORD_1
	v_pk_fma_f32 v[24:25], v[224:225], v[248:249], v[24:25] op_sel_hi:[1,0,1]
	v_pk_fma_f32 v[26:27], v[226:227], v[248:249], v[26:27] op_sel_hi:[1,0,1]
	v_pk_fma_f32 v[28:29], v[228:229], v[248:249], v[28:29] op_sel_hi:[1,0,1]
	v_pk_fma_f32 v[30:31], v[230:231], v[248:249], v[30:31] op_sel_hi:[1,0,1]
	s_waitcnt vmcnt(18)
	v_cvt_pk_f32_fp8_e32 v[224:225], v164
	v_cvt_pk_f32_fp8_sdwa v[226:227], v164 src0_sel:WORD_1
	v_cvt_pk_f32_fp8_e32 v[228:229], v165
	v_cvt_pk_f32_fp8_sdwa v[230:231], v165 src0_sel:WORD_1
	v_pk_fma_f32 v[16:17], v[224:225], v[248:249], v[16:17] op_sel:[0,1,0] op_sel_hi:[1,1,1]
	v_pk_fma_f32 v[18:19], v[226:227], v[248:249], v[18:19] op_sel:[0,1,0] op_sel_hi:[1,1,1]
	v_pk_fma_f32 v[20:21], v[228:229], v[248:249], v[20:21] op_sel:[0,1,0] op_sel_hi:[1,1,1]
	v_pk_fma_f32 v[22:23], v[230:231], v[248:249], v[22:23] op_sel:[0,1,0] op_sel_hi:[1,1,1]
	v_cvt_pk_f32_fp8_e32 v[224:225], v166
	v_cvt_pk_f32_fp8_sdwa v[226:227], v166 src0_sel:WORD_1
	v_cvt_pk_f32_fp8_e32 v[228:229], v167
	v_cvt_pk_f32_fp8_sdwa v[230:231], v167 src0_sel:WORD_1
	v_pk_fma_f32 v[24:25], v[224:225], v[248:249], v[24:25] op_sel:[0,1,0] op_sel_hi:[1,1,1]
	v_pk_fma_f32 v[26:27], v[226:227], v[248:249], v[26:27] op_sel:[0,1,0] op_sel_hi:[1,1,1]
	v_pk_fma_f32 v[28:29], v[228:229], v[248:249], v[28:29] op_sel:[0,1,0] op_sel_hi:[1,1,1]
	v_pk_fma_f32 v[30:31], v[230:231], v[248:249], v[30:31] op_sel:[0,1,0] op_sel_hi:[1,1,1]
	s_waitcnt vmcnt(17)
	v_cvt_pk_f32_fp8_e32 v[224:225], v168
	v_cvt_pk_f32_fp8_sdwa v[226:227], v168 src0_sel:WORD_1
	v_cvt_pk_f32_fp8_e32 v[228:229], v169
	v_cvt_pk_f32_fp8_sdwa v[230:231], v169 src0_sel:WORD_1
	v_pk_fma_f32 v[16:17], v[224:225], v[250:251], v[16:17] op_sel_hi:[1,0,1]
	v_pk_fma_f32 v[18:19], v[226:227], v[250:251], v[18:19] op_sel_hi:[1,0,1]
	v_pk_fma_f32 v[20:21], v[228:229], v[250:251], v[20:21] op_sel_hi:[1,0,1]
	v_pk_fma_f32 v[22:23], v[230:231], v[250:251], v[22:23] op_sel_hi:[1,0,1]
	v_cvt_pk_f32_fp8_e32 v[224:225], v170
	v_cvt_pk_f32_fp8_sdwa v[226:227], v170 src0_sel:WORD_1
	v_cvt_pk_f32_fp8_e32 v[228:229], v171
	v_cvt_pk_f32_fp8_sdwa v[230:231], v171 src0_sel:WORD_1
	v_pk_fma_f32 v[24:25], v[224:225], v[250:251], v[24:25] op_sel_hi:[1,0,1]
	v_pk_fma_f32 v[26:27], v[226:227], v[250:251], v[26:27] op_sel_hi:[1,0,1]
	v_pk_fma_f32 v[28:29], v[228:229], v[250:251], v[28:29] op_sel_hi:[1,0,1]
	v_pk_fma_f32 v[30:31], v[230:231], v[250:251], v[30:31] op_sel_hi:[1,0,1]
	s_waitcnt vmcnt(16)
	v_cvt_pk_f32_fp8_e32 v[224:225], v172
	v_cvt_pk_f32_fp8_sdwa v[226:227], v172 src0_sel:WORD_1
	v_cvt_pk_f32_fp8_e32 v[228:229], v173
	v_cvt_pk_f32_fp8_sdwa v[230:231], v173 src0_sel:WORD_1
	v_pk_fma_f32 v[16:17], v[224:225], v[250:251], v[16:17] op_sel:[0,1,0] op_sel_hi:[1,1,1]
	v_pk_fma_f32 v[18:19], v[226:227], v[250:251], v[18:19] op_sel:[0,1,0] op_sel_hi:[1,1,1]
	v_pk_fma_f32 v[20:21], v[228:229], v[250:251], v[20:21] op_sel:[0,1,0] op_sel_hi:[1,1,1]
	v_pk_fma_f32 v[22:23], v[230:231], v[250:251], v[22:23] op_sel:[0,1,0] op_sel_hi:[1,1,1]
	v_cvt_pk_f32_fp8_e32 v[224:225], v174
	v_cvt_pk_f32_fp8_sdwa v[226:227], v174 src0_sel:WORD_1
	v_cvt_pk_f32_fp8_e32 v[228:229], v175
	v_cvt_pk_f32_fp8_sdwa v[230:231], v175 src0_sel:WORD_1
	v_pk_fma_f32 v[24:25], v[224:225], v[250:251], v[24:25] op_sel:[0,1,0] op_sel_hi:[1,1,1]
	v_pk_fma_f32 v[26:27], v[226:227], v[250:251], v[26:27] op_sel:[0,1,0] op_sel_hi:[1,1,1]
	v_pk_fma_f32 v[28:29], v[228:229], v[250:251], v[28:29] op_sel:[0,1,0] op_sel_hi:[1,1,1]
	v_pk_fma_f32 v[30:31], v[230:231], v[250:251], v[30:31] op_sel:[0,1,0] op_sel_hi:[1,1,1]
	s_sub_i32 s90, s90, 1
	s_cmp_eq_u32 s90, 0
	s_cbranch_scc1 .LV_sw3
.LV_t1_s3:
	s_waitcnt lgkmcnt(0)
	buffer_load_dwordx4 v[160:163], v[232:233], s[60:63], 0 idxen offen
	buffer_load_dwordx4 v[164:167], v[234:235], s[60:63], 0 idxen offen
	buffer_load_dwordx4 v[168:171], v[236:237], s[60:63], 0 idxen offen
	buffer_load_dwordx4 v[172:175], v[238:239], s[60:63], 0 idxen offen
	ds_read_b32 v232, v213 offset:128
	ds_read_b32 v234, v213 offset:132
	ds_read_b32 v236, v213 offset:136
	ds_read_b32 v238, v213 offset:140
	ds_read_b128 v[208:211], v213 offset:5056
	s_waitcnt vmcnt(19)
	v_cvt_pk_f32_fp8_e32 v[224:225], v176
	v_cvt_pk_f32_fp8_sdwa v[226:227], v176 src0_sel:WORD_1
	v_cvt_pk_f32_fp8_e32 v[228:229], v177
	v_cvt_pk_f32_fp8_sdwa v[230:231], v177 src0_sel:WORD_1
	v_pk_fma_f32 v[16:17], v[224:225], v[252:253], v[16:17] op_sel_hi:[1,0,1]
	v_pk_fma_f32 v[18:19], v[226:227], v[252:253], v[18:19] op_sel_hi:[1,0,1]
	v_pk_fma_f32 v[20:21], v[228:229], v[252:253], v[20:21] op_sel_hi:[1,0,1]
	v_pk_fma_f32 v[22:23], v[230:231], v[252:253], v[22:23] op_sel_hi:[1,0,1]
	v_cvt_pk_f32_fp8_e32 v[224:225], v178
	v_cvt_pk_f32_fp8_sdwa v[226:227], v178 src0_sel:WORD_1
	v_cvt_pk_f32_fp8_e32 v[228:229], v179
	v_cvt_pk_f32_fp8_sdwa v[230:231], v179 src0_sel:WORD_1
	v_pk_fma_f32 v[24:25], v[224:225], v[252:253], v[24:25] op_sel_hi:[1,0,1]
	v_pk_fma_f32 v[26:27], v[226:227], v[252:253], v[26:27] op_sel_hi:[1,0,1]
	v_pk_fma_f32 v[28:29], v[228:229], v[252:253], v[28:29] op_sel_hi:[1,0,1]
	v_pk_fma_f32 v[30:31], v[230:231], v[252:253], v[30:31] op_sel_hi:[1,0,1]
	s_waitcnt vmcnt(18)
	v_cvt_pk_f32_fp8_e32 v[224:225], v180
	v_cvt_pk_f32_fp8_sdwa v[226:227], v180 src0_sel:WORD_1
	v_cvt_pk_f32_fp8_e32 v[228:229], v181
	v_cvt_pk_f32_fp8_sdwa v[230:231], v181 src0_sel:WORD_1
	v_pk_fma_f32 v[16:17], v[224:225], v[252:253], v[16:17] op_sel:[0,1,0] op_sel_hi:[1,1,1]
	v_pk_fma_f32 v[18:19], v[226:227], v[252:253], v[18:19] op_sel:[0,1,0] op_sel_hi:[1,1,1]
	v_pk_fma_f32 v[20:21], v[228:229], v[252:253], v[20:21] op_sel:[0,1,0] op_sel_hi:[1,1,1]
	v_pk_fma_f32 v[22:23], v[230:231], v[252:253], v[22:23] op_sel:[0,1,0] op_sel_hi:[1,1,1]
	v_cvt_pk_f32_fp8_e32 v[224:225], v182
	v_cvt_pk_f32_fp8_sdwa v[226:227], v182 src0_sel:WORD_1
	v_cvt_pk_f32_fp8_e32 v[228:229], v183
	v_cvt_pk_f32_fp8_sdwa v[230:231], v183 src0_sel:WORD_1
	v_pk_fma_f32 v[24:25], v[224:225], v[252:253], v[24:25] op_sel:[0,1,0] op_sel_hi:[1,1,1]
	v_pk_fma_f32 v[26:27], v[226:227], v[252:253], v[26:27] op_sel:[0,1,0] op_sel_hi:[1,1,1]
	v_pk_fma_f32 v[28:29], v[228:229], v[252:253], v[28:29] op_sel:[0,1,0] op_sel_hi:[1,1,1]
	v_pk_fma_f32 v[30:31], v[230:231], v[252:253], v[30:31] op_sel:[0,1,0] op_sel_hi:[1,1,1]
	s_waitcnt vmcnt(17)
	v_cvt_pk_f32_fp8_e32 v[224:225], v184
	v_cvt_pk_f32_fp8_sdwa v[226:227], v184 src0_sel:WORD_1
	v_cvt_pk_f32_fp8_e32 v[228:229], v185
	v_cvt_pk_f32_fp8_sdwa v[230:231], v185 src0_sel:WORD_1
	v_pk_fma_f32 v[16:17], v[224:225], v[254:255], v[16:17] op_sel_hi:[1,0,1]
	v_pk_fma_f32 v[18:19], v[226:227], v[254:255], v[18:19] op_sel_hi:[1,0,1]
	v_pk_fma_f32 v[20:21], v[228:229], v[254:255], v[20:21] op_sel_hi:[1,0,1]
	v_pk_fma_f32 v[22:23], v[230:231], v[254:255], v[22:23] op_sel_hi:[1,0,1]
	v_cvt_pk_f32_fp8_e32 v[224:225], v186
	v_cvt_pk_f32_fp8_sdwa v[226:227], v186 src0_sel:WORD_1
	v_cvt_pk_f32_fp8_e32 v[228:229], v187
	v_cvt_pk_f32_fp8_sdwa v[230:231], v187 src0_sel:WORD_1
	v_pk_fma_f32 v[24:25], v[224:225], v[254:255], v[24:25] op_sel_hi:[1,0,1]
	v_pk_fma_f32 v[26:27], v[226:227], v[254:255], v[26:27] op_sel_hi:[1,0,1]
	v_pk_fma_f32 v[28:29], v[228:229], v[254:255], v[28:29] op_sel_hi:[1,0,1]
	v_pk_fma_f32 v[30:31], v[230:231], v[254:255], v[30:31] op_sel_hi:[1,0,1]
	s_waitcnt vmcnt(16)
	v_cvt_pk_f32_fp8_e32 v[224:225], v188
	v_cvt_pk_f32_fp8_sdwa v[226:227], v188 src0_sel:WORD_1
	v_cvt_pk_f32_fp8_e32 v[228:229], v189
	v_cvt_pk_f32_fp8_sdwa v[230:231], v189 src0_sel:WORD_1
	v_pk_fma_f32 v[16:17], v[224:225], v[254:255], v[16:17] op_sel:[0,1,0] op_sel_hi:[1,1,1]
	v_pk_fma_f32 v[18:19], v[226:227], v[254:255], v[18:19] op_sel:[0,1,0] op_sel_hi:[1,1,1]
	v_pk_fma_f32 v[20:21], v[228:229], v[254:255], v[20:21] op_sel:[0,1,0] op_sel_hi:[1,1,1]
	v_pk_fma_f32 v[22:23], v[230:231], v[254:255], v[22:23] op_sel:[0,1,0] op_sel_hi:[1,1,1]
	v_cvt_pk_f32_fp8_e32 v[224:225], v190
	v_cvt_pk_f32_fp8_sdwa v[226:227], v190 src0_sel:WORD_1
	v_cvt_pk_f32_fp8_e32 v[228:229], v191
	v_cvt_pk_f32_fp8_sdwa v[230:231], v191 src0_sel:WORD_1
	v_pk_fma_f32 v[24:25], v[224:225], v[254:255], v[24:25] op_sel:[0,1,0] op_sel_hi:[1,1,1]
	v_pk_fma_f32 v[26:27], v[226:227], v[254:255], v[26:27] op_sel:[0,1,0] op_sel_hi:[1,1,1]
	v_pk_fma_f32 v[28:29], v[228:229], v[254:255], v[28:29] op_sel:[0,1,0] op_sel_hi:[1,1,1]
	v_pk_fma_f32 v[30:31], v[230:231], v[254:255], v[30:31] op_sel:[0,1,0] op_sel_hi:[1,1,1]
	s_sub_i32 s90, s90, 1
	s_cmp_eq_u32 s90, 0
	s_cbranch_scc1 .LV_sw4
.LV_t1_s4:
	s_waitcnt lgkmcnt(0)
	buffer_load_dwordx4 v[176:179], v[232:233], s[60:63], 0 idxen offen
	buffer_load_dwordx4 v[180:183], v[234:235], s[60:63], 0 idxen offen
	buffer_load_dwordx4 v[184:187], v[236:237], s[60:63], 0 idxen offen
	buffer_load_dwordx4 v[188:191], v[238:239], s[60:63], 0 idxen offen
	ds_read_b32 v232, v213 offset:144
	ds_read_b32 v234, v213 offset:148
	ds_read_b32 v236, v213 offset:152
	ds_read_b32 v238, v213 offset:156
	ds_read_b128 v[248:251], v213 offset:5072
	s_waitcnt vmcnt(19)
	v_cvt_pk_f32_fp8_e32 v[224:225], v192
	v_cvt_pk_f32_fp8_sdwa v[226:227], v192 src0_sel:WORD_1
	v_cvt_pk_f32_fp8_e32 v[228:229], v193
	v_cvt_pk_f32_fp8_sdwa v[230:231], v193 src0_sel:WORD_1
	v_pk_fma_f32 v[16:17], v[224:225], v[208:209], v[16:17] op_sel_hi:[1,0,1]
	v_pk_fma_f32 v[18:19], v[226:227], v[208:209], v[18:19] op_sel_hi:[1,0,1]
	v_pk_fma_f32 v[20:21], v[228:229], v[208:209], v[20:21] op_sel_hi:[1,0,1]
	v_pk_fma_f32 v[22:23], v[230:231], v[208:209], v[22:23] op_sel_hi:[1,0,1]
	v_cvt_pk_f32_fp8_e32 v[224:225], v194
	v_cvt_pk_f32_fp8_sdwa v[226:227], v194 src0_sel:WORD_1
	v_cvt_pk_f32_fp8_e32 v[228:229], v195
	v_cvt_pk_f32_fp8_sdwa v[230:231], v195 src0_sel:WORD_1
	v_pk_fma_f32 v[24:25], v[224:225], v[208:209], v[24:25] op_sel_hi:[1,0,1]
	v_pk_fma_f32 v[26:27], v[226:227], v[208:209], v[26:27] op_sel_hi:[1,0,1]
	v_pk_fma_f32 v[28:29], v[228:229], v[208:209], v[28:29] op_sel_hi:[1,0,1]
	v_pk_fma_f32 v[30:31], v[230:231], v[208:209], v[30:31] op_sel_hi:[1,0,1]
	s_waitcnt vmcnt(18)
	v_cvt_pk_f32_fp8_e32 v[224:225], v196
	v_cvt_pk_f32_fp8_sdwa v[226:227], v196 src0_sel:WORD_1
	v_cvt_pk_f32_fp8_e32 v[228:229], v197
	v_cvt_pk_f32_fp8_sdwa v[230:231], v197 src0_sel:WORD_1
	v_pk_fma_f32 v[16:17], v[224:225], v[208:209], v[16:17] op_sel:[0,1,0] op_sel_hi:[1,1,1]
	v_pk_fma_f32 v[18:19], v[226:227], v[208:209], v[18:19] op_sel:[0,1,0] op_sel_hi:[1,1,1]
	v_pk_fma_f32 v[20:21], v[228:229], v[208:209], v[20:21] op_sel:[0,1,0] op_sel_hi:[1,1,1]
	v_pk_fma_f32 v[22:23], v[230:231], v[208:209], v[22:23] op_sel:[0,1,0] op_sel_hi:[1,1,1]
	v_cvt_pk_f32_fp8_e32 v[224:225], v198
	v_cvt_pk_f32_fp8_sdwa v[226:227], v198 src0_sel:WORD_1
	v_cvt_pk_f32_fp8_e32 v[228:229], v199
	v_cvt_pk_f32_fp8_sdwa v[230:231], v199 src0_sel:WORD_1
	v_pk_fma_f32 v[24:25], v[224:225], v[208:209], v[24:25] op_sel:[0,1,0] op_sel_hi:[1,1,1]
	v_pk_fma_f32 v[26:27], v[226:227], v[208:209], v[26:27] op_sel:[0,1,0] op_sel_hi:[1,1,1]
	v_pk_fma_f32 v[28:29], v[228:229], v[208:209], v[28:29] op_sel:[0,1,0] op_sel_hi:[1,1,1]
	v_pk_fma_f32 v[30:31], v[230:231], v[208:209], v[30:31] op_sel:[0,1,0] op_sel_hi:[1,1,1]
	s_waitcnt vmcnt(17)
	v_cvt_pk_f32_fp8_e32 v[224:225], v200
	v_cvt_pk_f32_fp8_sdwa v[226:227], v200 src0_sel:WORD_1
	v_cvt_pk_f32_fp8_e32 v[228:229], v201
	v_cvt_pk_f32_fp8_sdwa v[230:231], v201 src0_sel:WORD_1
	v_pk_fma_f32 v[16:17], v[224:225], v[210:211], v[16:17] op_sel_hi:[1,0,1]
	v_pk_fma_f32 v[18:19], v[226:227], v[210:211], v[18:19] op_sel_hi:[1,0,1]
	v_pk_fma_f32 v[20:21], v[228:229], v[210:211], v[20:21] op_sel_hi:[1,0,1]
	v_pk_fma_f32 v[22:23], v[230:231], v[210:211], v[22:23] op_sel_hi:[1,0,1]
	v_cvt_pk_f32_fp8_e32 v[224:225], v202
	v_cvt_pk_f32_fp8_sdwa v[226:227], v202 src0_sel:WORD_1
	v_cvt_pk_f32_fp8_e32 v[228:229], v203
	v_cvt_pk_f32_fp8_sdwa v[230:231], v203 src0_sel:WORD_1
	v_pk_fma_f32 v[24:25], v[224:225], v[210:211], v[24:25] op_sel_hi:[1,0,1]
	v_pk_fma_f32 v[26:27], v[226:227], v[210:211], v[26:27] op_sel_hi:[1,0,1]
	v_pk_fma_f32 v[28:29], v[228:229], v[210:211], v[28:29] op_sel_hi:[1,0,1]
	v_pk_fma_f32 v[30:31], v[230:231], v[210:211], v[30:31] op_sel_hi:[1,0,1]
	s_waitcnt vmcnt(16)
	v_cvt_pk_f32_fp8_e32 v[224:225], v204
	v_cvt_pk_f32_fp8_sdwa v[226:227], v204 src0_sel:WORD_1
	v_cvt_pk_f32_fp8_e32 v[228:229], v205
	v_cvt_pk_f32_fp8_sdwa v[230:231], v205 src0_sel:WORD_1
	v_pk_fma_f32 v[16:17], v[224:225], v[210:211], v[16:17] op_sel:[0,1,0] op_sel_hi:[1,1,1]
	v_pk_fma_f32 v[18:19], v[226:227], v[210:211], v[18:19] op_sel:[0,1,0] op_sel_hi:[1,1,1]
	v_pk_fma_f32 v[20:21], v[228:229], v[210:211], v[20:21] op_sel:[0,1,0] op_sel_hi:[1,1,1]
	v_pk_fma_f32 v[22:23], v[230:231], v[210:211], v[22:23] op_sel:[0,1,0] op_sel_hi:[1,1,1]
	v_cvt_pk_f32_fp8_e32 v[224:225], v206
	v_cvt_pk_f32_fp8_sdwa v[226:227], v206 src0_sel:WORD_1
	v_cvt_pk_f32_fp8_e32 v[228:229], v207
	v_cvt_pk_f32_fp8_sdwa v[230:231], v207 src0_sel:WORD_1
	v_pk_fma_f32 v[24:25], v[224:225], v[210:211], v[24:25] op_sel:[0,1,0] op_sel_hi:[1,1,1]
	v_pk_fma_f32 v[26:27], v[226:227], v[210:211], v[26:27] op_sel:[0,1,0] op_sel_hi:[1,1,1]
	v_pk_fma_f32 v[28:29], v[228:229], v[210:211], v[28:29] op_sel:[0,1,0] op_sel_hi:[1,1,1]
	v_pk_fma_f32 v[30:31], v[230:231], v[210:211], v[30:31] op_sel:[0,1,0] op_sel_hi:[1,1,1]
	v_add_u32_e32 v213, 80, v213
	s_add_i32 s21, s21, 5
	s_sub_i32 s90, s90, 1
	s_cmp_eq_u32 s90, 0
	s_cbranch_scc1 .LV_sw0
	s_branch .LV_t1_s0
.LV_t2_s0:
	s_cmp_ge_u32 s21, s20
	s_cbranch_scc1 .LV_done
	s_waitcnt lgkmcnt(0)
	buffer_load_dwordx4 v[192:195], v[232:233], s[60:63], 0 idxen offen
	buffer_load_dwordx4 v[196:199], v[234:235], s[60:63], 0 idxen offen
	buffer_load_dwordx4 v[200:203], v[236:237], s[60:63], 0 idxen offen
	buffer_load_dwordx4 v[204:207], v[238:239], s[60:63], 0 idxen offen
	ds_read_b32 v232, v213 offset:80
	ds_read_b32 v234, v213 offset:84
	ds_read_b32 v236, v213 offset:88
	ds_read_b32 v238, v213 offset:92
	ds_read_b128 v[252:255], v213 offset:5008
	s_waitcnt vmcnt(19)
	v_cvt_pk_f32_fp8_e32 v[224:225], v128
	v_cvt_pk_f32_fp8_sdwa v[226:227], v128 src0_sel:WORD_1
	v_cvt_pk_f32_fp8_e32 v[228:229], v129
	v_cvt_pk_f32_fp8_sdwa v[230:231], v129 src0_sel:WORD_1
	v_pk_fma_f32 v[32:33], v[224:225], v[248:249], v[32:33] op_sel_hi:[1,0,1]
	v_pk_fma_f32 v[34:35], v[226:227], v[248:249], v[34:35] op_sel_hi:[1,0,1]
	v_pk_fma_f32 v[36:37], v[228:229], v[248:249], v[36:37] op_sel_hi:[1,0,1]
	v_pk_fma_f32 v[38:39], v[230:231], v[248:249], v[38:39] op_sel_hi:[1,0,1]
	v_cvt_pk_f32_fp8_e32 v[224:225], v130
	v_cvt_pk_f32_fp8_sdwa v[226:227], v130 src0_sel:WORD_1
	v_cvt_pk_f32_fp8_e32 v[228:229], v131
	v_cvt_pk_f32_fp8_sdwa v[230:231], v131 src0_sel:WORD_1
	v_pk_fma_f32 v[40:41], v[224:225], v[248:249], v[40:41] op_sel_hi:[1,0,1]
	v_pk_fma_f32 v[42:43], v[226:227], v[248:249], v[42:43] op_sel_hi:[1,0,1]
	v_pk_fma_f32 v[44:45], v[228:229], v[248:249], v[44:45] op_sel_hi:[1,0,1]
	v_pk_fma_f32 v[46:47], v[230:231], v[248:249], v[46:47] op_sel_hi:[1,0,1]
	s_waitcnt vmcnt(18)
	v_cvt_pk_f32_fp8_e32 v[224:225], v132
	v_cvt_pk_f32_fp8_sdwa v[226:227], v132 src0_sel:WORD_1
	v_cvt_pk_f32_fp8_e32 v[228:229], v133
	v_cvt_pk_f32_fp8_sdwa v[230:231], v133 src0_sel:WORD_1
	v_pk_fma_f32 v[32:33], v[224:225], v[248:249], v[32:33] op_sel:[0,1,0] op_sel_hi:[1,1,1]
	v_pk_fma_f32 v[34:35], v[226:227], v[248:249], v[34:35] op_sel:[0,1,0] op_sel_hi:[1,1,1]
	v_pk_fma_f32 v[36:37], v[228:229], v[248:249], v[36:37] op_sel:[0,1,0] op_sel_hi:[1,1,1]
	v_pk_fma_f32 v[38:39], v[230:231], v[248:249], v[38:39] op_sel:[0,1,0] op_sel_hi:[1,1,1]
	v_cvt_pk_f32_fp8_e32 v[224:225], v134
	v_cvt_pk_f32_fp8_sdwa v[226:227], v134 src0_sel:WORD_1
	v_cvt_pk_f32_fp8_e32 v[228:229], v135
	v_cvt_pk_f32_fp8_sdwa v[230:231], v135 src0_sel:WORD_1
	v_pk_fma_f32 v[40:41], v[224:225], v[248:249], v[40:41] op_sel:[0,1,0] op_sel_hi:[1,1,1]
	v_pk_fma_f32 v[42:43], v[226:227], v[248:249], v[42:43] op_sel:[0,1,0] op_sel_hi:[1,1,1]
	v_pk_fma_f32 v[44:45], v[228:229], v[248:249], v[44:45] op_sel:[0,1,0] op_sel_hi:[1,1,1]
	v_pk_fma_f32 v[46:47], v[230:231], v[248:249], v[46:47] op_sel:[0,1,0] op_sel_hi:[1,1,1]
	s_waitcnt vmcnt(17)
	v_cvt_pk_f32_fp8_e32 v[224:225], v136
	v_cvt_pk_f32_fp8_sdwa v[226:227], v136 src0_sel:WORD_1
	v_cvt_pk_f32_fp8_e32 v[228:229], v137
	v_cvt_pk_f32_fp8_sdwa v[230:231], v137 src0_sel:WORD_1
	v_pk_fma_f32 v[32:33], v[224:225], v[250:251], v[32:33] op_sel_hi:[1,0,1]
	v_pk_fma_f32 v[34:35], v[226:227], v[250:251], v[34:35] op_sel_hi:[1,0,1]
	v_pk_fma_f32 v[36:37], v[228:229], v[250:251], v[36:37] op_sel_hi:[1,0,1]
	v_pk_fma_f32 v[38:39], v[230:231], v[250:251], v[38:39] op_sel_hi:[1,0,1]
	v_cvt_pk_f32_fp8_e32 v[224:225], v138
	v_cvt_pk_f32_fp8_sdwa v[226:227], v138 src0_sel:WORD_1
	v_cvt_pk_f32_fp8_e32 v[228:229], v139
	v_cvt_pk_f32_fp8_sdwa v[230:231], v139 src0_sel:WORD_1
	v_pk_fma_f32 v[40:41], v[224:225], v[250:251], v[40:41] op_sel_hi:[1,0,1]
	v_pk_fma_f32 v[42:43], v[226:227], v[250:251], v[42:43] op_sel_hi:[1,0,1]
	v_pk_fma_f32 v[44:45], v[228:229], v[250:251], v[44:45] op_sel_hi:[1,0,1]
	v_pk_fma_f32 v[46:47], v[230:231], v[250:251], v[46:47] op_sel_hi:[1,0,1]
	s_waitcnt vmcnt(16)
	v_cvt_pk_f32_fp8_e32 v[224:225], v140
	v_cvt_pk_f32_fp8_sdwa v[226:227], v140 src0_sel:WORD_1
	v_cvt_pk_f32_fp8_e32 v[228:229], v141
	v_cvt_pk_f32_fp8_sdwa v[230:231], v141 src0_sel:WORD_1
	v_pk_fma_f32 v[32:33], v[224:225], v[250:251], v[32:33] op_sel:[0,1,0] op_sel_hi:[1,1,1]
	v_pk_fma_f32 v[34:35], v[226:227], v[250:251], v[34:35] op_sel:[0,1,0] op_sel_hi:[1,1,1]
	v_pk_fma_f32 v[36:37], v[228:229], v[250:251], v[36:37] op_sel:[0,1,0] op_sel_hi:[1,1,1]
	v_pk_fma_f32 v[38:39], v[230:231], v[250:251], v[38:39] op_sel:[0,1,0] op_sel_hi:[1,1,1]
	v_cvt_pk_f32_fp8_e32 v[224:225], v142
	v_cvt_pk_f32_fp8_sdwa v[226:227], v142 src0_sel:WORD_1
	v_cvt_pk_f32_fp8_e32 v[228:229], v143
	v_cvt_pk_f32_fp8_sdwa v[230:231], v143 src0_sel:WORD_1
	v_pk_fma_f32 v[40:41], v[224:225], v[250:251], v[40:41] op_sel:[0,1,0] op_sel_hi:[1,1,1]
	v_pk_fma_f32 v[42:43], v[226:227], v[250:251], v[42:43] op_sel:[0,1,0] op_sel_hi:[1,1,1]
	v_pk_fma_f32 v[44:45], v[228:229], v[250:251], v[44:45] op_sel:[0,1,0] op_sel_hi:[1,1,1]
	v_pk_fma_f32 v[46:47], v[230:231], v[250:251], v[46:47] op_sel:[0,1,0] op_sel_hi:[1,1,1]
	s_sub_i32 s90, s90, 1
	s_cmp_eq_u32 s90, 0
	s_cbranch_scc1 .LV_sw1
.LV_t2_s1:
	s_waitcnt lgkmcnt(0)
	buffer_load_dwordx4 v[128:131], v[232:233], s[60:63], 0 idxen offen
	buffer_load_dwordx4 v[132:135], v[234:235], s[60:63], 0 idxen offen
	buffer_load_dwordx4 v[136:139], v[236:237], s[60:63], 0 idxen offen
	buffer_load_dwordx4 v[140:143], v[238:239], s[60:63], 0 idxen offen
	ds_read_b32 v232, v213 offset:96
	ds_read_b32 v234, v213 offset:100
	ds_read_b32 v236, v213 offset:104
	ds_read_b32 v238, v213 offset:108
	ds_read_b128 v[248:251], v213 offset:5024
	s_waitcnt vmcnt(19)
	v_cvt_pk_f32_fp8_e32 v[224:225], v144
	v_cvt_pk_f32_fp8_sdwa v[226:227], v144 src0_sel:WORD_1
	v_cvt_pk_f32_fp8_e32 v[228:229], v145
	v_cvt_pk_f32_fp8_sdwa v[230:231], v145 src0_sel:WORD_1
	v_pk_fma_f32 v[32:33], v[224:225], v[252:253], v[32:33] op_sel_hi:[1,0,1]
	v_pk_fma_f32 v[34:35], v[226:227], v[252:253], v[34:35] op_sel_hi:[1,0,1]
	v_pk_fma_f32 v[36:37], v[228:229], v[252:253], v[36:37] op_sel_hi:[1,0,1]
	v_pk_fma_f32 v[38:39], v[230:231], v[252:253], v[38:39] op_sel_hi:[1,0,1]
	v_cvt_pk_f32_fp8_e32 v[224:225], v146
	v_cvt_pk_f32_fp8_sdwa v[226:227], v146 src0_sel:WORD_1
	v_cvt_pk_f32_fp8_e32 v[228:229], v147
	v_cvt_pk_f32_fp8_sdwa v[230:231], v147 src0_sel:WORD_1
	v_pk_fma_f32 v[40:41], v[224:225], v[252:253], v[40:41] op_sel_hi:[1,0,1]
	v_pk_fma_f32 v[42:43], v[226:227], v[252:253], v[42:43] op_sel_hi:[1,0,1]
	v_pk_fma_f32 v[44:45], v[228:229], v[252:253], v[44:45] op_sel_hi:[1,0,1]
	v_pk_fma_f32 v[46:47], v[230:231], v[252:253], v[46:47] op_sel_hi:[1,0,1]
	s_waitcnt vmcnt(18)
	v_cvt_pk_f32_fp8_e32 v[224:225], v148
	v_cvt_pk_f32_fp8_sdwa v[226:227], v148 src0_sel:WORD_1
	v_cvt_pk_f32_fp8_e32 v[228:229], v149
	v_cvt_pk_f32_fp8_sdwa v[230:231], v149 src0_sel:WORD_1
	v_pk_fma_f32 v[32:33], v[224:225], v[252:253], v[32:33] op_sel:[0,1,0] op_sel_hi:[1,1,1]
	v_pk_fma_f32 v[34:35], v[226:227], v[252:253], v[34:35] op_sel:[0,1,0] op_sel_hi:[1,1,1]
	v_pk_fma_f32 v[36:37], v[228:229], v[252:253], v[36:37] op_sel:[0,1,0] op_sel_hi:[1,1,1]
	v_pk_fma_f32 v[38:39], v[230:231], v[252:253], v[38:39] op_sel:[0,1,0] op_sel_hi:[1,1,1]
	v_cvt_pk_f32_fp8_e32 v[224:225], v150
	v_cvt_pk_f32_fp8_sdwa v[226:227], v150 src0_sel:WORD_1
	v_cvt_pk_f32_fp8_e32 v[228:229], v151
	v_cvt_pk_f32_fp8_sdwa v[230:231], v151 src0_sel:WORD_1
	v_pk_fma_f32 v[40:41], v[224:225], v[252:253], v[40:41] op_sel:[0,1,0] op_sel_hi:[1,1,1]
	v_pk_fma_f32 v[42:43], v[226:227], v[252:253], v[42:43] op_sel:[0,1,0] op_sel_hi:[1,1,1]
	v_pk_fma_f32 v[44:45], v[228:229], v[252:253], v[44:45] op_sel:[0,1,0] op_sel_hi:[1,1,1]
	v_pk_fma_f32 v[46:47], v[230:231], v[252:253], v[46:47] op_sel:[0,1,0] op_sel_hi:[1,1,1]
	s_waitcnt vmcnt(17)
	v_cvt_pk_f32_fp8_e32 v[224:225], v152
	v_cvt_pk_f32_fp8_sdwa v[226:227], v152 src0_sel:WORD_1
	v_cvt_pk_f32_fp8_e32 v[228:229], v153
	v_cvt_pk_f32_fp8_sdwa v[230:231], v153 src0_sel:WORD_1
	v_pk_fma_f32 v[32:33], v[224:225], v[254:255], v[32:33] op_sel_hi:[1,0,1]
	v_pk_fma_f32 v[34:35], v[226:227], v[254:255], v[34:35] op_sel_hi:[1,0,1]
	v_pk_fma_f32 v[36:37], v[228:229], v[254:255], v[36:37] op_sel_hi:[1,0,1]
	v_pk_fma_f32 v[38:39], v[230:231], v[254:255], v[38:39] op_sel_hi:[1,0,1]
	v_cvt_pk_f32_fp8_e32 v[224:225], v154
	v_cvt_pk_f32_fp8_sdwa v[226:227], v154 src0_sel:WORD_1
	v_cvt_pk_f32_fp8_e32 v[228:229], v155
	v_cvt_pk_f32_fp8_sdwa v[230:231], v155 src0_sel:WORD_1
	v_pk_fma_f32 v[40:41], v[224:225], v[254:255], v[40:41] op_sel_hi:[1,0,1]
	v_pk_fma_f32 v[42:43], v[226:227], v[254:255], v[42:43] op_sel_hi:[1,0,1]
	v_pk_fma_f32 v[44:45], v[228:229], v[254:255], v[44:45] op_sel_hi:[1,0,1]
	v_pk_fma_f32 v[46:47], v[230:231], v[254:255], v[46:47] op_sel_hi:[1,0,1]
	s_waitcnt vmcnt(16)
	v_cvt_pk_f32_fp8_e32 v[224:225], v156
	v_cvt_pk_f32_fp8_sdwa v[226:227], v156 src0_sel:WORD_1
	v_cvt_pk_f32_fp8_e32 v[228:229], v157
	v_cvt_pk_f32_fp8_sdwa v[230:231], v157 src0_sel:WORD_1
	v_pk_fma_f32 v[32:33], v[224:225], v[254:255], v[32:33] op_sel:[0,1,0] op_sel_hi:[1,1,1]
	v_pk_fma_f32 v[34:35], v[226:227], v[254:255], v[34:35] op_sel:[0,1,0] op_sel_hi:[1,1,1]
	v_pk_fma_f32 v[36:37], v[228:229], v[254:255], v[36:37] op_sel:[0,1,0] op_sel_hi:[1,1,1]
	v_pk_fma_f32 v[38:39], v[230:231], v[254:255], v[38:39] op_sel:[0,1,0] op_sel_hi:[1,1,1]
	v_cvt_pk_f32_fp8_e32 v[224:225], v158
	v_cvt_pk_f32_fp8_sdwa v[226:227], v158 src0_sel:WORD_1
	v_cvt_pk_f32_fp8_e32 v[228:229], v159
	v_cvt_pk_f32_fp8_sdwa v[230:231], v159 src0_sel:WORD_1
	v_pk_fma_f32 v[40:41], v[224:225], v[254:255], v[40:41] op_sel:[0,1,0] op_sel_hi:[1,1,1]
	v_pk_fma_f32 v[42:43], v[226:227], v[254:255], v[42:43] op_sel:[0,1,0] op_sel_hi:[1,1,1]
	v_pk_fma_f32 v[44:45], v[228:229], v[254:255], v[44:45] op_sel:[0,1,0] op_sel_hi:[1,1,1]
	v_pk_fma_f32 v[46:47], v[230:231], v[254:255], v[46:47] op_sel:[0,1,0] op_sel_hi:[1,1,1]
	s_sub_i32 s90, s90, 1
	s_cmp_eq_u32 s90, 0
	s_cbranch_scc1 .LV_sw2
.LV_t2_s2:
	s_waitcnt lgkmcnt(0)
	buffer_load_dwordx4 v[144:147], v[232:233], s[60:63], 0 idxen offen
	buffer_load_dwordx4 v[148:151], v[234:235], s[60:63], 0 idxen offen
	buffer_load_dwordx4 v[152:155], v[236:237], s[60:63], 0 idxen offen
	buffer_load_dwordx4 v[156:159], v[238:239], s[60:63], 0 idxen offen
	ds_read_b32 v232, v213 offset:112
	ds_read_b32 v234, v213 offset:116
	ds_read_b32 v236, v213 offset:120
	ds_read_b32 v238, v213 offset:124
	ds_read_b128 v[252:255], v213 offset:5040
	s_waitcnt vmcnt(19)
	v_cvt_pk_f32_fp8_e32 v[224:225], v160
	v_cvt_pk_f32_fp8_sdwa v[226:227], v160 src0_sel:WORD_1
	v_cvt_pk_f32_fp8_e32 v[228:229], v161
	v_cvt_pk_f32_fp8_sdwa v[230:231], v161 src0_sel:WORD_1
	v_pk_fma_f32 v[32:33], v[224:225], v[248:249], v[32:33] op_sel_hi:[1,0,1]
	v_pk_fma_f32 v[34:35], v[226:227], v[248:249], v[34:35] op_sel_hi:[1,0,1]
	v_pk_fma_f32 v[36:37], v[228:229], v[248:249], v[36:37] op_sel_hi:[1,0,1]
	v_pk_fma_f32 v[38:39], v[230:231], v[248:249], v[38:39] op_sel_hi:[1,0,1]
	v_cvt_pk_f32_fp8_e32 v[224:225], v162
	v_cvt_pk_f32_fp8_sdwa v[226:227], v162 src0_sel:WORD_1
	v_cvt_pk_f32_fp8_e32 v[228:229], v163
	v_cvt_pk_f32_fp8_sdwa v[230:231], v163 src0_sel:WORD_1
	v_pk_fma_f32 v[40:41], v[224:225], v[248:249], v[40:41] op_sel_hi:[1,0,1]
	v_pk_fma_f32 v[42:43], v[226:227], v[248:249], v[42:43] op_sel_hi:[1,0,1]
	v_pk_fma_f32 v[44:45], v[228:229], v[248:249], v[44:45] op_sel_hi:[1,0,1]
	v_pk_fma_f32 v[46:47], v[230:231], v[248:249], v[46:47] op_sel_hi:[1,0,1]
	s_waitcnt vmcnt(18)
	v_cvt_pk_f32_fp8_e32 v[224:225], v164
	v_cvt_pk_f32_fp8_sdwa v[226:227], v164 src0_sel:WORD_1
	v_cvt_pk_f32_fp8_e32 v[228:229], v165
	v_cvt_pk_f32_fp8_sdwa v[230:231], v165 src0_sel:WORD_1
	v_pk_fma_f32 v[32:33], v[224:225], v[248:249], v[32:33] op_sel:[0,1,0] op_sel_hi:[1,1,1]
	v_pk_fma_f32 v[34:35], v[226:227], v[248:249], v[34:35] op_sel:[0,1,0] op_sel_hi:[1,1,1]
	v_pk_fma_f32 v[36:37], v[228:229], v[248:249], v[36:37] op_sel:[0,1,0] op_sel_hi:[1,1,1]
	v_pk_fma_f32 v[38:39], v[230:231], v[248:249], v[38:39] op_sel:[0,1,0] op_sel_hi:[1,1,1]
	v_cvt_pk_f32_fp8_e32 v[224:225], v166
	v_cvt_pk_f32_fp8_sdwa v[226:227], v166 src0_sel:WORD_1
	v_cvt_pk_f32_fp8_e32 v[228:229], v167
	v_cvt_pk_f32_fp8_sdwa v[230:231], v167 src0_sel:WORD_1
	v_pk_fma_f32 v[40:41], v[224:225], v[248:249], v[40:41] op_sel:[0,1,0] op_sel_hi:[1,1,1]
	v_pk_fma_f32 v[42:43], v[226:227], v[248:249], v[42:43] op_sel:[0,1,0] op_sel_hi:[1,1,1]
	v_pk_fma_f32 v[44:45], v[228:229], v[248:249], v[44:45] op_sel:[0,1,0] op_sel_hi:[1,1,1]
	v_pk_fma_f32 v[46:47], v[230:231], v[248:249], v[46:47] op_sel:[0,1,0] op_sel_hi:[1,1,1]
	s_waitcnt vmcnt(17)
	v_cvt_pk_f32_fp8_e32 v[224:225], v168
	v_cvt_pk_f32_fp8_sdwa v[226:227], v168 src0_sel:WORD_1
	v_cvt_pk_f32_fp8_e32 v[228:229], v169
	v_cvt_pk_f32_fp8_sdwa v[230:231], v169 src0_sel:WORD_1
	v_pk_fma_f32 v[32:33], v[224:225], v[250:251], v[32:33] op_sel_hi:[1,0,1]
	v_pk_fma_f32 v[34:35], v[226:227], v[250:251], v[34:35] op_sel_hi:[1,0,1]
	v_pk_fma_f32 v[36:37], v[228:229], v[250:251], v[36:37] op_sel_hi:[1,0,1]
	v_pk_fma_f32 v[38:39], v[230:231], v[250:251], v[38:39] op_sel_hi:[1,0,1]
	v_cvt_pk_f32_fp8_e32 v[224:225], v170
	v_cvt_pk_f32_fp8_sdwa v[226:227], v170 src0_sel:WORD_1
	v_cvt_pk_f32_fp8_e32 v[228:229], v171
	v_cvt_pk_f32_fp8_sdwa v[230:231], v171 src0_sel:WORD_1
	v_pk_fma_f32 v[40:41], v[224:225], v[250:251], v[40:41] op_sel_hi:[1,0,1]
	v_pk_fma_f32 v[42:43], v[226:227], v[250:251], v[42:43] op_sel_hi:[1,0,1]
	v_pk_fma_f32 v[44:45], v[228:229], v[250:251], v[44:45] op_sel_hi:[1,0,1]
	v_pk_fma_f32 v[46:47], v[230:231], v[250:251], v[46:47] op_sel_hi:[1,0,1]
	s_waitcnt vmcnt(16)
	v_cvt_pk_f32_fp8_e32 v[224:225], v172
	v_cvt_pk_f32_fp8_sdwa v[226:227], v172 src0_sel:WORD_1
	v_cvt_pk_f32_fp8_e32 v[228:229], v173
	v_cvt_pk_f32_fp8_sdwa v[230:231], v173 src0_sel:WORD_1
	v_pk_fma_f32 v[32:33], v[224:225], v[250:251], v[32:33] op_sel:[0,1,0] op_sel_hi:[1,1,1]
	v_pk_fma_f32 v[34:35], v[226:227], v[250:251], v[34:35] op_sel:[0,1,0] op_sel_hi:[1,1,1]
	v_pk_fma_f32 v[36:37], v[228:229], v[250:251], v[36:37] op_sel:[0,1,0] op_sel_hi:[1,1,1]
	v_pk_fma_f32 v[38:39], v[230:231], v[250:251], v[38:39] op_sel:[0,1,0] op_sel_hi:[1,1,1]
	v_cvt_pk_f32_fp8_e32 v[224:225], v174
	v_cvt_pk_f32_fp8_sdwa v[226:227], v174 src0_sel:WORD_1
	v_cvt_pk_f32_fp8_e32 v[228:229], v175
	v_cvt_pk_f32_fp8_sdwa v[230:231], v175 src0_sel:WORD_1
	v_pk_fma_f32 v[40:41], v[224:225], v[250:251], v[40:41] op_sel:[0,1,0] op_sel_hi:[1,1,1]
	v_pk_fma_f32 v[42:43], v[226:227], v[250:251], v[42:43] op_sel:[0,1,0] op_sel_hi:[1,1,1]
	v_pk_fma_f32 v[44:45], v[228:229], v[250:251], v[44:45] op_sel:[0,1,0] op_sel_hi:[1,1,1]
	v_pk_fma_f32 v[46:47], v[230:231], v[250:251], v[46:47] op_sel:[0,1,0] op_sel_hi:[1,1,1]
	s_sub_i32 s90, s90, 1
	s_cmp_eq_u32 s90, 0
	s_cbranch_scc1 .LV_sw3
.LV_t2_s3:
	s_waitcnt lgkmcnt(0)
	buffer_load_dwordx4 v[160:163], v[232:233], s[60:63], 0 idxen offen
	buffer_load_dwordx4 v[164:167], v[234:235], s[60:63], 0 idxen offen
	buffer_load_dwordx4 v[168:171], v[236:237], s[60:63], 0 idxen offen
	buffer_load_dwordx4 v[172:175], v[238:239], s[60:63], 0 idxen offen
	ds_read_b32 v232, v213 offset:128
	ds_read_b32 v234, v213 offset:132
	ds_read_b32 v236, v213 offset:136
	ds_read_b32 v238, v213 offset:140
	ds_read_b128 v[208:211], v213 offset:5056
	s_waitcnt vmcnt(19)
	v_cvt_pk_f32_fp8_e32 v[224:225], v176
	v_cvt_pk_f32_fp8_sdwa v[226:227], v176 src0_sel:WORD_1
	v_cvt_pk_f32_fp8_e32 v[228:229], v177
	v_cvt_pk_f32_fp8_sdwa v[230:231], v177 src0_sel:WORD_1
	v_pk_fma_f32 v[32:33], v[224:225], v[252:253], v[32:33] op_sel_hi:[1,0,1]
	v_pk_fma_f32 v[34:35], v[226:227], v[252:253], v[34:35] op_sel_hi:[1,0,1]
	v_pk_fma_f32 v[36:37], v[228:229], v[252:253], v[36:37] op_sel_hi:[1,0,1]
	v_pk_fma_f32 v[38:39], v[230:231], v[252:253], v[38:39] op_sel_hi:[1,0,1]
	v_cvt_pk_f32_fp8_e32 v[224:225], v178
	v_cvt_pk_f32_fp8_sdwa v[226:227], v178 src0_sel:WORD_1
	v_cvt_pk_f32_fp8_e32 v[228:229], v179
	v_cvt_pk_f32_fp8_sdwa v[230:231], v179 src0_sel:WORD_1
	v_pk_fma_f32 v[40:41], v[224:225], v[252:253], v[40:41] op_sel_hi:[1,0,1]
	v_pk_fma_f32 v[42:43], v[226:227], v[252:253], v[42:43] op_sel_hi:[1,0,1]
	v_pk_fma_f32 v[44:45], v[228:229], v[252:253], v[44:45] op_sel_hi:[1,0,1]
	v_pk_fma_f32 v[46:47], v[230:231], v[252:253], v[46:47] op_sel_hi:[1,0,1]
	s_waitcnt vmcnt(18)
	v_cvt_pk_f32_fp8_e32 v[224:225], v180
	v_cvt_pk_f32_fp8_sdwa v[226:227], v180 src0_sel:WORD_1
	v_cvt_pk_f32_fp8_e32 v[228:229], v181
	v_cvt_pk_f32_fp8_sdwa v[230:231], v181 src0_sel:WORD_1
	v_pk_fma_f32 v[32:33], v[224:225], v[252:253], v[32:33] op_sel:[0,1,0] op_sel_hi:[1,1,1]
	v_pk_fma_f32 v[34:35], v[226:227], v[252:253], v[34:35] op_sel:[0,1,0] op_sel_hi:[1,1,1]
	v_pk_fma_f32 v[36:37], v[228:229], v[252:253], v[36:37] op_sel:[0,1,0] op_sel_hi:[1,1,1]
	v_pk_fma_f32 v[38:39], v[230:231], v[252:253], v[38:39] op_sel:[0,1,0] op_sel_hi:[1,1,1]
	v_cvt_pk_f32_fp8_e32 v[224:225], v182
	v_cvt_pk_f32_fp8_sdwa v[226:227], v182 src0_sel:WORD_1
	v_cvt_pk_f32_fp8_e32 v[228:229], v183
	v_cvt_pk_f32_fp8_sdwa v[230:231], v183 src0_sel:WORD_1
	v_pk_fma_f32 v[40:41], v[224:225], v[252:253], v[40:41] op_sel:[0,1,0] op_sel_hi:[1,1,1]
	v_pk_fma_f32 v[42:43], v[226:227], v[252:253], v[42:43] op_sel:[0,1,0] op_sel_hi:[1,1,1]
	v_pk_fma_f32 v[44:45], v[228:229], v[252:253], v[44:45] op_sel:[0,1,0] op_sel_hi:[1,1,1]
	v_pk_fma_f32 v[46:47], v[230:231], v[252:253], v[46:47] op_sel:[0,1,0] op_sel_hi:[1,1,1]
	s_waitcnt vmcnt(17)
	v_cvt_pk_f32_fp8_e32 v[224:225], v184
	v_cvt_pk_f32_fp8_sdwa v[226:227], v184 src0_sel:WORD_1
	v_cvt_pk_f32_fp8_e32 v[228:229], v185
	v_cvt_pk_f32_fp8_sdwa v[230:231], v185 src0_sel:WORD_1
	v_pk_fma_f32 v[32:33], v[224:225], v[254:255], v[32:33] op_sel_hi:[1,0,1]
	v_pk_fma_f32 v[34:35], v[226:227], v[254:255], v[34:35] op_sel_hi:[1,0,1]
	v_pk_fma_f32 v[36:37], v[228:229], v[254:255], v[36:37] op_sel_hi:[1,0,1]
	v_pk_fma_f32 v[38:39], v[230:231], v[254:255], v[38:39] op_sel_hi:[1,0,1]
	v_cvt_pk_f32_fp8_e32 v[224:225], v186
	v_cvt_pk_f32_fp8_sdwa v[226:227], v186 src0_sel:WORD_1
	v_cvt_pk_f32_fp8_e32 v[228:229], v187
	v_cvt_pk_f32_fp8_sdwa v[230:231], v187 src0_sel:WORD_1
	v_pk_fma_f32 v[40:41], v[224:225], v[254:255], v[40:41] op_sel_hi:[1,0,1]
	v_pk_fma_f32 v[42:43], v[226:227], v[254:255], v[42:43] op_sel_hi:[1,0,1]
	v_pk_fma_f32 v[44:45], v[228:229], v[254:255], v[44:45] op_sel_hi:[1,0,1]
	v_pk_fma_f32 v[46:47], v[230:231], v[254:255], v[46:47] op_sel_hi:[1,0,1]
	s_waitcnt vmcnt(16)
	v_cvt_pk_f32_fp8_e32 v[224:225], v188
	v_cvt_pk_f32_fp8_sdwa v[226:227], v188 src0_sel:WORD_1
	v_cvt_pk_f32_fp8_e32 v[228:229], v189
	v_cvt_pk_f32_fp8_sdwa v[230:231], v189 src0_sel:WORD_1
	v_pk_fma_f32 v[32:33], v[224:225], v[254:255], v[32:33] op_sel:[0,1,0] op_sel_hi:[1,1,1]
	v_pk_fma_f32 v[34:35], v[226:227], v[254:255], v[34:35] op_sel:[0,1,0] op_sel_hi:[1,1,1]
	v_pk_fma_f32 v[36:37], v[228:229], v[254:255], v[36:37] op_sel:[0,1,0] op_sel_hi:[1,1,1]
	v_pk_fma_f32 v[38:39], v[230:231], v[254:255], v[38:39] op_sel:[0,1,0] op_sel_hi:[1,1,1]
	v_cvt_pk_f32_fp8_e32 v[224:225], v190
	v_cvt_pk_f32_fp8_sdwa v[226:227], v190 src0_sel:WORD_1
	v_cvt_pk_f32_fp8_e32 v[228:229], v191
	v_cvt_pk_f32_fp8_sdwa v[230:231], v191 src0_sel:WORD_1
	v_pk_fma_f32 v[40:41], v[224:225], v[254:255], v[40:41] op_sel:[0,1,0] op_sel_hi:[1,1,1]
	v_pk_fma_f32 v[42:43], v[226:227], v[254:255], v[42:43] op_sel:[0,1,0] op_sel_hi:[1,1,1]
	v_pk_fma_f32 v[44:45], v[228:229], v[254:255], v[44:45] op_sel:[0,1,0] op_sel_hi:[1,1,1]
	v_pk_fma_f32 v[46:47], v[230:231], v[254:255], v[46:47] op_sel:[0,1,0] op_sel_hi:[1,1,1]
	s_sub_i32 s90, s90, 1
	s_cmp_eq_u32 s90, 0
	s_cbranch_scc1 .LV_sw4
.LV_t2_s4:
	s_waitcnt lgkmcnt(0)
	buffer_load_dwordx4 v[176:179], v[232:233], s[60:63], 0 idxen offen
	buffer_load_dwordx4 v[180:183], v[234:235], s[60:63], 0 idxen offen
	buffer_load_dwordx4 v[184:187], v[236:237], s[60:63], 0 idxen offen
	buffer_load_dwordx4 v[188:191], v[238:239], s[60:63], 0 idxen offen
	ds_read_b32 v232, v213 offset:144
	ds_read_b32 v234, v213 offset:148
	ds_read_b32 v236, v213 offset:152
	ds_read_b32 v238, v213 offset:156
	ds_read_b128 v[248:251], v213 offset:5072
	s_waitcnt vmcnt(19)
	v_cvt_pk_f32_fp8_e32 v[224:225], v192
	v_cvt_pk_f32_fp8_sdwa v[226:227], v192 src0_sel:WORD_1
	v_cvt_pk_f32_fp8_e32 v[228:229], v193
	v_cvt_pk_f32_fp8_sdwa v[230:231], v193 src0_sel:WORD_1
	v_pk_fma_f32 v[32:33], v[224:225], v[208:209], v[32:33] op_sel_hi:[1,0,1]
	v_pk_fma_f32 v[34:35], v[226:227], v[208:209], v[34:35] op_sel_hi:[1,0,1]
	v_pk_fma_f32 v[36:37], v[228:229], v[208:209], v[36:37] op_sel_hi:[1,0,1]
	v_pk_fma_f32 v[38:39], v[230:231], v[208:209], v[38:39] op_sel_hi:[1,0,1]
	v_cvt_pk_f32_fp8_e32 v[224:225], v194
	v_cvt_pk_f32_fp8_sdwa v[226:227], v194 src0_sel:WORD_1
	v_cvt_pk_f32_fp8_e32 v[228:229], v195
	v_cvt_pk_f32_fp8_sdwa v[230:231], v195 src0_sel:WORD_1
	v_pk_fma_f32 v[40:41], v[224:225], v[208:209], v[40:41] op_sel_hi:[1,0,1]
	v_pk_fma_f32 v[42:43], v[226:227], v[208:209], v[42:43] op_sel_hi:[1,0,1]
	v_pk_fma_f32 v[44:45], v[228:229], v[208:209], v[44:45] op_sel_hi:[1,0,1]
	v_pk_fma_f32 v[46:47], v[230:231], v[208:209], v[46:47] op_sel_hi:[1,0,1]
	s_waitcnt vmcnt(18)
	v_cvt_pk_f32_fp8_e32 v[224:225], v196
	v_cvt_pk_f32_fp8_sdwa v[226:227], v196 src0_sel:WORD_1
	v_cvt_pk_f32_fp8_e32 v[228:229], v197
	v_cvt_pk_f32_fp8_sdwa v[230:231], v197 src0_sel:WORD_1
	v_pk_fma_f32 v[32:33], v[224:225], v[208:209], v[32:33] op_sel:[0,1,0] op_sel_hi:[1,1,1]
	v_pk_fma_f32 v[34:35], v[226:227], v[208:209], v[34:35] op_sel:[0,1,0] op_sel_hi:[1,1,1]
	v_pk_fma_f32 v[36:37], v[228:229], v[208:209], v[36:37] op_sel:[0,1,0] op_sel_hi:[1,1,1]
	v_pk_fma_f32 v[38:39], v[230:231], v[208:209], v[38:39] op_sel:[0,1,0] op_sel_hi:[1,1,1]
	v_cvt_pk_f32_fp8_e32 v[224:225], v198
	v_cvt_pk_f32_fp8_sdwa v[226:227], v198 src0_sel:WORD_1
	v_cvt_pk_f32_fp8_e32 v[228:229], v199
	v_cvt_pk_f32_fp8_sdwa v[230:231], v199 src0_sel:WORD_1
	v_pk_fma_f32 v[40:41], v[224:225], v[208:209], v[40:41] op_sel:[0,1,0] op_sel_hi:[1,1,1]
	v_pk_fma_f32 v[42:43], v[226:227], v[208:209], v[42:43] op_sel:[0,1,0] op_sel_hi:[1,1,1]
	v_pk_fma_f32 v[44:45], v[228:229], v[208:209], v[44:45] op_sel:[0,1,0] op_sel_hi:[1,1,1]
	v_pk_fma_f32 v[46:47], v[230:231], v[208:209], v[46:47] op_sel:[0,1,0] op_sel_hi:[1,1,1]
	s_waitcnt vmcnt(17)
	v_cvt_pk_f32_fp8_e32 v[224:225], v200
	v_cvt_pk_f32_fp8_sdwa v[226:227], v200 src0_sel:WORD_1
	v_cvt_pk_f32_fp8_e32 v[228:229], v201
	v_cvt_pk_f32_fp8_sdwa v[230:231], v201 src0_sel:WORD_1
	v_pk_fma_f32 v[32:33], v[224:225], v[210:211], v[32:33] op_sel_hi:[1,0,1]
	v_pk_fma_f32 v[34:35], v[226:227], v[210:211], v[34:35] op_sel_hi:[1,0,1]
	v_pk_fma_f32 v[36:37], v[228:229], v[210:211], v[36:37] op_sel_hi:[1,0,1]
	v_pk_fma_f32 v[38:39], v[230:231], v[210:211], v[38:39] op_sel_hi:[1,0,1]
	v_cvt_pk_f32_fp8_e32 v[224:225], v202
	v_cvt_pk_f32_fp8_sdwa v[226:227], v202 src0_sel:WORD_1
	v_cvt_pk_f32_fp8_e32 v[228:229], v203
	v_cvt_pk_f32_fp8_sdwa v[230:231], v203 src0_sel:WORD_1
	v_pk_fma_f32 v[40:41], v[224:225], v[210:211], v[40:41] op_sel_hi:[1,0,1]
	v_pk_fma_f32 v[42:43], v[226:227], v[210:211], v[42:43] op_sel_hi:[1,0,1]
	v_pk_fma_f32 v[44:45], v[228:229], v[210:211], v[44:45] op_sel_hi:[1,0,1]
	v_pk_fma_f32 v[46:47], v[230:231], v[210:211], v[46:47] op_sel_hi:[1,0,1]
	s_waitcnt vmcnt(16)
	v_cvt_pk_f32_fp8_e32 v[224:225], v204
	v_cvt_pk_f32_fp8_sdwa v[226:227], v204 src0_sel:WORD_1
	v_cvt_pk_f32_fp8_e32 v[228:229], v205
	v_cvt_pk_f32_fp8_sdwa v[230:231], v205 src0_sel:WORD_1
	v_pk_fma_f32 v[32:33], v[224:225], v[210:211], v[32:33] op_sel:[0,1,0] op_sel_hi:[1,1,1]
	v_pk_fma_f32 v[34:35], v[226:227], v[210:211], v[34:35] op_sel:[0,1,0] op_sel_hi:[1,1,1]
	v_pk_fma_f32 v[36:37], v[228:229], v[210:211], v[36:37] op_sel:[0,1,0] op_sel_hi:[1,1,1]
	v_pk_fma_f32 v[38:39], v[230:231], v[210:211], v[38:39] op_sel:[0,1,0] op_sel_hi:[1,1,1]
	v_cvt_pk_f32_fp8_e32 v[224:225], v206
	v_cvt_pk_f32_fp8_sdwa v[226:227], v206 src0_sel:WORD_1
	v_cvt_pk_f32_fp8_e32 v[228:229], v207
	v_cvt_pk_f32_fp8_sdwa v[230:231], v207 src0_sel:WORD_1
	v_pk_fma_f32 v[40:41], v[224:225], v[210:211], v[40:41] op_sel:[0,1,0] op_sel_hi:[1,1,1]
	v_pk_fma_f32 v[42:43], v[226:227], v[210:211], v[42:43] op_sel:[0,1,0] op_sel_hi:[1,1,1]
	v_pk_fma_f32 v[44:45], v[228:229], v[210:211], v[44:45] op_sel:[0,1,0] op_sel_hi:[1,1,1]
	v_pk_fma_f32 v[46:47], v[230:231], v[210:211], v[46:47] op_sel:[0,1,0] op_sel_hi:[1,1,1]
	v_add_u32_e32 v213, 80, v213
	s_add_i32 s21, s21, 5
	s_sub_i32 s90, s90, 1
	s_cmp_eq_u32 s90, 0
	s_cbranch_scc1 .LV_sw0
	s_branch .LV_t2_s0
.LV_t3_s0:
	s_cmp_ge_u32 s21, s20
	s_cbranch_scc1 .LV_done
	s_waitcnt lgkmcnt(0)
	buffer_load_dwordx4 v[192:195], v[232:233], s[60:63], 0 idxen offen
	buffer_load_dwordx4 v[196:199], v[234:235], s[60:63], 0 idxen offen
	buffer_load_dwordx4 v[200:203], v[236:237], s[60:63], 0 idxen offen
	buffer_load_dwordx4 v[204:207], v[238:239], s[60:63], 0 idxen offen
	ds_read_b32 v232, v213 offset:80
	ds_read_b32 v234, v213 offset:84
	ds_read_b32 v236, v213 offset:88
	ds_read_b32 v238, v213 offset:92
	ds_read_b128 v[252:255], v213 offset:5008
	s_waitcnt vmcnt(19)
	v_cvt_pk_f32_fp8_e32 v[224:225], v128
	v_cvt_pk_f32_fp8_sdwa v[226:227], v128 src0_sel:WORD_1
	v_cvt_pk_f32_fp8_e32 v[228:229], v129
	v_cvt_pk_f32_fp8_sdwa v[230:231], v129 src0_sel:WORD_1
	v_pk_fma_f32 v[48:49], v[224:225], v[248:249], v[48:49] op_sel_hi:[1,0,1]
	v_pk_fma_f32 v[50:51], v[226:227], v[248:249], v[50:51] op_sel_hi:[1,0,1]
	v_pk_fma_f32 v[52:53], v[228:229], v[248:249], v[52:53] op_sel_hi:[1,0,1]
	v_pk_fma_f32 v[54:55], v[230:231], v[248:249], v[54:55] op_sel_hi:[1,0,1]
	v_cvt_pk_f32_fp8_e32 v[224:225], v130
	v_cvt_pk_f32_fp8_sdwa v[226:227], v130 src0_sel:WORD_1
	v_cvt_pk_f32_fp8_e32 v[228:229], v131
	v_cvt_pk_f32_fp8_sdwa v[230:231], v131 src0_sel:WORD_1
	v_pk_fma_f32 v[56:57], v[224:225], v[248:249], v[56:57] op_sel_hi:[1,0,1]
	v_pk_fma_f32 v[58:59], v[226:227], v[248:249], v[58:59] op_sel_hi:[1,0,1]
	v_pk_fma_f32 v[60:61], v[228:229], v[248:249], v[60:61] op_sel_hi:[1,0,1]
	v_pk_fma_f32 v[62:63], v[230:231], v[248:249], v[62:63] op_sel_hi:[1,0,1]
	s_waitcnt vmcnt(18)
	v_cvt_pk_f32_fp8_e32 v[224:225], v132
	v_cvt_pk_f32_fp8_sdwa v[226:227], v132 src0_sel:WORD_1
	v_cvt_pk_f32_fp8_e32 v[228:229], v133
	v_cvt_pk_f32_fp8_sdwa v[230:231], v133 src0_sel:WORD_1
	v_pk_fma_f32 v[48:49], v[224:225], v[248:249], v[48:49] op_sel:[0,1,0] op_sel_hi:[1,1,1]
	v_pk_fma_f32 v[50:51], v[226:227], v[248:249], v[50:51] op_sel:[0,1,0] op_sel_hi:[1,1,1]
	v_pk_fma_f32 v[52:53], v[228:229], v[248:249], v[52:53] op_sel:[0,1,0] op_sel_hi:[1,1,1]
	v_pk_fma_f32 v[54:55], v[230:231], v[248:249], v[54:55] op_sel:[0,1,0] op_sel_hi:[1,1,1]
	v_cvt_pk_f32_fp8_e32 v[224:225], v134
	v_cvt_pk_f32_fp8_sdwa v[226:227], v134 src0_sel:WORD_1
	v_cvt_pk_f32_fp8_e32 v[228:229], v135
	v_cvt_pk_f32_fp8_sdwa v[230:231], v135 src0_sel:WORD_1
	v_pk_fma_f32 v[56:57], v[224:225], v[248:249], v[56:57] op_sel:[0,1,0] op_sel_hi:[1,1,1]
	v_pk_fma_f32 v[58:59], v[226:227], v[248:249], v[58:59] op_sel:[0,1,0] op_sel_hi:[1,1,1]
	v_pk_fma_f32 v[60:61], v[228:229], v[248:249], v[60:61] op_sel:[0,1,0] op_sel_hi:[1,1,1]
	v_pk_fma_f32 v[62:63], v[230:231], v[248:249], v[62:63] op_sel:[0,1,0] op_sel_hi:[1,1,1]
	s_waitcnt vmcnt(17)
	v_cvt_pk_f32_fp8_e32 v[224:225], v136
	v_cvt_pk_f32_fp8_sdwa v[226:227], v136 src0_sel:WORD_1
	v_cvt_pk_f32_fp8_e32 v[228:229], v137
	v_cvt_pk_f32_fp8_sdwa v[230:231], v137 src0_sel:WORD_1
	v_pk_fma_f32 v[48:49], v[224:225], v[250:251], v[48:49] op_sel_hi:[1,0,1]
	v_pk_fma_f32 v[50:51], v[226:227], v[250:251], v[50:51] op_sel_hi:[1,0,1]
	v_pk_fma_f32 v[52:53], v[228:229], v[250:251], v[52:53] op_sel_hi:[1,0,1]
	v_pk_fma_f32 v[54:55], v[230:231], v[250:251], v[54:55] op_sel_hi:[1,0,1]
	v_cvt_pk_f32_fp8_e32 v[224:225], v138
	v_cvt_pk_f32_fp8_sdwa v[226:227], v138 src0_sel:WORD_1
	v_cvt_pk_f32_fp8_e32 v[228:229], v139
	v_cvt_pk_f32_fp8_sdwa v[230:231], v139 src0_sel:WORD_1
	v_pk_fma_f32 v[56:57], v[224:225], v[250:251], v[56:57] op_sel_hi:[1,0,1]
	v_pk_fma_f32 v[58:59], v[226:227], v[250:251], v[58:59] op_sel_hi:[1,0,1]
	v_pk_fma_f32 v[60:61], v[228:229], v[250:251], v[60:61] op_sel_hi:[1,0,1]
	v_pk_fma_f32 v[62:63], v[230:231], v[250:251], v[62:63] op_sel_hi:[1,0,1]
	s_waitcnt vmcnt(16)
	v_cvt_pk_f32_fp8_e32 v[224:225], v140
	v_cvt_pk_f32_fp8_sdwa v[226:227], v140 src0_sel:WORD_1
	v_cvt_pk_f32_fp8_e32 v[228:229], v141
	v_cvt_pk_f32_fp8_sdwa v[230:231], v141 src0_sel:WORD_1
	v_pk_fma_f32 v[48:49], v[224:225], v[250:251], v[48:49] op_sel:[0,1,0] op_sel_hi:[1,1,1]
	v_pk_fma_f32 v[50:51], v[226:227], v[250:251], v[50:51] op_sel:[0,1,0] op_sel_hi:[1,1,1]
	v_pk_fma_f32 v[52:53], v[228:229], v[250:251], v[52:53] op_sel:[0,1,0] op_sel_hi:[1,1,1]
	v_pk_fma_f32 v[54:55], v[230:231], v[250:251], v[54:55] op_sel:[0,1,0] op_sel_hi:[1,1,1]
	v_cvt_pk_f32_fp8_e32 v[224:225], v142
	v_cvt_pk_f32_fp8_sdwa v[226:227], v142 src0_sel:WORD_1
	v_cvt_pk_f32_fp8_e32 v[228:229], v143
	v_cvt_pk_f32_fp8_sdwa v[230:231], v143 src0_sel:WORD_1
	v_pk_fma_f32 v[56:57], v[224:225], v[250:251], v[56:57] op_sel:[0,1,0] op_sel_hi:[1,1,1]
	v_pk_fma_f32 v[58:59], v[226:227], v[250:251], v[58:59] op_sel:[0,1,0] op_sel_hi:[1,1,1]
	v_pk_fma_f32 v[60:61], v[228:229], v[250:251], v[60:61] op_sel:[0,1,0] op_sel_hi:[1,1,1]
	v_pk_fma_f32 v[62:63], v[230:231], v[250:251], v[62:63] op_sel:[0,1,0] op_sel_hi:[1,1,1]
	s_sub_i32 s90, s90, 1
	s_cmp_eq_u32 s90, 0
	s_cbranch_scc1 .LV_sw1
.LV_t3_s1:
	s_waitcnt lgkmcnt(0)
	buffer_load_dwordx4 v[128:131], v[232:233], s[60:63], 0 idxen offen
	buffer_load_dwordx4 v[132:135], v[234:235], s[60:63], 0 idxen offen
	buffer_load_dwordx4 v[136:139], v[236:237], s[60:63], 0 idxen offen
	buffer_load_dwordx4 v[140:143], v[238:239], s[60:63], 0 idxen offen
	ds_read_b32 v232, v213 offset:96
	ds_read_b32 v234, v213 offset:100
	ds_read_b32 v236, v213 offset:104
	ds_read_b32 v238, v213 offset:108
	ds_read_b128 v[248:251], v213 offset:5024
	s_waitcnt vmcnt(19)
	v_cvt_pk_f32_fp8_e32 v[224:225], v144
	v_cvt_pk_f32_fp8_sdwa v[226:227], v144 src0_sel:WORD_1
	v_cvt_pk_f32_fp8_e32 v[228:229], v145
	v_cvt_pk_f32_fp8_sdwa v[230:231], v145 src0_sel:WORD_1
	v_pk_fma_f32 v[48:49], v[224:225], v[252:253], v[48:49] op_sel_hi:[1,0,1]
	v_pk_fma_f32 v[50:51], v[226:227], v[252:253], v[50:51] op_sel_hi:[1,0,1]
	v_pk_fma_f32 v[52:53], v[228:229], v[252:253], v[52:53] op_sel_hi:[1,0,1]
	v_pk_fma_f32 v[54:55], v[230:231], v[252:253], v[54:55] op_sel_hi:[1,0,1]
	v_cvt_pk_f32_fp8_e32 v[224:225], v146
	v_cvt_pk_f32_fp8_sdwa v[226:227], v146 src0_sel:WORD_1
	v_cvt_pk_f32_fp8_e32 v[228:229], v147
	v_cvt_pk_f32_fp8_sdwa v[230:231], v147 src0_sel:WORD_1
	v_pk_fma_f32 v[56:57], v[224:225], v[252:253], v[56:57] op_sel_hi:[1,0,1]
	v_pk_fma_f32 v[58:59], v[226:227], v[252:253], v[58:59] op_sel_hi:[1,0,1]
	v_pk_fma_f32 v[60:61], v[228:229], v[252:253], v[60:61] op_sel_hi:[1,0,1]
	v_pk_fma_f32 v[62:63], v[230:231], v[252:253], v[62:63] op_sel_hi:[1,0,1]
	s_waitcnt vmcnt(18)
	v_cvt_pk_f32_fp8_e32 v[224:225], v148
	v_cvt_pk_f32_fp8_sdwa v[226:227], v148 src0_sel:WORD_1
	v_cvt_pk_f32_fp8_e32 v[228:229], v149
	v_cvt_pk_f32_fp8_sdwa v[230:231], v149 src0_sel:WORD_1
	v_pk_fma_f32 v[48:49], v[224:225], v[252:253], v[48:49] op_sel:[0,1,0] op_sel_hi:[1,1,1]
	v_pk_fma_f32 v[50:51], v[226:227], v[252:253], v[50:51] op_sel:[0,1,0] op_sel_hi:[1,1,1]
	v_pk_fma_f32 v[52:53], v[228:229], v[252:253], v[52:53] op_sel:[0,1,0] op_sel_hi:[1,1,1]
	v_pk_fma_f32 v[54:55], v[230:231], v[252:253], v[54:55] op_sel:[0,1,0] op_sel_hi:[1,1,1]
	v_cvt_pk_f32_fp8_e32 v[224:225], v150
	v_cvt_pk_f32_fp8_sdwa v[226:227], v150 src0_sel:WORD_1
	v_cvt_pk_f32_fp8_e32 v[228:229], v151
	v_cvt_pk_f32_fp8_sdwa v[230:231], v151 src0_sel:WORD_1
	v_pk_fma_f32 v[56:57], v[224:225], v[252:253], v[56:57] op_sel:[0,1,0] op_sel_hi:[1,1,1]
	v_pk_fma_f32 v[58:59], v[226:227], v[252:253], v[58:59] op_sel:[0,1,0] op_sel_hi:[1,1,1]
	v_pk_fma_f32 v[60:61], v[228:229], v[252:253], v[60:61] op_sel:[0,1,0] op_sel_hi:[1,1,1]
	v_pk_fma_f32 v[62:63], v[230:231], v[252:253], v[62:63] op_sel:[0,1,0] op_sel_hi:[1,1,1]
	s_waitcnt vmcnt(17)
	v_cvt_pk_f32_fp8_e32 v[224:225], v152
	v_cvt_pk_f32_fp8_sdwa v[226:227], v152 src0_sel:WORD_1
	v_cvt_pk_f32_fp8_e32 v[228:229], v153
	v_cvt_pk_f32_fp8_sdwa v[230:231], v153 src0_sel:WORD_1
	v_pk_fma_f32 v[48:49], v[224:225], v[254:255], v[48:49] op_sel_hi:[1,0,1]
	v_pk_fma_f32 v[50:51], v[226:227], v[254:255], v[50:51] op_sel_hi:[1,0,1]
	v_pk_fma_f32 v[52:53], v[228:229], v[254:255], v[52:53] op_sel_hi:[1,0,1]
	v_pk_fma_f32 v[54:55], v[230:231], v[254:255], v[54:55] op_sel_hi:[1,0,1]
	v_cvt_pk_f32_fp8_e32 v[224:225], v154
	v_cvt_pk_f32_fp8_sdwa v[226:227], v154 src0_sel:WORD_1
	v_cvt_pk_f32_fp8_e32 v[228:229], v155
	v_cvt_pk_f32_fp8_sdwa v[230:231], v155 src0_sel:WORD_1
	v_pk_fma_f32 v[56:57], v[224:225], v[254:255], v[56:57] op_sel_hi:[1,0,1]
	v_pk_fma_f32 v[58:59], v[226:227], v[254:255], v[58:59] op_sel_hi:[1,0,1]
	v_pk_fma_f32 v[60:61], v[228:229], v[254:255], v[60:61] op_sel_hi:[1,0,1]
	v_pk_fma_f32 v[62:63], v[230:231], v[254:255], v[62:63] op_sel_hi:[1,0,1]
	s_waitcnt vmcnt(16)
	v_cvt_pk_f32_fp8_e32 v[224:225], v156
	v_cvt_pk_f32_fp8_sdwa v[226:227], v156 src0_sel:WORD_1
	v_cvt_pk_f32_fp8_e32 v[228:229], v157
	v_cvt_pk_f32_fp8_sdwa v[230:231], v157 src0_sel:WORD_1
	v_pk_fma_f32 v[48:49], v[224:225], v[254:255], v[48:49] op_sel:[0,1,0] op_sel_hi:[1,1,1]
	v_pk_fma_f32 v[50:51], v[226:227], v[254:255], v[50:51] op_sel:[0,1,0] op_sel_hi:[1,1,1]
	v_pk_fma_f32 v[52:53], v[228:229], v[254:255], v[52:53] op_sel:[0,1,0] op_sel_hi:[1,1,1]
	v_pk_fma_f32 v[54:55], v[230:231], v[254:255], v[54:55] op_sel:[0,1,0] op_sel_hi:[1,1,1]
	v_cvt_pk_f32_fp8_e32 v[224:225], v158
	v_cvt_pk_f32_fp8_sdwa v[226:227], v158 src0_sel:WORD_1
	v_cvt_pk_f32_fp8_e32 v[228:229], v159
	v_cvt_pk_f32_fp8_sdwa v[230:231], v159 src0_sel:WORD_1
	v_pk_fma_f32 v[56:57], v[224:225], v[254:255], v[56:57] op_sel:[0,1,0] op_sel_hi:[1,1,1]
	v_pk_fma_f32 v[58:59], v[226:227], v[254:255], v[58:59] op_sel:[0,1,0] op_sel_hi:[1,1,1]
	v_pk_fma_f32 v[60:61], v[228:229], v[254:255], v[60:61] op_sel:[0,1,0] op_sel_hi:[1,1,1]
	v_pk_fma_f32 v[62:63], v[230:231], v[254:255], v[62:63] op_sel:[0,1,0] op_sel_hi:[1,1,1]
	s_sub_i32 s90, s90, 1
	s_cmp_eq_u32 s90, 0
	s_cbranch_scc1 .LV_sw2
.LV_t3_s2:
	s_waitcnt lgkmcnt(0)
	buffer_load_dwordx4 v[144:147], v[232:233], s[60:63], 0 idxen offen
	buffer_load_dwordx4 v[148:151], v[234:235], s[60:63], 0 idxen offen
	buffer_load_dwordx4 v[152:155], v[236:237], s[60:63], 0 idxen offen
	buffer_load_dwordx4 v[156:159], v[238:239], s[60:63], 0 idxen offen
	ds_read_b32 v232, v213 offset:112
	ds_read_b32 v234, v213 offset:116
	ds_read_b32 v236, v213 offset:120
	ds_read_b32 v238, v213 offset:124
	ds_read_b128 v[252:255], v213 offset:5040
	s_waitcnt vmcnt(19)
	v_cvt_pk_f32_fp8_e32 v[224:225], v160
	v_cvt_pk_f32_fp8_sdwa v[226:227], v160 src0_sel:WORD_1
	v_cvt_pk_f32_fp8_e32 v[228:229], v161
	v_cvt_pk_f32_fp8_sdwa v[230:231], v161 src0_sel:WORD_1
	v_pk_fma_f32 v[48:49], v[224:225], v[248:249], v[48:49] op_sel_hi:[1,0,1]
	v_pk_fma_f32 v[50:51], v[226:227], v[248:249], v[50:51] op_sel_hi:[1,0,1]
	v_pk_fma_f32 v[52:53], v[228:229], v[248:249], v[52:53] op_sel_hi:[1,0,1]
	v_pk_fma_f32 v[54:55], v[230:231], v[248:249], v[54:55] op_sel_hi:[1,0,1]
	v_cvt_pk_f32_fp8_e32 v[224:225], v162
	v_cvt_pk_f32_fp8_sdwa v[226:227], v162 src0_sel:WORD_1
	v_cvt_pk_f32_fp8_e32 v[228:229], v163
	v_cvt_pk_f32_fp8_sdwa v[230:231], v163 src0_sel:WORD_1
	v_pk_fma_f32 v[56:57], v[224:225], v[248:249], v[56:57] op_sel_hi:[1,0,1]
	v_pk_fma_f32 v[58:59], v[226:227], v[248:249], v[58:59] op_sel_hi:[1,0,1]
	v_pk_fma_f32 v[60:61], v[228:229], v[248:249], v[60:61] op_sel_hi:[1,0,1]
	v_pk_fma_f32 v[62:63], v[230:231], v[248:249], v[62:63] op_sel_hi:[1,0,1]
	s_waitcnt vmcnt(18)
	v_cvt_pk_f32_fp8_e32 v[224:225], v164
	v_cvt_pk_f32_fp8_sdwa v[226:227], v164 src0_sel:WORD_1
	v_cvt_pk_f32_fp8_e32 v[228:229], v165
	v_cvt_pk_f32_fp8_sdwa v[230:231], v165 src0_sel:WORD_1
	v_pk_fma_f32 v[48:49], v[224:225], v[248:249], v[48:49] op_sel:[0,1,0] op_sel_hi:[1,1,1]
	v_pk_fma_f32 v[50:51], v[226:227], v[248:249], v[50:51] op_sel:[0,1,0] op_sel_hi:[1,1,1]
	v_pk_fma_f32 v[52:53], v[228:229], v[248:249], v[52:53] op_sel:[0,1,0] op_sel_hi:[1,1,1]
	v_pk_fma_f32 v[54:55], v[230:231], v[248:249], v[54:55] op_sel:[0,1,0] op_sel_hi:[1,1,1]
	v_cvt_pk_f32_fp8_e32 v[224:225], v166
	v_cvt_pk_f32_fp8_sdwa v[226:227], v166 src0_sel:WORD_1
	v_cvt_pk_f32_fp8_e32 v[228:229], v167
	v_cvt_pk_f32_fp8_sdwa v[230:231], v167 src0_sel:WORD_1
	v_pk_fma_f32 v[56:57], v[224:225], v[248:249], v[56:57] op_sel:[0,1,0] op_sel_hi:[1,1,1]
	v_pk_fma_f32 v[58:59], v[226:227], v[248:249], v[58:59] op_sel:[0,1,0] op_sel_hi:[1,1,1]
	v_pk_fma_f32 v[60:61], v[228:229], v[248:249], v[60:61] op_sel:[0,1,0] op_sel_hi:[1,1,1]
	v_pk_fma_f32 v[62:63], v[230:231], v[248:249], v[62:63] op_sel:[0,1,0] op_sel_hi:[1,1,1]
	s_waitcnt vmcnt(17)
	v_cvt_pk_f32_fp8_e32 v[224:225], v168
	v_cvt_pk_f32_fp8_sdwa v[226:227], v168 src0_sel:WORD_1
	v_cvt_pk_f32_fp8_e32 v[228:229], v169
	v_cvt_pk_f32_fp8_sdwa v[230:231], v169 src0_sel:WORD_1
	v_pk_fma_f32 v[48:49], v[224:225], v[250:251], v[48:49] op_sel_hi:[1,0,1]
	v_pk_fma_f32 v[50:51], v[226:227], v[250:251], v[50:51] op_sel_hi:[1,0,1]
	v_pk_fma_f32 v[52:53], v[228:229], v[250:251], v[52:53] op_sel_hi:[1,0,1]
	v_pk_fma_f32 v[54:55], v[230:231], v[250:251], v[54:55] op_sel_hi:[1,0,1]
	v_cvt_pk_f32_fp8_e32 v[224:225], v170
	v_cvt_pk_f32_fp8_sdwa v[226:227], v170 src0_sel:WORD_1
	v_cvt_pk_f32_fp8_e32 v[228:229], v171
	v_cvt_pk_f32_fp8_sdwa v[230:231], v171 src0_sel:WORD_1
	v_pk_fma_f32 v[56:57], v[224:225], v[250:251], v[56:57] op_sel_hi:[1,0,1]
	v_pk_fma_f32 v[58:59], v[226:227], v[250:251], v[58:59] op_sel_hi:[1,0,1]
	v_pk_fma_f32 v[60:61], v[228:229], v[250:251], v[60:61] op_sel_hi:[1,0,1]
	v_pk_fma_f32 v[62:63], v[230:231], v[250:251], v[62:63] op_sel_hi:[1,0,1]
	s_waitcnt vmcnt(16)
	v_cvt_pk_f32_fp8_e32 v[224:225], v172
	v_cvt_pk_f32_fp8_sdwa v[226:227], v172 src0_sel:WORD_1
	v_cvt_pk_f32_fp8_e32 v[228:229], v173
	v_cvt_pk_f32_fp8_sdwa v[230:231], v173 src0_sel:WORD_1
	v_pk_fma_f32 v[48:49], v[224:225], v[250:251], v[48:49] op_sel:[0,1,0] op_sel_hi:[1,1,1]
	v_pk_fma_f32 v[50:51], v[226:227], v[250:251], v[50:51] op_sel:[0,1,0] op_sel_hi:[1,1,1]
	v_pk_fma_f32 v[52:53], v[228:229], v[250:251], v[52:53] op_sel:[0,1,0] op_sel_hi:[1,1,1]
	v_pk_fma_f32 v[54:55], v[230:231], v[250:251], v[54:55] op_sel:[0,1,0] op_sel_hi:[1,1,1]
	v_cvt_pk_f32_fp8_e32 v[224:225], v174
	v_cvt_pk_f32_fp8_sdwa v[226:227], v174 src0_sel:WORD_1
	v_cvt_pk_f32_fp8_e32 v[228:229], v175
	v_cvt_pk_f32_fp8_sdwa v[230:231], v175 src0_sel:WORD_1
	v_pk_fma_f32 v[56:57], v[224:225], v[250:251], v[56:57] op_sel:[0,1,0] op_sel_hi:[1,1,1]
	v_pk_fma_f32 v[58:59], v[226:227], v[250:251], v[58:59] op_sel:[0,1,0] op_sel_hi:[1,1,1]
	v_pk_fma_f32 v[60:61], v[228:229], v[250:251], v[60:61] op_sel:[0,1,0] op_sel_hi:[1,1,1]
	v_pk_fma_f32 v[62:63], v[230:231], v[250:251], v[62:63] op_sel:[0,1,0] op_sel_hi:[1,1,1]
	s_sub_i32 s90, s90, 1
	s_cmp_eq_u32 s90, 0
	s_cbranch_scc1 .LV_sw3
.LV_t3_s3:
	s_waitcnt lgkmcnt(0)
	buffer_load_dwordx4 v[160:163], v[232:233], s[60:63], 0 idxen offen
	buffer_load_dwordx4 v[164:167], v[234:235], s[60:63], 0 idxen offen
	buffer_load_dwordx4 v[168:171], v[236:237], s[60:63], 0 idxen offen
	buffer_load_dwordx4 v[172:175], v[238:239], s[60:63], 0 idxen offen
	ds_read_b32 v232, v213 offset:128
	ds_read_b32 v234, v213 offset:132
	ds_read_b32 v236, v213 offset:136
	ds_read_b32 v238, v213 offset:140
	ds_read_b128 v[208:211], v213 offset:5056
	s_waitcnt vmcnt(19)
	v_cvt_pk_f32_fp8_e32 v[224:225], v176
	v_cvt_pk_f32_fp8_sdwa v[226:227], v176 src0_sel:WORD_1
	v_cvt_pk_f32_fp8_e32 v[228:229], v177
	v_cvt_pk_f32_fp8_sdwa v[230:231], v177 src0_sel:WORD_1
	v_pk_fma_f32 v[48:49], v[224:225], v[252:253], v[48:49] op_sel_hi:[1,0,1]
	v_pk_fma_f32 v[50:51], v[226:227], v[252:253], v[50:51] op_sel_hi:[1,0,1]
	v_pk_fma_f32 v[52:53], v[228:229], v[252:253], v[52:53] op_sel_hi:[1,0,1]
	v_pk_fma_f32 v[54:55], v[230:231], v[252:253], v[54:55] op_sel_hi:[1,0,1]
	v_cvt_pk_f32_fp8_e32 v[224:225], v178
	v_cvt_pk_f32_fp8_sdwa v[226:227], v178 src0_sel:WORD_1
	v_cvt_pk_f32_fp8_e32 v[228:229], v179
	v_cvt_pk_f32_fp8_sdwa v[230:231], v179 src0_sel:WORD_1
	v_pk_fma_f32 v[56:57], v[224:225], v[252:253], v[56:57] op_sel_hi:[1,0,1]
	v_pk_fma_f32 v[58:59], v[226:227], v[252:253], v[58:59] op_sel_hi:[1,0,1]
	v_pk_fma_f32 v[60:61], v[228:229], v[252:253], v[60:61] op_sel_hi:[1,0,1]
	v_pk_fma_f32 v[62:63], v[230:231], v[252:253], v[62:63] op_sel_hi:[1,0,1]
	s_waitcnt vmcnt(18)
	v_cvt_pk_f32_fp8_e32 v[224:225], v180
	v_cvt_pk_f32_fp8_sdwa v[226:227], v180 src0_sel:WORD_1
	v_cvt_pk_f32_fp8_e32 v[228:229], v181
	v_cvt_pk_f32_fp8_sdwa v[230:231], v181 src0_sel:WORD_1
	v_pk_fma_f32 v[48:49], v[224:225], v[252:253], v[48:49] op_sel:[0,1,0] op_sel_hi:[1,1,1]
	v_pk_fma_f32 v[50:51], v[226:227], v[252:253], v[50:51] op_sel:[0,1,0] op_sel_hi:[1,1,1]
	v_pk_fma_f32 v[52:53], v[228:229], v[252:253], v[52:53] op_sel:[0,1,0] op_sel_hi:[1,1,1]
	v_pk_fma_f32 v[54:55], v[230:231], v[252:253], v[54:55] op_sel:[0,1,0] op_sel_hi:[1,1,1]
	v_cvt_pk_f32_fp8_e32 v[224:225], v182
	v_cvt_pk_f32_fp8_sdwa v[226:227], v182 src0_sel:WORD_1
	v_cvt_pk_f32_fp8_e32 v[228:229], v183
	v_cvt_pk_f32_fp8_sdwa v[230:231], v183 src0_sel:WORD_1
	v_pk_fma_f32 v[56:57], v[224:225], v[252:253], v[56:57] op_sel:[0,1,0] op_sel_hi:[1,1,1]
	v_pk_fma_f32 v[58:59], v[226:227], v[252:253], v[58:59] op_sel:[0,1,0] op_sel_hi:[1,1,1]
	v_pk_fma_f32 v[60:61], v[228:229], v[252:253], v[60:61] op_sel:[0,1,0] op_sel_hi:[1,1,1]
	v_pk_fma_f32 v[62:63], v[230:231], v[252:253], v[62:63] op_sel:[0,1,0] op_sel_hi:[1,1,1]
	s_waitcnt vmcnt(17)
	v_cvt_pk_f32_fp8_e32 v[224:225], v184
	v_cvt_pk_f32_fp8_sdwa v[226:227], v184 src0_sel:WORD_1
	v_cvt_pk_f32_fp8_e32 v[228:229], v185
	v_cvt_pk_f32_fp8_sdwa v[230:231], v185 src0_sel:WORD_1
	v_pk_fma_f32 v[48:49], v[224:225], v[254:255], v[48:49] op_sel_hi:[1,0,1]
	v_pk_fma_f32 v[50:51], v[226:227], v[254:255], v[50:51] op_sel_hi:[1,0,1]
	v_pk_fma_f32 v[52:53], v[228:229], v[254:255], v[52:53] op_sel_hi:[1,0,1]
	v_pk_fma_f32 v[54:55], v[230:231], v[254:255], v[54:55] op_sel_hi:[1,0,1]
	v_cvt_pk_f32_fp8_e32 v[224:225], v186
	v_cvt_pk_f32_fp8_sdwa v[226:227], v186 src0_sel:WORD_1
	v_cvt_pk_f32_fp8_e32 v[228:229], v187
	v_cvt_pk_f32_fp8_sdwa v[230:231], v187 src0_sel:WORD_1
	v_pk_fma_f32 v[56:57], v[224:225], v[254:255], v[56:57] op_sel_hi:[1,0,1]
	v_pk_fma_f32 v[58:59], v[226:227], v[254:255], v[58:59] op_sel_hi:[1,0,1]
	v_pk_fma_f32 v[60:61], v[228:229], v[254:255], v[60:61] op_sel_hi:[1,0,1]
	v_pk_fma_f32 v[62:63], v[230:231], v[254:255], v[62:63] op_sel_hi:[1,0,1]
	s_waitcnt vmcnt(16)
	v_cvt_pk_f32_fp8_e32 v[224:225], v188
	v_cvt_pk_f32_fp8_sdwa v[226:227], v188 src0_sel:WORD_1
	v_cvt_pk_f32_fp8_e32 v[228:229], v189
	v_cvt_pk_f32_fp8_sdwa v[230:231], v189 src0_sel:WORD_1
	v_pk_fma_f32 v[48:49], v[224:225], v[254:255], v[48:49] op_sel:[0,1,0] op_sel_hi:[1,1,1]
	v_pk_fma_f32 v[50:51], v[226:227], v[254:255], v[50:51] op_sel:[0,1,0] op_sel_hi:[1,1,1]
	v_pk_fma_f32 v[52:53], v[228:229], v[254:255], v[52:53] op_sel:[0,1,0] op_sel_hi:[1,1,1]
	v_pk_fma_f32 v[54:55], v[230:231], v[254:255], v[54:55] op_sel:[0,1,0] op_sel_hi:[1,1,1]
	v_cvt_pk_f32_fp8_e32 v[224:225], v190
	v_cvt_pk_f32_fp8_sdwa v[226:227], v190 src0_sel:WORD_1
	v_cvt_pk_f32_fp8_e32 v[228:229], v191
	v_cvt_pk_f32_fp8_sdwa v[230:231], v191 src0_sel:WORD_1
	v_pk_fma_f32 v[56:57], v[224:225], v[254:255], v[56:57] op_sel:[0,1,0] op_sel_hi:[1,1,1]
	v_pk_fma_f32 v[58:59], v[226:227], v[254:255], v[58:59] op_sel:[0,1,0] op_sel_hi:[1,1,1]
	v_pk_fma_f32 v[60:61], v[228:229], v[254:255], v[60:61] op_sel:[0,1,0] op_sel_hi:[1,1,1]
	v_pk_fma_f32 v[62:63], v[230:231], v[254:255], v[62:63] op_sel:[0,1,0] op_sel_hi:[1,1,1]
	s_sub_i32 s90, s90, 1
	s_cmp_eq_u32 s90, 0
	s_cbranch_scc1 .LV_sw4
.LV_t3_s4:
	s_waitcnt lgkmcnt(0)
	buffer_load_dwordx4 v[176:179], v[232:233], s[60:63], 0 idxen offen
	buffer_load_dwordx4 v[180:183], v[234:235], s[60:63], 0 idxen offen
	buffer_load_dwordx4 v[184:187], v[236:237], s[60:63], 0 idxen offen
	buffer_load_dwordx4 v[188:191], v[238:239], s[60:63], 0 idxen offen
	ds_read_b32 v232, v213 offset:144
	ds_read_b32 v234, v213 offset:148
	ds_read_b32 v236, v213 offset:152
	ds_read_b32 v238, v213 offset:156
	ds_read_b128 v[248:251], v213 offset:5072
	s_waitcnt vmcnt(19)
	v_cvt_pk_f32_fp8_e32 v[224:225], v192
	v_cvt_pk_f32_fp8_sdwa v[226:227], v192 src0_sel:WORD_1
	v_cvt_pk_f32_fp8_e32 v[228:229], v193
	v_cvt_pk_f32_fp8_sdwa v[230:231], v193 src0_sel:WORD_1
	v_pk_fma_f32 v[48:49], v[224:225], v[208:209], v[48:49] op_sel_hi:[1,0,1]
	v_pk_fma_f32 v[50:51], v[226:227], v[208:209], v[50:51] op_sel_hi:[1,0,1]
	v_pk_fma_f32 v[52:53], v[228:229], v[208:209], v[52:53] op_sel_hi:[1,0,1]
	v_pk_fma_f32 v[54:55], v[230:231], v[208:209], v[54:55] op_sel_hi:[1,0,1]
	v_cvt_pk_f32_fp8_e32 v[224:225], v194
	v_cvt_pk_f32_fp8_sdwa v[226:227], v194 src0_sel:WORD_1
	v_cvt_pk_f32_fp8_e32 v[228:229], v195
	v_cvt_pk_f32_fp8_sdwa v[230:231], v195 src0_sel:WORD_1
	v_pk_fma_f32 v[56:57], v[224:225], v[208:209], v[56:57] op_sel_hi:[1,0,1]
	v_pk_fma_f32 v[58:59], v[226:227], v[208:209], v[58:59] op_sel_hi:[1,0,1]
	v_pk_fma_f32 v[60:61], v[228:229], v[208:209], v[60:61] op_sel_hi:[1,0,1]
	v_pk_fma_f32 v[62:63], v[230:231], v[208:209], v[62:63] op_sel_hi:[1,0,1]
	s_waitcnt vmcnt(18)
	v_cvt_pk_f32_fp8_e32 v[224:225], v196
	v_cvt_pk_f32_fp8_sdwa v[226:227], v196 src0_sel:WORD_1
	v_cvt_pk_f32_fp8_e32 v[228:229], v197
	v_cvt_pk_f32_fp8_sdwa v[230:231], v197 src0_sel:WORD_1
	v_pk_fma_f32 v[48:49], v[224:225], v[208:209], v[48:49] op_sel:[0,1,0] op_sel_hi:[1,1,1]
	v_pk_fma_f32 v[50:51], v[226:227], v[208:209], v[50:51] op_sel:[0,1,0] op_sel_hi:[1,1,1]
	v_pk_fma_f32 v[52:53], v[228:229], v[208:209], v[52:53] op_sel:[0,1,0] op_sel_hi:[1,1,1]
	v_pk_fma_f32 v[54:55], v[230:231], v[208:209], v[54:55] op_sel:[0,1,0] op_sel_hi:[1,1,1]
	v_cvt_pk_f32_fp8_e32 v[224:225], v198
	v_cvt_pk_f32_fp8_sdwa v[226:227], v198 src0_sel:WORD_1
	v_cvt_pk_f32_fp8_e32 v[228:229], v199
	v_cvt_pk_f32_fp8_sdwa v[230:231], v199 src0_sel:WORD_1
	v_pk_fma_f32 v[56:57], v[224:225], v[208:209], v[56:57] op_sel:[0,1,0] op_sel_hi:[1,1,1]
	v_pk_fma_f32 v[58:59], v[226:227], v[208:209], v[58:59] op_sel:[0,1,0] op_sel_hi:[1,1,1]
	v_pk_fma_f32 v[60:61], v[228:229], v[208:209], v[60:61] op_sel:[0,1,0] op_sel_hi:[1,1,1]
	v_pk_fma_f32 v[62:63], v[230:231], v[208:209], v[62:63] op_sel:[0,1,0] op_sel_hi:[1,1,1]
	s_waitcnt vmcnt(17)
	v_cvt_pk_f32_fp8_e32 v[224:225], v200
	v_cvt_pk_f32_fp8_sdwa v[226:227], v200 src0_sel:WORD_1
	v_cvt_pk_f32_fp8_e32 v[228:229], v201
	v_cvt_pk_f32_fp8_sdwa v[230:231], v201 src0_sel:WORD_1
	v_pk_fma_f32 v[48:49], v[224:225], v[210:211], v[48:49] op_sel_hi:[1,0,1]
	v_pk_fma_f32 v[50:51], v[226:227], v[210:211], v[50:51] op_sel_hi:[1,0,1]
	v_pk_fma_f32 v[52:53], v[228:229], v[210:211], v[52:53] op_sel_hi:[1,0,1]
	v_pk_fma_f32 v[54:55], v[230:231], v[210:211], v[54:55] op_sel_hi:[1,0,1]
	v_cvt_pk_f32_fp8_e32 v[224:225], v202
	v_cvt_pk_f32_fp8_sdwa v[226:227], v202 src0_sel:WORD_1
	v_cvt_pk_f32_fp8_e32 v[228:229], v203
	v_cvt_pk_f32_fp8_sdwa v[230:231], v203 src0_sel:WORD_1
	v_pk_fma_f32 v[56:57], v[224:225], v[210:211], v[56:57] op_sel_hi:[1,0,1]
	v_pk_fma_f32 v[58:59], v[226:227], v[210:211], v[58:59] op_sel_hi:[1,0,1]
	v_pk_fma_f32 v[60:61], v[228:229], v[210:211], v[60:61] op_sel_hi:[1,0,1]
	v_pk_fma_f32 v[62:63], v[230:231], v[210:211], v[62:63] op_sel_hi:[1,0,1]
	s_waitcnt vmcnt(16)
	v_cvt_pk_f32_fp8_e32 v[224:225], v204
	v_cvt_pk_f32_fp8_sdwa v[226:227], v204 src0_sel:WORD_1
	v_cvt_pk_f32_fp8_e32 v[228:229], v205
	v_cvt_pk_f32_fp8_sdwa v[230:231], v205 src0_sel:WORD_1
	v_pk_fma_f32 v[48:49], v[224:225], v[210:211], v[48:49] op_sel:[0,1,0] op_sel_hi:[1,1,1]
	v_pk_fma_f32 v[50:51], v[226:227], v[210:211], v[50:51] op_sel:[0,1,0] op_sel_hi:[1,1,1]
	v_pk_fma_f32 v[52:53], v[228:229], v[210:211], v[52:53] op_sel:[0,1,0] op_sel_hi:[1,1,1]
	v_pk_fma_f32 v[54:55], v[230:231], v[210:211], v[54:55] op_sel:[0,1,0] op_sel_hi:[1,1,1]
	v_cvt_pk_f32_fp8_e32 v[224:225], v206
	v_cvt_pk_f32_fp8_sdwa v[226:227], v206 src0_sel:WORD_1
	v_cvt_pk_f32_fp8_e32 v[228:229], v207
	v_cvt_pk_f32_fp8_sdwa v[230:231], v207 src0_sel:WORD_1
	v_pk_fma_f32 v[56:57], v[224:225], v[210:211], v[56:57] op_sel:[0,1,0] op_sel_hi:[1,1,1]
	v_pk_fma_f32 v[58:59], v[226:227], v[210:211], v[58:59] op_sel:[0,1,0] op_sel_hi:[1,1,1]
	v_pk_fma_f32 v[60:61], v[228:229], v[210:211], v[60:61] op_sel:[0,1,0] op_sel_hi:[1,1,1]
	v_pk_fma_f32 v[62:63], v[230:231], v[210:211], v[62:63] op_sel:[0,1,0] op_sel_hi:[1,1,1]
	v_add_u32_e32 v213, 80, v213
	s_add_i32 s21, s21, 5
	s_sub_i32 s90, s90, 1
	s_cmp_eq_u32 s90, 0
	s_cbranch_scc1 .LV_sw0
	s_branch .LV_t3_s0
; #define IT_ADVANCE() do { it_j += 4; while (it_j >= it_end) { if (it_done) break; ++it_tk; if (it_tk == 4) { it_tk = 0; ++it_p; if (it_p == 16) { it_done = true; it_p = 15; it_j = 0; it_end = 1; break; } } \
;             it_j = __builtin_amdgcn_readfirstlane(OFFS[(tb + it_tk) * 17 + it_p]); it_end = __builtin_amdgcn_readfirstlane(OFFS[(tb + it_tk) * 17 + it_p + 1]); } } while (0)
; __device__ __forceinline__ void peer_tile(const Args& A, LAS unsigned char* lds, int tile) {
;     ...
;                 for (int j0 = beg; j0 < end; j0 += 8) {
;                     IT_ADVANCE();
.LV_t4_s0:
	s_cmp_ge_u32 s21, s20
	s_cbranch_scc1 .LV_done
	s_waitcnt lgkmcnt(0)
	buffer_load_dwordx4 v[192:195], v[232:233], s[60:63], 0 idxen offen
	buffer_load_dwordx4 v[196:199], v[234:235], s[60:63], 0 idxen offen
	buffer_load_dwordx4 v[200:203], v[236:237], s[60:63], 0 idxen offen
	buffer_load_dwordx4 v[204:207], v[238:239], s[60:63], 0 idxen offen
	ds_read_b32 v232, v213 offset:80
	ds_read_b32 v234, v213 offset:84
	ds_read_b32 v236, v213 offset:88
	ds_read_b32 v238, v213 offset:92
	ds_read_b128 v[252:255], v213 offset:5008
	s_waitcnt vmcnt(19)
	v_cvt_pk_f32_fp8_e32 v[224:225], v128
	v_cvt_pk_f32_fp8_sdwa v[226:227], v128 src0_sel:WORD_1
	v_cvt_pk_f32_fp8_e32 v[228:229], v129
	v_cvt_pk_f32_fp8_sdwa v[230:231], v129 src0_sel:WORD_1
	v_pk_fma_f32 v[64:65], v[224:225], v[248:249], v[64:65] op_sel_hi:[1,0,1]
	v_pk_fma_f32 v[66:67], v[226:227], v[248:249], v[66:67] op_sel_hi:[1,0,1]
	v_pk_fma_f32 v[68:69], v[228:229], v[248:249], v[68:69] op_sel_hi:[1,0,1]
	v_pk_fma_f32 v[70:71], v[230:231], v[248:249], v[70:71] op_sel_hi:[1,0,1]
	v_cvt_pk_f32_fp8_e32 v[224:225], v130
	v_cvt_pk_f32_fp8_sdwa v[226:227], v130 src0_sel:WORD_1
	v_cvt_pk_f32_fp8_e32 v[228:229], v131
	v_cvt_pk_f32_fp8_sdwa v[230:231], v131 src0_sel:WORD_1
	v_pk_fma_f32 v[72:73], v[224:225], v[248:249], v[72:73] op_sel_hi:[1,0,1]
	v_pk_fma_f32 v[74:75], v[226:227], v[248:249], v[74:75] op_sel_hi:[1,0,1]
	v_pk_fma_f32 v[76:77], v[228:229], v[248:249], v[76:77] op_sel_hi:[1,0,1]
	v_pk_fma_f32 v[78:79], v[230:231], v[248:249], v[78:79] op_sel_hi:[1,0,1]
	s_waitcnt vmcnt(18)
	v_cvt_pk_f32_fp8_e32 v[224:225], v132
	v_cvt_pk_f32_fp8_sdwa v[226:227], v132 src0_sel:WORD_1
	v_cvt_pk_f32_fp8_e32 v[228:229], v133
	v_cvt_pk_f32_fp8_sdwa v[230:231], v133 src0_sel:WORD_1
	v_pk_fma_f32 v[64:65], v[224:225], v[248:249], v[64:65] op_sel:[0,1,0] op_sel_hi:[1,1,1]
	v_pk_fma_f32 v[66:67], v[226:227], v[248:249], v[66:67] op_sel:[0,1,0] op_sel_hi:[1,1,1]
	v_pk_fma_f32 v[68:69], v[228:229], v[248:249], v[68:69] op_sel:[0,1,0] op_sel_hi:[1,1,1]
	v_pk_fma_f32 v[70:71], v[230:231], v[248:249], v[70:71] op_sel:[0,1,0] op_sel_hi:[1,1,1]
	v_cvt_pk_f32_fp8_e32 v[224:225], v134
	v_cvt_pk_f32_fp8_sdwa v[226:227], v134 src0_sel:WORD_1
	v_cvt_pk_f32_fp8_e32 v[228:229], v135
	v_cvt_pk_f32_fp8_sdwa v[230:231], v135 src0_sel:WORD_1
	v_pk_fma_f32 v[72:73], v[224:225], v[248:249], v[72:73] op_sel:[0,1,0] op_sel_hi:[1,1,1]
	v_pk_fma_f32 v[74:75], v[226:227], v[248:249], v[74:75] op_sel:[0,1,0] op_sel_hi:[1,1,1]
	v_pk_fma_f32 v[76:77], v[228:229], v[248:249], v[76:77] op_sel:[0,1,0] op_sel_hi:[1,1,1]
	v_pk_fma_f32 v[78:79], v[230:231], v[248:249], v[78:79] op_sel:[0,1,0] op_sel_hi:[1,1,1]
	s_waitcnt vmcnt(17)
	v_cvt_pk_f32_fp8_e32 v[224:225], v136
	v_cvt_pk_f32_fp8_sdwa v[226:227], v136 src0_sel:WORD_1
	v_cvt_pk_f32_fp8_e32 v[228:229], v137
	v_cvt_pk_f32_fp8_sdwa v[230:231], v137 src0_sel:WORD_1
	v_pk_fma_f32 v[64:65], v[224:225], v[250:251], v[64:65] op_sel_hi:[1,0,1]
	v_pk_fma_f32 v[66:67], v[226:227], v[250:251], v[66:67] op_sel_hi:[1,0,1]
	v_pk_fma_f32 v[68:69], v[228:229], v[250:251], v[68:69] op_sel_hi:[1,0,1]
	v_pk_fma_f32 v[70:71], v[230:231], v[250:251], v[70:71] op_sel_hi:[1,0,1]
	v_cvt_pk_f32_fp8_e32 v[224:225], v138
	v_cvt_pk_f32_fp8_sdwa v[226:227], v138 src0_sel:WORD_1
	v_cvt_pk_f32_fp8_e32 v[228:229], v139
	v_cvt_pk_f32_fp8_sdwa v[230:231], v139 src0_sel:WORD_1
	v_pk_fma_f32 v[72:73], v[224:225], v[250:251], v[72:73] op_sel_hi:[1,0,1]
	v_pk_fma_f32 v[74:75], v[226:227], v[250:251], v[74:75] op_sel_hi:[1,0,1]
	v_pk_fma_f32 v[76:77], v[228:229], v[250:251], v[76:77] op_sel_hi:[1,0,1]
	v_pk_fma_f32 v[78:79], v[230:231], v[250:251], v[78:79] op_sel_hi:[1,0,1]
	s_waitcnt vmcnt(16)
	v_cvt_pk_f32_fp8_e32 v[224:225], v140
	v_cvt_pk_f32_fp8_sdwa v[226:227], v140 src0_sel:WORD_1
	v_cvt_pk_f32_fp8_e32 v[228:229], v141
	v_cvt_pk_f32_fp8_sdwa v[230:231], v141 src0_sel:WORD_1
	v_pk_fma_f32 v[64:65], v[224:225], v[250:251], v[64:65] op_sel:[0,1,0] op_sel_hi:[1,1,1]
	v_pk_fma_f32 v[66:67], v[226:227], v[250:251], v[66:67] op_sel:[0,1,0] op_sel_hi:[1,1,1]
	v_pk_fma_f32 v[68:69], v[228:229], v[250:251], v[68:69] op_sel:[0,1,0] op_sel_hi:[1,1,1]
	v_pk_fma_f32 v[70:71], v[230:231], v[250:251], v[70:71] op_sel:[0,1,0] op_sel_hi:[1,1,1]
	v_cvt_pk_f32_fp8_e32 v[224:225], v142
	v_cvt_pk_f32_fp8_sdwa v[226:227], v142 src0_sel:WORD_1
	v_cvt_pk_f32_fp8_e32 v[228:229], v143
	v_cvt_pk_f32_fp8_sdwa v[230:231], v143 src0_sel:WORD_1
	v_pk_fma_f32 v[72:73], v[224:225], v[250:251], v[72:73] op_sel:[0,1,0] op_sel_hi:[1,1,1]
	v_pk_fma_f32 v[74:75], v[226:227], v[250:251], v[74:75] op_sel:[0,1,0] op_sel_hi:[1,1,1]
	v_pk_fma_f32 v[76:77], v[228:229], v[250:251], v[76:77] op_sel:[0,1,0] op_sel_hi:[1,1,1]
	v_pk_fma_f32 v[78:79], v[230:231], v[250:251], v[78:79] op_sel:[0,1,0] op_sel_hi:[1,1,1]
	s_sub_i32 s90, s90, 1
	s_cmp_eq_u32 s90, 0
	s_cbranch_scc1 .LV_sw1
.LV_t4_s1:
	s_waitcnt lgkmcnt(0)
	buffer_load_dwordx4 v[128:131], v[232:233], s[60:63], 0 idxen offen
	buffer_load_dwordx4 v[132:135], v[234:235], s[60:63], 0 idxen offen
	buffer_load_dwordx4 v[136:139], v[236:237], s[60:63], 0 idxen offen
	buffer_load_dwordx4 v[140:143], v[238:239], s[60:63], 0 idxen offen
	ds_read_b32 v232, v213 offset:96
	ds_read_b32 v234, v213 offset:100
	ds_read_b32 v236, v213 offset:104
	ds_read_b32 v238, v213 offset:108
	ds_read_b128 v[248:251], v213 offset:5024
	s_waitcnt vmcnt(19)
	v_cvt_pk_f32_fp8_e32 v[224:225], v144
	v_cvt_pk_f32_fp8_sdwa v[226:227], v144 src0_sel:WORD_1
	v_cvt_pk_f32_fp8_e32 v[228:229], v145
	v_cvt_pk_f32_fp8_sdwa v[230:231], v145 src0_sel:WORD_1
	v_pk_fma_f32 v[64:65], v[224:225], v[252:253], v[64:65] op_sel_hi:[1,0,1]
	v_pk_fma_f32 v[66:67], v[226:227], v[252:253], v[66:67] op_sel_hi:[1,0,1]
	v_pk_fma_f32 v[68:69], v[228:229], v[252:253], v[68:69] op_sel_hi:[1,0,1]
	v_pk_fma_f32 v[70:71], v[230:231], v[252:253], v[70:71] op_sel_hi:[1,0,1]
	v_cvt_pk_f32_fp8_e32 v[224:225], v146
	v_cvt_pk_f32_fp8_sdwa v[226:227], v146 src0_sel:WORD_1
	v_cvt_pk_f32_fp8_e32 v[228:229], v147
	v_cvt_pk_f32_fp8_sdwa v[230:231], v147 src0_sel:WORD_1
	v_pk_fma_f32 v[72:73], v[224:225], v[252:253], v[72:73] op_sel_hi:[1,0,1]
	v_pk_fma_f32 v[74:75], v[226:227], v[252:253], v[74:75] op_sel_hi:[1,0,1]
	v_pk_fma_f32 v[76:77], v[228:229], v[252:253], v[76:77] op_sel_hi:[1,0,1]
	v_pk_fma_f32 v[78:79], v[230:231], v[252:253], v[78:79] op_sel_hi:[1,0,1]
	s_waitcnt vmcnt(18)
	v_cvt_pk_f32_fp8_e32 v[224:225], v148
	v_cvt_pk_f32_fp8_sdwa v[226:227], v148 src0_sel:WORD_1
	v_cvt_pk_f32_fp8_e32 v[228:229], v149
	v_cvt_pk_f32_fp8_sdwa v[230:231], v149 src0_sel:WORD_1
	v_pk_fma_f32 v[64:65], v[224:225], v[252:253], v[64:65] op_sel:[0,1,0] op_sel_hi:[1,1,1]
	v_pk_fma_f32 v[66:67], v[226:227], v[252:253], v[66:67] op_sel:[0,1,0] op_sel_hi:[1,1,1]
	v_pk_fma_f32 v[68:69], v[228:229], v[252:253], v[68:69] op_sel:[0,1,0] op_sel_hi:[1,1,1]
	v_pk_fma_f32 v[70:71], v[230:231], v[252:253], v[70:71] op_sel:[0,1,0] op_sel_hi:[1,1,1]
	v_cvt_pk_f32_fp8_e32 v[224:225], v150
	v_cvt_pk_f32_fp8_sdwa v[226:227], v150 src0_sel:WORD_1
	v_cvt_pk_f32_fp8_e32 v[228:229], v151
	v_cvt_pk_f32_fp8_sdwa v[230:231], v151 src0_sel:WORD_1
	v_pk_fma_f32 v[72:73], v[224:225], v[252:253], v[72:73] op_sel:[0,1,0] op_sel_hi:[1,1,1]
	v_pk_fma_f32 v[74:75], v[226:227], v[252:253], v[74:75] op_sel:[0,1,0] op_sel_hi:[1,1,1]
	v_pk_fma_f32 v[76:77], v[228:229], v[252:253], v[76:77] op_sel:[0,1,0] op_sel_hi:[1,1,1]
	v_pk_fma_f32 v[78:79], v[230:231], v[252:253], v[78:79] op_sel:[0,1,0] op_sel_hi:[1,1,1]
	s_waitcnt vmcnt(17)
	v_cvt_pk_f32_fp8_e32 v[224:225], v152
	v_cvt_pk_f32_fp8_sdwa v[226:227], v152 src0_sel:WORD_1
	v_cvt_pk_f32_fp8_e32 v[228:229], v153
	v_cvt_pk_f32_fp8_sdwa v[230:231], v153 src0_sel:WORD_1
	v_pk_fma_f32 v[64:65], v[224:225], v[254:255], v[64:65] op_sel_hi:[1,0,1]
	v_pk_fma_f32 v[66:67], v[226:227], v[254:255], v[66:67] op_sel_hi:[1,0,1]
	v_pk_fma_f32 v[68:69], v[228:229], v[254:255], v[68:69] op_sel_hi:[1,0,1]
	v_pk_fma_f32 v[70:71], v[230:231], v[254:255], v[70:71] op_sel_hi:[1,0,1]
	v_cvt_pk_f32_fp8_e32 v[224:225], v154
	v_cvt_pk_f32_fp8_sdwa v[226:227], v154 src0_sel:WORD_1
	v_cvt_pk_f32_fp8_e32 v[228:229], v155
	v_cvt_pk_f32_fp8_sdwa v[230:231], v155 src0_sel:WORD_1
	v_pk_fma_f32 v[72:73], v[224:225], v[254:255], v[72:73] op_sel_hi:[1,0,1]
	v_pk_fma_f32 v[74:75], v[226:227], v[254:255], v[74:75] op_sel_hi:[1,0,1]
	v_pk_fma_f32 v[76:77], v[228:229], v[254:255], v[76:77] op_sel_hi:[1,0,1]
	v_pk_fma_f32 v[78:79], v[230:231], v[254:255], v[78:79] op_sel_hi:[1,0,1]
	s_waitcnt vmcnt(16)
	v_cvt_pk_f32_fp8_e32 v[224:225], v156
	v_cvt_pk_f32_fp8_sdwa v[226:227], v156 src0_sel:WORD_1
	v_cvt_pk_f32_fp8_e32 v[228:229], v157
	v_cvt_pk_f32_fp8_sdwa v[230:231], v157 src0_sel:WORD_1
	v_pk_fma_f32 v[64:65], v[224:225], v[254:255], v[64:65] op_sel:[0,1,0] op_sel_hi:[1,1,1]
	v_pk_fma_f32 v[66:67], v[226:227], v[254:255], v[66:67] op_sel:[0,1,0] op_sel_hi:[1,1,1]
	v_pk_fma_f32 v[68:69], v[228:229], v[254:255], v[68:69] op_sel:[0,1,0] op_sel_hi:[1,1,1]
	v_pk_fma_f32 v[70:71], v[230:231], v[254:255], v[70:71] op_sel:[0,1,0] op_sel_hi:[1,1,1]
	v_cvt_pk_f32_fp8_e32 v[224:225], v158
	v_cvt_pk_f32_fp8_sdwa v[226:227], v158 src0_sel:WORD_1
	v_cvt_pk_f32_fp8_e32 v[228:229], v159
	v_cvt_pk_f32_fp8_sdwa v[230:231], v159 src0_sel:WORD_1
	v_pk_fma_f32 v[72:73], v[224:225], v[254:255], v[72:73] op_sel:[0,1,0] op_sel_hi:[1,1,1]
	v_pk_fma_f32 v[74:75], v[226:227], v[254:255], v[74:75] op_sel:[0,1,0] op_sel_hi:[1,1,1]
	v_pk_fma_f32 v[76:77], v[228:229], v[254:255], v[76:77] op_sel:[0,1,0] op_sel_hi:[1,1,1]
	v_pk_fma_f32 v[78:79], v[230:231], v[254:255], v[78:79] op_sel:[0,1,0] op_sel_hi:[1,1,1]
	s_sub_i32 s90, s90, 1
	s_cmp_eq_u32 s90, 0
	s_cbranch_scc1 .LV_sw2
.LV_t4_s2:
	s_waitcnt lgkmcnt(0)
	buffer_load_dwordx4 v[144:147], v[232:233], s[60:63], 0 idxen offen
	buffer_load_dwordx4 v[148:151], v[234:235], s[60:63], 0 idxen offen
	buffer_load_dwordx4 v[152:155], v[236:237], s[60:63], 0 idxen offen
	buffer_load_dwordx4 v[156:159], v[238:239], s[60:63], 0 idxen offen
	ds_read_b32 v232, v213 offset:112
	ds_read_b32 v234, v213 offset:116
	ds_read_b32 v236, v213 offset:120
	ds_read_b32 v238, v213 offset:124
	ds_read_b128 v[252:255], v213 offset:5040
	s_waitcnt vmcnt(19)
	v_cvt_pk_f32_fp8_e32 v[224:225], v160
	v_cvt_pk_f32_fp8_sdwa v[226:227], v160 src0_sel:WORD_1
	v_cvt_pk_f32_fp8_e32 v[228:229], v161
	v_cvt_pk_f32_fp8_sdwa v[230:231], v161 src0_sel:WORD_1
	v_pk_fma_f32 v[64:65], v[224:225], v[248:249], v[64:65] op_sel_hi:[1,0,1]
	v_pk_fma_f32 v[66:67], v[226:227], v[248:249], v[66:67] op_sel_hi:[1,0,1]
	v_pk_fma_f32 v[68:69], v[228:229], v[248:249], v[68:69] op_sel_hi:[1,0,1]
	v_pk_fma_f32 v[70:71], v[230:231], v[248:249], v[70:71] op_sel_hi:[1,0,1]
	v_cvt_pk_f32_fp8_e32 v[224:225], v162
	v_cvt_pk_f32_fp8_sdwa v[226:227], v162 src0_sel:WORD_1
	v_cvt_pk_f32_fp8_e32 v[228:229], v163
	v_cvt_pk_f32_fp8_sdwa v[230:231], v163 src0_sel:WORD_1
	v_pk_fma_f32 v[72:73], v[224:225], v[248:249], v[72:73] op_sel_hi:[1,0,1]
	v_pk_fma_f32 v[74:75], v[226:227], v[248:249], v[74:75] op_sel_hi:[1,0,1]
	v_pk_fma_f32 v[76:77], v[228:229], v[248:249], v[76:77] op_sel_hi:[1,0,1]
	v_pk_fma_f32 v[78:79], v[230:231], v[248:249], v[78:79] op_sel_hi:[1,0,1]
	s_waitcnt vmcnt(18)
	v_cvt_pk_f32_fp8_e32 v[224:225], v164
	v_cvt_pk_f32_fp8_sdwa v[226:227], v164 src0_sel:WORD_1
	v_cvt_pk_f32_fp8_e32 v[228:229], v165
	v_cvt_pk_f32_fp8_sdwa v[230:231], v165 src0_sel:WORD_1
	v_pk_fma_f32 v[64:65], v[224:225], v[248:249], v[64:65] op_sel:[0,1,0] op_sel_hi:[1,1,1]
	v_pk_fma_f32 v[66:67], v[226:227], v[248:249], v[66:67] op_sel:[0,1,0] op_sel_hi:[1,1,1]
	v_pk_fma_f32 v[68:69], v[228:229], v[248:249], v[68:69] op_sel:[0,1,0] op_sel_hi:[1,1,1]
	v_pk_fma_f32 v[70:71], v[230:231], v[248:249], v[70:71] op_sel:[0,1,0] op_sel_hi:[1,1,1]
	v_cvt_pk_f32_fp8_e32 v[224:225], v166
	v_cvt_pk_f32_fp8_sdwa v[226:227], v166 src0_sel:WORD_1
	v_cvt_pk_f32_fp8_e32 v[228:229], v167
	v_cvt_pk_f32_fp8_sdwa v[230:231], v167 src0_sel:WORD_1
	v_pk_fma_f32 v[72:73], v[224:225], v[248:249], v[72:73] op_sel:[0,1,0] op_sel_hi:[1,1,1]
	v_pk_fma_f32 v[74:75], v[226:227], v[248:249], v[74:75] op_sel:[0,1,0] op_sel_hi:[1,1,1]
	v_pk_fma_f32 v[76:77], v[228:229], v[248:249], v[76:77] op_sel:[0,1,0] op_sel_hi:[1,1,1]
	v_pk_fma_f32 v[78:79], v[230:231], v[248:249], v[78:79] op_sel:[0,1,0] op_sel_hi:[1,1,1]
	s_waitcnt vmcnt(17)
	v_cvt_pk_f32_fp8_e32 v[224:225], v168
	v_cvt_pk_f32_fp8_sdwa v[226:227], v168 src0_sel:WORD_1
	v_cvt_pk_f32_fp8_e32 v[228:229], v169
	v_cvt_pk_f32_fp8_sdwa v[230:231], v169 src0_sel:WORD_1
	v_pk_fma_f32 v[64:65], v[224:225], v[250:251], v[64:65] op_sel_hi:[1,0,1]
	v_pk_fma_f32 v[66:67], v[226:227], v[250:251], v[66:67] op_sel_hi:[1,0,1]
	v_pk_fma_f32 v[68:69], v[228:229], v[250:251], v[68:69] op_sel_hi:[1,0,1]
	v_pk_fma_f32 v[70:71], v[230:231], v[250:251], v[70:71] op_sel_hi:[1,0,1]
	v_cvt_pk_f32_fp8_e32 v[224:225], v170
	v_cvt_pk_f32_fp8_sdwa v[226:227], v170 src0_sel:WORD_1
	v_cvt_pk_f32_fp8_e32 v[228:229], v171
	v_cvt_pk_f32_fp8_sdwa v[230:231], v171 src0_sel:WORD_1
	v_pk_fma_f32 v[72:73], v[224:225], v[250:251], v[72:73] op_sel_hi:[1,0,1]
	v_pk_fma_f32 v[74:75], v[226:227], v[250:251], v[74:75] op_sel_hi:[1,0,1]
	v_pk_fma_f32 v[76:77], v[228:229], v[250:251], v[76:77] op_sel_hi:[1,0,1]
	v_pk_fma_f32 v[78:79], v[230:231], v[250:251], v[78:79] op_sel_hi:[1,0,1]
	s_waitcnt vmcnt(16)
	v_cvt_pk_f32_fp8_e32 v[224:225], v172
	v_cvt_pk_f32_fp8_sdwa v[226:227], v172 src0_sel:WORD_1
	v_cvt_pk_f32_fp8_e32 v[228:229], v173
	v_cvt_pk_f32_fp8_sdwa v[230:231], v173 src0_sel:WORD_1
	v_pk_fma_f32 v[64:65], v[224:225], v[250:251], v[64:65] op_sel:[0,1,0] op_sel_hi:[1,1,1]
	v_pk_fma_f32 v[66:67], v[226:227], v[250:251], v[66:67] op_sel:[0,1,0] op_sel_hi:[1,1,1]
	v_pk_fma_f32 v[68:69], v[228:229], v[250:251], v[68:69] op_sel:[0,1,0] op_sel_hi:[1,1,1]
	v_pk_fma_f32 v[70:71], v[230:231], v[250:251], v[70:71] op_sel:[0,1,0] op_sel_hi:[1,1,1]
	v_cvt_pk_f32_fp8_e32 v[224:225], v174
	v_cvt_pk_f32_fp8_sdwa v[226:227], v174 src0_sel:WORD_1
	v_cvt_pk_f32_fp8_e32 v[228:229], v175
	v_cvt_pk_f32_fp8_sdwa v[230:231], v175 src0_sel:WORD_1
	v_pk_fma_f32 v[72:73], v[224:225], v[250:251], v[72:73] op_sel:[0,1,0] op_sel_hi:[1,1,1]
	v_pk_fma_f32 v[74:75], v[226:227], v[250:251], v[74:75] op_sel:[0,1,0] op_sel_hi:[1,1,1]
	v_pk_fma_f32 v[76:77], v[228:229], v[250:251], v[76:77] op_sel:[0,1,0] op_sel_hi:[1,1,1]
	v_pk_fma_f32 v[78:79], v[230:231], v[250:251], v[78:79] op_sel:[0,1,0] op_sel_hi:[1,1,1]
	s_sub_i32 s90, s90, 1
	s_cmp_eq_u32 s90, 0
	s_cbranch_scc1 .LV_sw3
.LV_t4_s3:
	s_waitcnt lgkmcnt(0)
	buffer_load_dwordx4 v[160:163], v[232:233], s[60:63], 0 idxen offen
	buffer_load_dwordx4 v[164:167], v[234:235], s[60:63], 0 idxen offen
	buffer_load_dwordx4 v[168:171], v[236:237], s[60:63], 0 idxen offen
	buffer_load_dwordx4 v[172:175], v[238:239], s[60:63], 0 idxen offen
	ds_read_b32 v232, v213 offset:128
	ds_read_b32 v234, v213 offset:132
	ds_read_b32 v236, v213 offset:136
	ds_read_b32 v238, v213 offset:140
	ds_read_b128 v[208:211], v213 offset:5056
	s_waitcnt vmcnt(19)
	v_cvt_pk_f32_fp8_e32 v[224:225], v176
	v_cvt_pk_f32_fp8_sdwa v[226:227], v176 src0_sel:WORD_1
	v_cvt_pk_f32_fp8_e32 v[228:229], v177
	v_cvt_pk_f32_fp8_sdwa v[230:231], v177 src0_sel:WORD_1
	v_pk_fma_f32 v[64:65], v[224:225], v[252:253], v[64:65] op_sel_hi:[1,0,1]
	v_pk_fma_f32 v[66:67], v[226:227], v[252:253], v[66:67] op_sel_hi:[1,0,1]
	v_pk_fma_f32 v[68:69], v[228:229], v[252:253], v[68:69] op_sel_hi:[1,0,1]
	v_pk_fma_f32 v[70:71], v[230:231], v[252:253], v[70:71] op_sel_hi:[1,0,1]
	v_cvt_pk_f32_fp8_e32 v[224:225], v178
	v_cvt_pk_f32_fp8_sdwa v[226:227], v178 src0_sel:WORD_1
	v_cvt_pk_f32_fp8_e32 v[228:229], v179
	v_cvt_pk_f32_fp8_sdwa v[230:231], v179 src0_sel:WORD_1
	v_pk_fma_f32 v[72:73], v[224:225], v[252:253], v[72:73] op_sel_hi:[1,0,1]
	v_pk_fma_f32 v[74:75], v[226:227], v[252:253], v[74:75] op_sel_hi:[1,0,1]
	v_pk_fma_f32 v[76:77], v[228:229], v[252:253], v[76:77] op_sel_hi:[1,0,1]
	v_pk_fma_f32 v[78:79], v[230:231], v[252:253], v[78:79] op_sel_hi:[1,0,1]
	s_waitcnt vmcnt(18)
	v_cvt_pk_f32_fp8_e32 v[224:225], v180
	v_cvt_pk_f32_fp8_sdwa v[226:227], v180 src0_sel:WORD_1
	v_cvt_pk_f32_fp8_e32 v[228:229], v181
	v_cvt_pk_f32_fp8_sdwa v[230:231], v181 src0_sel:WORD_1
	v_pk_fma_f32 v[64:65], v[224:225], v[252:253], v[64:65] op_sel:[0,1,0] op_sel_hi:[1,1,1]
	v_pk_fma_f32 v[66:67], v[226:227], v[252:253], v[66:67] op_sel:[0,1,0] op_sel_hi:[1,1,1]
	v_pk_fma_f32 v[68:69], v[228:229], v[252:253], v[68:69] op_sel:[0,1,0] op_sel_hi:[1,1,1]
	v_pk_fma_f32 v[70:71], v[230:231], v[252:253], v[70:71] op_sel:[0,1,0] op_sel_hi:[1,1,1]
	v_cvt_pk_f32_fp8_e32 v[224:225], v182
	v_cvt_pk_f32_fp8_sdwa v[226:227], v182 src0_sel:WORD_1
	v_cvt_pk_f32_fp8_e32 v[228:229], v183
	v_cvt_pk_f32_fp8_sdwa v[230:231], v183 src0_sel:WORD_1
	v_pk_fma_f32 v[72:73], v[224:225], v[252:253], v[72:73] op_sel:[0,1,0] op_sel_hi:[1,1,1]
	v_pk_fma_f32 v[74:75], v[226:227], v[252:253], v[74:75] op_sel:[0,1,0] op_sel_hi:[1,1,1]
	v_pk_fma_f32 v[76:77], v[228:229], v[252:253], v[76:77] op_sel:[0,1,0] op_sel_hi:[1,1,1]
	v_pk_fma_f32 v[78:79], v[230:231], v[252:253], v[78:79] op_sel:[0,1,0] op_sel_hi:[1,1,1]
	s_waitcnt vmcnt(17)
	v_cvt_pk_f32_fp8_e32 v[224:225], v184
	v_cvt_pk_f32_fp8_sdwa v[226:227], v184 src0_sel:WORD_1
	v_cvt_pk_f32_fp8_e32 v[228:229], v185
	v_cvt_pk_f32_fp8_sdwa v[230:231], v185 src0_sel:WORD_1
	v_pk_fma_f32 v[64:65], v[224:225], v[254:255], v[64:65] op_sel_hi:[1,0,1]
	v_pk_fma_f32 v[66:67], v[226:227], v[254:255], v[66:67] op_sel_hi:[1,0,1]
	v_pk_fma_f32 v[68:69], v[228:229], v[254:255], v[68:69] op_sel_hi:[1,0,1]
	v_pk_fma_f32 v[70:71], v[230:231], v[254:255], v[70:71] op_sel_hi:[1,0,1]
	v_cvt_pk_f32_fp8_e32 v[224:225], v186
	v_cvt_pk_f32_fp8_sdwa v[226:227], v186 src0_sel:WORD_1
	v_cvt_pk_f32_fp8_e32 v[228:229], v187
	v_cvt_pk_f32_fp8_sdwa v[230:231], v187 src0_sel:WORD_1
	v_pk_fma_f32 v[72:73], v[224:225], v[254:255], v[72:73] op_sel_hi:[1,0,1]
	v_pk_fma_f32 v[74:75], v[226:227], v[254:255], v[74:75] op_sel_hi:[1,0,1]
	v_pk_fma_f32 v[76:77], v[228:229], v[254:255], v[76:77] op_sel_hi:[1,0,1]
	v_pk_fma_f32 v[78:79], v[230:231], v[254:255], v[78:79] op_sel_hi:[1,0,1]
	s_waitcnt vmcnt(16)
	v_cvt_pk_f32_fp8_e32 v[224:225], v188
	v_cvt_pk_f32_fp8_sdwa v[226:227], v188 src0_sel:WORD_1
	v_cvt_pk_f32_fp8_e32 v[228:229], v189
	v_cvt_pk_f32_fp8_sdwa v[230:231], v189 src0_sel:WORD_1
	v_pk_fma_f32 v[64:65], v[224:225], v[254:255], v[64:65] op_sel:[0,1,0] op_sel_hi:[1,1,1]
	v_pk_fma_f32 v[66:67], v[226:227], v[254:255], v[66:67] op_sel:[0,1,0] op_sel_hi:[1,1,1]
	v_pk_fma_f32 v[68:69], v[228:229], v[254:255], v[68:69] op_sel:[0,1,0] op_sel_hi:[1,1,1]
	v_pk_fma_f32 v[70:71], v[230:231], v[254:255], v[70:71] op_sel:[0,1,0] op_sel_hi:[1,1,1]
	v_cvt_pk_f32_fp8_e32 v[224:225], v190
	v_cvt_pk_f32_fp8_sdwa v[226:227], v190 src0_sel:WORD_1
	v_cvt_pk_f32_fp8_e32 v[228:229], v191
	v_cvt_pk_f32_fp8_sdwa v[230:231], v191 src0_sel:WORD_1
	v_pk_fma_f32 v[72:73], v[224:225], v[254:255], v[72:73] op_sel:[0,1,0] op_sel_hi:[1,1,1]
	v_pk_fma_f32 v[74:75], v[226:227], v[254:255], v[74:75] op_sel:[0,1,0] op_sel_hi:[1,1,1]
	v_pk_fma_f32 v[76:77], v[228:229], v[254:255], v[76:77] op_sel:[0,1,0] op_sel_hi:[1,1,1]
	v_pk_fma_f32 v[78:79], v[230:231], v[254:255], v[78:79] op_sel:[0,1,0] op_sel_hi:[1,1,1]
	s_sub_i32 s90, s90, 1
	s_cmp_eq_u32 s90, 0
	s_cbranch_scc1 .LV_sw4
.LV_t4_s4:
	s_waitcnt lgkmcnt(0)
	buffer_load_dwordx4 v[176:179], v[232:233], s[60:63], 0 idxen offen
	buffer_load_dwordx4 v[180:183], v[234:235], s[60:63], 0 idxen offen
	buffer_load_dwordx4 v[184:187], v[236:237], s[60:63], 0 idxen offen
	buffer_load_dwordx4 v[188:191], v[238:239], s[60:63], 0 idxen offen
	ds_read_b32 v232, v213 offset:144
	ds_read_b32 v234, v213 offset:148
	ds_read_b32 v236, v213 offset:152
	ds_read_b32 v238, v213 offset:156
	ds_read_b128 v[248:251], v213 offset:5072
	s_waitcnt vmcnt(19)
	v_cvt_pk_f32_fp8_e32 v[224:225], v192
	v_cvt_pk_f32_fp8_sdwa v[226:227], v192 src0_sel:WORD_1
	v_cvt_pk_f32_fp8_e32 v[228:229], v193
	v_cvt_pk_f32_fp8_sdwa v[230:231], v193 src0_sel:WORD_1
	v_pk_fma_f32 v[64:65], v[224:225], v[208:209], v[64:65] op_sel_hi:[1,0,1]
	v_pk_fma_f32 v[66:67], v[226:227], v[208:209], v[66:67] op_sel_hi:[1,0,1]
	v_pk_fma_f32 v[68:69], v[228:229], v[208:209], v[68:69] op_sel_hi:[1,0,1]
	v_pk_fma_f32 v[70:71], v[230:231], v[208:209], v[70:71] op_sel_hi:[1,0,1]
	v_cvt_pk_f32_fp8_e32 v[224:225], v194
	v_cvt_pk_f32_fp8_sdwa v[226:227], v194 src0_sel:WORD_1
	v_cvt_pk_f32_fp8_e32 v[228:229], v195
	v_cvt_pk_f32_fp8_sdwa v[230:231], v195 src0_sel:WORD_1
	v_pk_fma_f32 v[72:73], v[224:225], v[208:209], v[72:73] op_sel_hi:[1,0,1]
	v_pk_fma_f32 v[74:75], v[226:227], v[208:209], v[74:75] op_sel_hi:[1,0,1]
	v_pk_fma_f32 v[76:77], v[228:229], v[208:209], v[76:77] op_sel_hi:[1,0,1]
	v_pk_fma_f32 v[78:79], v[230:231], v[208:209], v[78:79] op_sel_hi:[1,0,1]
	s_waitcnt vmcnt(18)
	v_cvt_pk_f32_fp8_e32 v[224:225], v196
	v_cvt_pk_f32_fp8_sdwa v[226:227], v196 src0_sel:WORD_1
	v_cvt_pk_f32_fp8_e32 v[228:229], v197
	v_cvt_pk_f32_fp8_sdwa v[230:231], v197 src0_sel:WORD_1
	v_pk_fma_f32 v[64:65], v[224:225], v[208:209], v[64:65] op_sel:[0,1,0] op_sel_hi:[1,1,1]
	v_pk_fma_f32 v[66:67], v[226:227], v[208:209], v[66:67] op_sel:[0,1,0] op_sel_hi:[1,1,1]
	v_pk_fma_f32 v[68:69], v[228:229], v[208:209], v[68:69] op_sel:[0,1,0] op_sel_hi:[1,1,1]
	v_pk_fma_f32 v[70:71], v[230:231], v[208:209], v[70:71] op_sel:[0,1,0] op_sel_hi:[1,1,1]
	v_cvt_pk_f32_fp8_e32 v[224:225], v198
	v_cvt_pk_f32_fp8_sdwa v[226:227], v198 src0_sel:WORD_1
	v_cvt_pk_f32_fp8_e32 v[228:229], v199
	v_cvt_pk_f32_fp8_sdwa v[230:231], v199 src0_sel:WORD_1
	v_pk_fma_f32 v[72:73], v[224:225], v[208:209], v[72:73] op_sel:[0,1,0] op_sel_hi:[1,1,1]
	v_pk_fma_f32 v[74:75], v[226:227], v[208:209], v[74:75] op_sel:[0,1,0] op_sel_hi:[1,1,1]
	v_pk_fma_f32 v[76:77], v[228:229], v[208:209], v[76:77] op_sel:[0,1,0] op_sel_hi:[1,1,1]
	v_pk_fma_f32 v[78:79], v[230:231], v[208:209], v[78:79] op_sel:[0,1,0] op_sel_hi:[1,1,1]
	s_waitcnt vmcnt(17)
	v_cvt_pk_f32_fp8_e32 v[224:225], v200
	v_cvt_pk_f32_fp8_sdwa v[226:227], v200 src0_sel:WORD_1
	v_cvt_pk_f32_fp8_e32 v[228:229], v201
	v_cvt_pk_f32_fp8_sdwa v[230:231], v201 src0_sel:WORD_1
	v_pk_fma_f32 v[64:65], v[224:225], v[210:211], v[64:65] op_sel_hi:[1,0,1]
	v_pk_fma_f32 v[66:67], v[226:227], v[210:211], v[66:67] op_sel_hi:[1,0,1]
	v_pk_fma_f32 v[68:69], v[228:229], v[210:211], v[68:69] op_sel_hi:[1,0,1]
	v_pk_fma_f32 v[70:71], v[230:231], v[210:211], v[70:71] op_sel_hi:[1,0,1]
	v_cvt_pk_f32_fp8_e32 v[224:225], v202
	v_cvt_pk_f32_fp8_sdwa v[226:227], v202 src0_sel:WORD_1
	v_cvt_pk_f32_fp8_e32 v[228:229], v203
	v_cvt_pk_f32_fp8_sdwa v[230:231], v203 src0_sel:WORD_1
	v_pk_fma_f32 v[72:73], v[224:225], v[210:211], v[72:73] op_sel_hi:[1,0,1]
	v_pk_fma_f32 v[74:75], v[226:227], v[210:211], v[74:75] op_sel_hi:[1,0,1]
	v_pk_fma_f32 v[76:77], v[228:229], v[210:211], v[76:77] op_sel_hi:[1,0,1]
	v_pk_fma_f32 v[78:79], v[230:231], v[210:211], v[78:79] op_sel_hi:[1,0,1]
	s_waitcnt vmcnt(16)
	v_cvt_pk_f32_fp8_e32 v[224:225], v204
	v_cvt_pk_f32_fp8_sdwa v[226:227], v204 src0_sel:WORD_1
	v_cvt_pk_f32_fp8_e32 v[228:229], v205
	v_cvt_pk_f32_fp8_sdwa v[230:231], v205 src0_sel:WORD_1
	v_pk_fma_f32 v[64:65], v[224:225], v[210:211], v[64:65] op_sel:[0,1,0] op_sel_hi:[1,1,1]
	v_pk_fma_f32 v[66:67], v[226:227], v[210:211], v[66:67] op_sel:[0,1,0] op_sel_hi:[1,1,1]
	v_pk_fma_f32 v[68:69], v[228:229], v[210:211], v[68:69] op_sel:[0,1,0] op_sel_hi:[1,1,1]
	v_pk_fma_f32 v[70:71], v[230:231], v[210:211], v[70:71] op_sel:[0,1,0] op_sel_hi:[1,1,1]
	v_cvt_pk_f32_fp8_e32 v[224:225], v206
	v_cvt_pk_f32_fp8_sdwa v[226:227], v206 src0_sel:WORD_1
	v_cvt_pk_f32_fp8_e32 v[228:229], v207
	v_cvt_pk_f32_fp8_sdwa v[230:231], v207 src0_sel:WORD_1
	v_pk_fma_f32 v[72:73], v[224:225], v[210:211], v[72:73] op_sel:[0,1,0] op_sel_hi:[1,1,1]
	v_pk_fma_f32 v[74:75], v[226:227], v[210:211], v[74:75] op_sel:[0,1,0] op_sel_hi:[1,1,1]
	v_pk_fma_f32 v[76:77], v[228:229], v[210:211], v[76:77] op_sel:[0,1,0] op_sel_hi:[1,1,1]
	v_pk_fma_f32 v[78:79], v[230:231], v[210:211], v[78:79] op_sel:[0,1,0] op_sel_hi:[1,1,1]
	v_add_u32_e32 v213, 80, v213
	s_add_i32 s21, s21, 5
	s_sub_i32 s90, s90, 1
	s_cmp_eq_u32 s90, 0
	s_cbranch_scc1 .LV_sw0
	s_branch .LV_t4_s0
; #define IT_ADVANCE() do { it_j += 4; while (it_j >= it_end) { if (it_done) break; ++it_tk; if (it_tk == 4) { it_tk = 0; ++it_p; if (it_p == 16) { it_done = true; it_p = 15; it_j = 0; it_end = 1; break; } } \
;             it_j = __builtin_amdgcn_readfirstlane(OFFS[(tb + it_tk) * 17 + it_p]); it_end = __builtin_amdgcn_readfirstlane(OFFS[(tb + it_tk) * 17 + it_p + 1]); } } while (0)
; __device__ __forceinline__ void peer_tile(const Args& A, LAS unsigned char* lds, int tile) {
;     ...
;                 for (int j0 = beg; j0 < end; j0 += 8) {
;                     IT_ADVANCE();
.LV_t5_s0:
	s_cmp_ge_u32 s21, s20
	s_cbranch_scc1 .LV_done
	s_waitcnt lgkmcnt(0)
	buffer_load_dwordx4 v[192:195], v[232:233], s[60:63], 0 idxen offen
	buffer_load_dwordx4 v[196:199], v[234:235], s[60:63], 0 idxen offen
	buffer_load_dwordx4 v[200:203], v[236:237], s[60:63], 0 idxen offen
	buffer_load_dwordx4 v[204:207], v[238:239], s[60:63], 0 idxen offen
	ds_read_b32 v232, v213 offset:80
	ds_read_b32 v234, v213 offset:84
	ds_read_b32 v236, v213 offset:88
	ds_read_b32 v238, v213 offset:92
	ds_read_b128 v[252:255], v213 offset:5008
	s_waitcnt vmcnt(19)
	v_cvt_pk_f32_fp8_e32 v[224:225], v128
	v_cvt_pk_f32_fp8_sdwa v[226:227], v128 src0_sel:WORD_1
	v_cvt_pk_f32_fp8_e32 v[228:229], v129
	v_cvt_pk_f32_fp8_sdwa v[230:231], v129 src0_sel:WORD_1
	v_pk_fma_f32 v[80:81], v[224:225], v[248:249], v[80:81] op_sel_hi:[1,0,1]
	v_pk_fma_f32 v[82:83], v[226:227], v[248:249], v[82:83] op_sel_hi:[1,0,1]
	v_pk_fma_f32 v[84:85], v[228:229], v[248:249], v[84:85] op_sel_hi:[1,0,1]
	v_pk_fma_f32 v[86:87], v[230:231], v[248:249], v[86:87] op_sel_hi:[1,0,1]
	v_cvt_pk_f32_fp8_e32 v[224:225], v130
	v_cvt_pk_f32_fp8_sdwa v[226:227], v130 src0_sel:WORD_1
	v_cvt_pk_f32_fp8_e32 v[228:229], v131
	v_cvt_pk_f32_fp8_sdwa v[230:231], v131 src0_sel:WORD_1
	v_pk_fma_f32 v[88:89], v[224:225], v[248:249], v[88:89] op_sel_hi:[1,0,1]
	v_pk_fma_f32 v[90:91], v[226:227], v[248:249], v[90:91] op_sel_hi:[1,0,1]
	v_pk_fma_f32 v[92:93], v[228:229], v[248:249], v[92:93] op_sel_hi:[1,0,1]
	v_pk_fma_f32 v[94:95], v[230:231], v[248:249], v[94:95] op_sel_hi:[1,0,1]
	s_waitcnt vmcnt(18)
	v_cvt_pk_f32_fp8_e32 v[224:225], v132
	v_cvt_pk_f32_fp8_sdwa v[226:227], v132 src0_sel:WORD_1
	v_cvt_pk_f32_fp8_e32 v[228:229], v133
	v_cvt_pk_f32_fp8_sdwa v[230:231], v133 src0_sel:WORD_1
	v_pk_fma_f32 v[80:81], v[224:225], v[248:249], v[80:81] op_sel:[0,1,0] op_sel_hi:[1,1,1]
	v_pk_fma_f32 v[82:83], v[226:227], v[248:249], v[82:83] op_sel:[0,1,0] op_sel_hi:[1,1,1]
	v_pk_fma_f32 v[84:85], v[228:229], v[248:249], v[84:85] op_sel:[0,1,0] op_sel_hi:[1,1,1]
	v_pk_fma_f32 v[86:87], v[230:231], v[248:249], v[86:87] op_sel:[0,1,0] op_sel_hi:[1,1,1]
	v_cvt_pk_f32_fp8_e32 v[224:225], v134
	v_cvt_pk_f32_fp8_sdwa v[226:227], v134 src0_sel:WORD_1
	v_cvt_pk_f32_fp8_e32 v[228:229], v135
	v_cvt_pk_f32_fp8_sdwa v[230:231], v135 src0_sel:WORD_1
	v_pk_fma_f32 v[88:89], v[224:225], v[248:249], v[88:89] op_sel:[0,1,0] op_sel_hi:[1,1,1]
	v_pk_fma_f32 v[90:91], v[226:227], v[248:249], v[90:91] op_sel:[0,1,0] op_sel_hi:[1,1,1]
	v_pk_fma_f32 v[92:93], v[228:229], v[248:249], v[92:93] op_sel:[0,1,0] op_sel_hi:[1,1,1]
	v_pk_fma_f32 v[94:95], v[230:231], v[248:249], v[94:95] op_sel:[0,1,0] op_sel_hi:[1,1,1]
	s_waitcnt vmcnt(17)
	v_cvt_pk_f32_fp8_e32 v[224:225], v136
	v_cvt_pk_f32_fp8_sdwa v[226:227], v136 src0_sel:WORD_1
	v_cvt_pk_f32_fp8_e32 v[228:229], v137
	v_cvt_pk_f32_fp8_sdwa v[230:231], v137 src0_sel:WORD_1
	v_pk_fma_f32 v[80:81], v[224:225], v[250:251], v[80:81] op_sel_hi:[1,0,1]
	v_pk_fma_f32 v[82:83], v[226:227], v[250:251], v[82:83] op_sel_hi:[1,0,1]
	v_pk_fma_f32 v[84:85], v[228:229], v[250:251], v[84:85] op_sel_hi:[1,0,1]
	v_pk_fma_f32 v[86:87], v[230:231], v[250:251], v[86:87] op_sel_hi:[1,0,1]
	v_cvt_pk_f32_fp8_e32 v[224:225], v138
	v_cvt_pk_f32_fp8_sdwa v[226:227], v138 src0_sel:WORD_1
	v_cvt_pk_f32_fp8_e32 v[228:229], v139
	v_cvt_pk_f32_fp8_sdwa v[230:231], v139 src0_sel:WORD_1
	v_pk_fma_f32 v[88:89], v[224:225], v[250:251], v[88:89] op_sel_hi:[1,0,1]
	v_pk_fma_f32 v[90:91], v[226:227], v[250:251], v[90:91] op_sel_hi:[1,0,1]
	v_pk_fma_f32 v[92:93], v[228:229], v[250:251], v[92:93] op_sel_hi:[1,0,1]
	v_pk_fma_f32 v[94:95], v[230:231], v[250:251], v[94:95] op_sel_hi:[1,0,1]
	s_waitcnt vmcnt(16)
	v_cvt_pk_f32_fp8_e32 v[224:225], v140
	v_cvt_pk_f32_fp8_sdwa v[226:227], v140 src0_sel:WORD_1
	v_cvt_pk_f32_fp8_e32 v[228:229], v141
	v_cvt_pk_f32_fp8_sdwa v[230:231], v141 src0_sel:WORD_1
	v_pk_fma_f32 v[80:81], v[224:225], v[250:251], v[80:81] op_sel:[0,1,0] op_sel_hi:[1,1,1]
	v_pk_fma_f32 v[82:83], v[226:227], v[250:251], v[82:83] op_sel:[0,1,0] op_sel_hi:[1,1,1]
	v_pk_fma_f32 v[84:85], v[228:229], v[250:251], v[84:85] op_sel:[0,1,0] op_sel_hi:[1,1,1]
	v_pk_fma_f32 v[86:87], v[230:231], v[250:251], v[86:87] op_sel:[0,1,0] op_sel_hi:[1,1,1]
	v_cvt_pk_f32_fp8_e32 v[224:225], v142
	v_cvt_pk_f32_fp8_sdwa v[226:227], v142 src0_sel:WORD_1
	v_cvt_pk_f32_fp8_e32 v[228:229], v143
	v_cvt_pk_f32_fp8_sdwa v[230:231], v143 src0_sel:WORD_1
	v_pk_fma_f32 v[88:89], v[224:225], v[250:251], v[88:89] op_sel:[0,1,0] op_sel_hi:[1,1,1]
	v_pk_fma_f32 v[90:91], v[226:227], v[250:251], v[90:91] op_sel:[0,1,0] op_sel_hi:[1,1,1]
	v_pk_fma_f32 v[92:93], v[228:229], v[250:251], v[92:93] op_sel:[0,1,0] op_sel_hi:[1,1,1]
	v_pk_fma_f32 v[94:95], v[230:231], v[250:251], v[94:95] op_sel:[0,1,0] op_sel_hi:[1,1,1]
	s_sub_i32 s90, s90, 1
	s_cmp_eq_u32 s90, 0
	s_cbranch_scc1 .LV_sw1
.LV_t5_s1:
	s_waitcnt lgkmcnt(0)
	buffer_load_dwordx4 v[128:131], v[232:233], s[60:63], 0 idxen offen
	buffer_load_dwordx4 v[132:135], v[234:235], s[60:63], 0 idxen offen
	buffer_load_dwordx4 v[136:139], v[236:237], s[60:63], 0 idxen offen
	buffer_load_dwordx4 v[140:143], v[238:239], s[60:63], 0 idxen offen
	ds_read_b32 v232, v213 offset:96
	ds_read_b32 v234, v213 offset:100
	ds_read_b32 v236, v213 offset:104
	ds_read_b32 v238, v213 offset:108
	ds_read_b128 v[248:251], v213 offset:5024
	s_waitcnt vmcnt(19)
	v_cvt_pk_f32_fp8_e32 v[224:225], v144
	v_cvt_pk_f32_fp8_sdwa v[226:227], v144 src0_sel:WORD_1
	v_cvt_pk_f32_fp8_e32 v[228:229], v145
	v_cvt_pk_f32_fp8_sdwa v[230:231], v145 src0_sel:WORD_1
	v_pk_fma_f32 v[80:81], v[224:225], v[252:253], v[80:81] op_sel_hi:[1,0,1]
	v_pk_fma_f32 v[82:83], v[226:227], v[252:253], v[82:83] op_sel_hi:[1,0,1]
	v_pk_fma_f32 v[84:85], v[228:229], v[252:253], v[84:85] op_sel_hi:[1,0,1]
	v_pk_fma_f32 v[86:87], v[230:231], v[252:253], v[86:87] op_sel_hi:[1,0,1]
	v_cvt_pk_f32_fp8_e32 v[224:225], v146
	v_cvt_pk_f32_fp8_sdwa v[226:227], v146 src0_sel:WORD_1
	v_cvt_pk_f32_fp8_e32 v[228:229], v147
	v_cvt_pk_f32_fp8_sdwa v[230:231], v147 src0_sel:WORD_1
	v_pk_fma_f32 v[88:89], v[224:225], v[252:253], v[88:89] op_sel_hi:[1,0,1]
	v_pk_fma_f32 v[90:91], v[226:227], v[252:253], v[90:91] op_sel_hi:[1,0,1]
	v_pk_fma_f32 v[92:93], v[228:229], v[252:253], v[92:93] op_sel_hi:[1,0,1]
	v_pk_fma_f32 v[94:95], v[230:231], v[252:253], v[94:95] op_sel_hi:[1,0,1]
	s_waitcnt vmcnt(18)
	v_cvt_pk_f32_fp8_e32 v[224:225], v148
	v_cvt_pk_f32_fp8_sdwa v[226:227], v148 src0_sel:WORD_1
	v_cvt_pk_f32_fp8_e32 v[228:229], v149
	v_cvt_pk_f32_fp8_sdwa v[230:231], v149 src0_sel:WORD_1
	v_pk_fma_f32 v[80:81], v[224:225], v[252:253], v[80:81] op_sel:[0,1,0] op_sel_hi:[1,1,1]
	v_pk_fma_f32 v[82:83], v[226:227], v[252:253], v[82:83] op_sel:[0,1,0] op_sel_hi:[1,1,1]
	v_pk_fma_f32 v[84:85], v[228:229], v[252:253], v[84:85] op_sel:[0,1,0] op_sel_hi:[1,1,1]
	v_pk_fma_f32 v[86:87], v[230:231], v[252:253], v[86:87] op_sel:[0,1,0] op_sel_hi:[1,1,1]
	v_cvt_pk_f32_fp8_e32 v[224:225], v150
	v_cvt_pk_f32_fp8_sdwa v[226:227], v150 src0_sel:WORD_1
	v_cvt_pk_f32_fp8_e32 v[228:229], v151
	v_cvt_pk_f32_fp8_sdwa v[230:231], v151 src0_sel:WORD_1
	v_pk_fma_f32 v[88:89], v[224:225], v[252:253], v[88:89] op_sel:[0,1,0] op_sel_hi:[1,1,1]
	v_pk_fma_f32 v[90:91], v[226:227], v[252:253], v[90:91] op_sel:[0,1,0] op_sel_hi:[1,1,1]
	v_pk_fma_f32 v[92:93], v[228:229], v[252:253], v[92:93] op_sel:[0,1,0] op_sel_hi:[1,1,1]
	v_pk_fma_f32 v[94:95], v[230:231], v[252:253], v[94:95] op_sel:[0,1,0] op_sel_hi:[1,1,1]
	s_waitcnt vmcnt(17)
	v_cvt_pk_f32_fp8_e32 v[224:225], v152
	v_cvt_pk_f32_fp8_sdwa v[226:227], v152 src0_sel:WORD_1
	v_cvt_pk_f32_fp8_e32 v[228:229], v153
	v_cvt_pk_f32_fp8_sdwa v[230:231], v153 src0_sel:WORD_1
	v_pk_fma_f32 v[80:81], v[224:225], v[254:255], v[80:81] op_sel_hi:[1,0,1]
	v_pk_fma_f32 v[82:83], v[226:227], v[254:255], v[82:83] op_sel_hi:[1,0,1]
	v_pk_fma_f32 v[84:85], v[228:229], v[254:255], v[84:85] op_sel_hi:[1,0,1]
	v_pk_fma_f32 v[86:87], v[230:231], v[254:255], v[86:87] op_sel_hi:[1,0,1]
	v_cvt_pk_f32_fp8_e32 v[224:225], v154
	v_cvt_pk_f32_fp8_sdwa v[226:227], v154 src0_sel:WORD_1
	v_cvt_pk_f32_fp8_e32 v[228:229], v155
	v_cvt_pk_f32_fp8_sdwa v[230:231], v155 src0_sel:WORD_1
	v_pk_fma_f32 v[88:89], v[224:225], v[254:255], v[88:89] op_sel_hi:[1,0,1]
	v_pk_fma_f32 v[90:91], v[226:227], v[254:255], v[90:91] op_sel_hi:[1,0,1]
	v_pk_fma_f32 v[92:93], v[228:229], v[254:255], v[92:93] op_sel_hi:[1,0,1]
	v_pk_fma_f32 v[94:95], v[230:231], v[254:255], v[94:95] op_sel_hi:[1,0,1]
	s_waitcnt vmcnt(16)
	v_cvt_pk_f32_fp8_e32 v[224:225], v156
	v_cvt_pk_f32_fp8_sdwa v[226:227], v156 src0_sel:WORD_1
	v_cvt_pk_f32_fp8_e32 v[228:229], v157
	v_cvt_pk_f32_fp8_sdwa v[230:231], v157 src0_sel:WORD_1
	v_pk_fma_f32 v[80:81], v[224:225], v[254:255], v[80:81] op_sel:[0,1,0] op_sel_hi:[1,1,1]
	v_pk_fma_f32 v[82:83], v[226:227], v[254:255], v[82:83] op_sel:[0,1,0] op_sel_hi:[1,1,1]
	v_pk_fma_f32 v[84:85], v[228:229], v[254:255], v[84:85] op_sel:[0,1,0] op_sel_hi:[1,1,1]
	v_pk_fma_f32 v[86:87], v[230:231], v[254:255], v[86:87] op_sel:[0,1,0] op_sel_hi:[1,1,1]
	v_cvt_pk_f32_fp8_e32 v[224:225], v158
	v_cvt_pk_f32_fp8_sdwa v[226:227], v158 src0_sel:WORD_1
	v_cvt_pk_f32_fp8_e32 v[228:229], v159
	v_cvt_pk_f32_fp8_sdwa v[230:231], v159 src0_sel:WORD_1
	v_pk_fma_f32 v[88:89], v[224:225], v[254:255], v[88:89] op_sel:[0,1,0] op_sel_hi:[1,1,1]
	v_pk_fma_f32 v[90:91], v[226:227], v[254:255], v[90:91] op_sel:[0,1,0] op_sel_hi:[1,1,1]
	v_pk_fma_f32 v[92:93], v[228:229], v[254:255], v[92:93] op_sel:[0,1,0] op_sel_hi:[1,1,1]
	v_pk_fma_f32 v[94:95], v[230:231], v[254:255], v[94:95] op_sel:[0,1,0] op_sel_hi:[1,1,1]
	s_sub_i32 s90, s90, 1
	s_cmp_eq_u32 s90, 0
	s_cbranch_scc1 .LV_sw2
.LV_t5_s2:
	s_waitcnt lgkmcnt(0)
	buffer_load_dwordx4 v[144:147], v[232:233], s[60:63], 0 idxen offen
	buffer_load_dwordx4 v[148:151], v[234:235], s[60:63], 0 idxen offen
	buffer_load_dwordx4 v[152:155], v[236:237], s[60:63], 0 idxen offen
	buffer_load_dwordx4 v[156:159], v[238:239], s[60:63], 0 idxen offen
	ds_read_b32 v232, v213 offset:112
	ds_read_b32 v234, v213 offset:116
	ds_read_b32 v236, v213 offset:120
	ds_read_b32 v238, v213 offset:124
	ds_read_b128 v[252:255], v213 offset:5040
	s_waitcnt vmcnt(19)
	v_cvt_pk_f32_fp8_e32 v[224:225], v160
	v_cvt_pk_f32_fp8_sdwa v[226:227], v160 src0_sel:WORD_1
	v_cvt_pk_f32_fp8_e32 v[228:229], v161
	v_cvt_pk_f32_fp8_sdwa v[230:231], v161 src0_sel:WORD_1
	v_pk_fma_f32 v[80:81], v[224:225], v[248:249], v[80:81] op_sel_hi:[1,0,1]
	v_pk_fma_f32 v[82:83], v[226:227], v[248:249], v[82:83] op_sel_hi:[1,0,1]
	v_pk_fma_f32 v[84:85], v[228:229], v[248:249], v[84:85] op_sel_hi:[1,0,1]
	v_pk_fma_f32 v[86:87], v[230:231], v[248:249], v[86:87] op_sel_hi:[1,0,1]
	v_cvt_pk_f32_fp8_e32 v[224:225], v162
	v_cvt_pk_f32_fp8_sdwa v[226:227], v162 src0_sel:WORD_1
	v_cvt_pk_f32_fp8_e32 v[228:229], v163
	v_cvt_pk_f32_fp8_sdwa v[230:231], v163 src0_sel:WORD_1
	v_pk_fma_f32 v[88:89], v[224:225], v[248:249], v[88:89] op_sel_hi:[1,0,1]
	v_pk_fma_f32 v[90:91], v[226:227], v[248:249], v[90:91] op_sel_hi:[1,0,1]
	v_pk_fma_f32 v[92:93], v[228:229], v[248:249], v[92:93] op_sel_hi:[1,0,1]
	v_pk_fma_f32 v[94:95], v[230:231], v[248:249], v[94:95] op_sel_hi:[1,0,1]
	s_waitcnt vmcnt(18)
	v_cvt_pk_f32_fp8_e32 v[224:225], v164
	v_cvt_pk_f32_fp8_sdwa v[226:227], v164 src0_sel:WORD_1
	v_cvt_pk_f32_fp8_e32 v[228:229], v165
	v_cvt_pk_f32_fp8_sdwa v[230:231], v165 src0_sel:WORD_1
	v_pk_fma_f32 v[80:81], v[224:225], v[248:249], v[80:81] op_sel:[0,1,0] op_sel_hi:[1,1,1]
	v_pk_fma_f32 v[82:83], v[226:227], v[248:249], v[82:83] op_sel:[0,1,0] op_sel_hi:[1,1,1]
	v_pk_fma_f32 v[84:85], v[228:229], v[248:249], v[84:85] op_sel:[0,1,0] op_sel_hi:[1,1,1]
	v_pk_fma_f32 v[86:87], v[230:231], v[248:249], v[86:87] op_sel:[0,1,0] op_sel_hi:[1,1,1]
	v_cvt_pk_f32_fp8_e32 v[224:225], v166
	v_cvt_pk_f32_fp8_sdwa v[226:227], v166 src0_sel:WORD_1
	v_cvt_pk_f32_fp8_e32 v[228:229], v167
	v_cvt_pk_f32_fp8_sdwa v[230:231], v167 src0_sel:WORD_1
	v_pk_fma_f32 v[88:89], v[224:225], v[248:249], v[88:89] op_sel:[0,1,0] op_sel_hi:[1,1,1]
	v_pk_fma_f32 v[90:91], v[226:227], v[248:249], v[90:91] op_sel:[0,1,0] op_sel_hi:[1,1,1]
	v_pk_fma_f32 v[92:93], v[228:229], v[248:249], v[92:93] op_sel:[0,1,0] op_sel_hi:[1,1,1]
	v_pk_fma_f32 v[94:95], v[230:231], v[248:249], v[94:95] op_sel:[0,1,0] op_sel_hi:[1,1,1]
	s_waitcnt vmcnt(17)
	v_cvt_pk_f32_fp8_e32 v[224:225], v168
	v_cvt_pk_f32_fp8_sdwa v[226:227], v168 src0_sel:WORD_1
	v_cvt_pk_f32_fp8_e32 v[228:229], v169
	v_cvt_pk_f32_fp8_sdwa v[230:231], v169 src0_sel:WORD_1
	v_pk_fma_f32 v[80:81], v[224:225], v[250:251], v[80:81] op_sel_hi:[1,0,1]
	v_pk_fma_f32 v[82:83], v[226:227], v[250:251], v[82:83] op_sel_hi:[1,0,1]
	v_pk_fma_f32 v[84:85], v[228:229], v[250:251], v[84:85] op_sel_hi:[1,0,1]
	v_pk_fma_f32 v[86:87], v[230:231], v[250:251], v[86:87] op_sel_hi:[1,0,1]
	v_cvt_pk_f32_fp8_e32 v[224:225], v170
	v_cvt_pk_f32_fp8_sdwa v[226:227], v170 src0_sel:WORD_1
	v_cvt_pk_f32_fp8_e32 v[228:229], v171
	v_cvt_pk_f32_fp8_sdwa v[230:231], v171 src0_sel:WORD_1
	v_pk_fma_f32 v[88:89], v[224:225], v[250:251], v[88:89] op_sel_hi:[1,0,1]
	v_pk_fma_f32 v[90:91], v[226:227], v[250:251], v[90:91] op_sel_hi:[1,0,1]
	v_pk_fma_f32 v[92:93], v[228:229], v[250:251], v[92:93] op_sel_hi:[1,0,1]
	v_pk_fma_f32 v[94:95], v[230:231], v[250:251], v[94:95] op_sel_hi:[1,0,1]
	s_waitcnt vmcnt(16)
	v_cvt_pk_f32_fp8_e32 v[224:225], v172
	v_cvt_pk_f32_fp8_sdwa v[226:227], v172 src0_sel:WORD_1
	v_cvt_pk_f32_fp8_e32 v[228:229], v173
	v_cvt_pk_f32_fp8_sdwa v[230:231], v173 src0_sel:WORD_1
	v_pk_fma_f32 v[80:81], v[224:225], v[250:251], v[80:81] op_sel:[0,1,0] op_sel_hi:[1,1,1]
	v_pk_fma_f32 v[82:83], v[226:227], v[250:251], v[82:83] op_sel:[0,1,0] op_sel_hi:[1,1,1]
	v_pk_fma_f32 v[84:85], v[228:229], v[250:251], v[84:85] op_sel:[0,1,0] op_sel_hi:[1,1,1]
	v_pk_fma_f32 v[86:87], v[230:231], v[250:251], v[86:87] op_sel:[0,1,0] op_sel_hi:[1,1,1]
	v_cvt_pk_f32_fp8_e32 v[224:225], v174
	v_cvt_pk_f32_fp8_sdwa v[226:227], v174 src0_sel:WORD_1
	v_cvt_pk_f32_fp8_e32 v[228:229], v175
	v_cvt_pk_f32_fp8_sdwa v[230:231], v175 src0_sel:WORD_1
	v_pk_fma_f32 v[88:89], v[224:225], v[250:251], v[88:89] op_sel:[0,1,0] op_sel_hi:[1,1,1]
	v_pk_fma_f32 v[90:91], v[226:227], v[250:251], v[90:91] op_sel:[0,1,0] op_sel_hi:[1,1,1]
	v_pk_fma_f32 v[92:93], v[228:229], v[250:251], v[92:93] op_sel:[0,1,0] op_sel_hi:[1,1,1]
	v_pk_fma_f32 v[94:95], v[230:231], v[250:251], v[94:95] op_sel:[0,1,0] op_sel_hi:[1,1,1]
	s_sub_i32 s90, s90, 1
	s_cmp_eq_u32 s90, 0
	s_cbranch_scc1 .LV_sw3
.LV_t5_s3:
	s_waitcnt lgkmcnt(0)
	buffer_load_dwordx4 v[160:163], v[232:233], s[60:63], 0 idxen offen
	buffer_load_dwordx4 v[164:167], v[234:235], s[60:63], 0 idxen offen
	buffer_load_dwordx4 v[168:171], v[236:237], s[60:63], 0 idxen offen
	buffer_load_dwordx4 v[172:175], v[238:239], s[60:63], 0 idxen offen
	ds_read_b32 v232, v213 offset:128
	ds_read_b32 v234, v213 offset:132
	ds_read_b32 v236, v213 offset:136
	ds_read_b32 v238, v213 offset:140
	ds_read_b128 v[208:211], v213 offset:5056
	s_waitcnt vmcnt(19)
	v_cvt_pk_f32_fp8_e32 v[224:225], v176
	v_cvt_pk_f32_fp8_sdwa v[226:227], v176 src0_sel:WORD_1
	v_cvt_pk_f32_fp8_e32 v[228:229], v177
	v_cvt_pk_f32_fp8_sdwa v[230:231], v177 src0_sel:WORD_1
	v_pk_fma_f32 v[80:81], v[224:225], v[252:253], v[80:81] op_sel_hi:[1,0,1]
	v_pk_fma_f32 v[82:83], v[226:227], v[252:253], v[82:83] op_sel_hi:[1,0,1]
	v_pk_fma_f32 v[84:85], v[228:229], v[252:253], v[84:85] op_sel_hi:[1,0,1]
	v_pk_fma_f32 v[86:87], v[230:231], v[252:253], v[86:87] op_sel_hi:[1,0,1]
	v_cvt_pk_f32_fp8_e32 v[224:225], v178
	v_cvt_pk_f32_fp8_sdwa v[226:227], v178 src0_sel:WORD_1
	v_cvt_pk_f32_fp8_e32 v[228:229], v179
	v_cvt_pk_f32_fp8_sdwa v[230:231], v179 src0_sel:WORD_1
	v_pk_fma_f32 v[88:89], v[224:225], v[252:253], v[88:89] op_sel_hi:[1,0,1]
	v_pk_fma_f32 v[90:91], v[226:227], v[252:253], v[90:91] op_sel_hi:[1,0,1]
	v_pk_fma_f32 v[92:93], v[228:229], v[252:253], v[92:93] op_sel_hi:[1,0,1]
	v_pk_fma_f32 v[94:95], v[230:231], v[252:253], v[94:95] op_sel_hi:[1,0,1]
	s_waitcnt vmcnt(18)
	v_cvt_pk_f32_fp8_e32 v[224:225], v180
	v_cvt_pk_f32_fp8_sdwa v[226:227], v180 src0_sel:WORD_1
	v_cvt_pk_f32_fp8_e32 v[228:229], v181
	v_cvt_pk_f32_fp8_sdwa v[230:231], v181 src0_sel:WORD_1
	v_pk_fma_f32 v[80:81], v[224:225], v[252:253], v[80:81] op_sel:[0,1,0] op_sel_hi:[1,1,1]
	v_pk_fma_f32 v[82:83], v[226:227], v[252:253], v[82:83] op_sel:[0,1,0] op_sel_hi:[1,1,1]
	v_pk_fma_f32 v[84:85], v[228:229], v[252:253], v[84:85] op_sel:[0,1,0] op_sel_hi:[1,1,1]
	v_pk_fma_f32 v[86:87], v[230:231], v[252:253], v[86:87] op_sel:[0,1,0] op_sel_hi:[1,1,1]
	v_cvt_pk_f32_fp8_e32 v[224:225], v182
	v_cvt_pk_f32_fp8_sdwa v[226:227], v182 src0_sel:WORD_1
	v_cvt_pk_f32_fp8_e32 v[228:229], v183
	v_cvt_pk_f32_fp8_sdwa v[230:231], v183 src0_sel:WORD_1
	v_pk_fma_f32 v[88:89], v[224:225], v[252:253], v[88:89] op_sel:[0,1,0] op_sel_hi:[1,1,1]
	v_pk_fma_f32 v[90:91], v[226:227], v[252:253], v[90:91] op_sel:[0,1,0] op_sel_hi:[1,1,1]
	v_pk_fma_f32 v[92:93], v[228:229], v[252:253], v[92:93] op_sel:[0,1,0] op_sel_hi:[1,1,1]
	v_pk_fma_f32 v[94:95], v[230:231], v[252:253], v[94:95] op_sel:[0,1,0] op_sel_hi:[1,1,1]
	s_waitcnt vmcnt(17)
	v_cvt_pk_f32_fp8_e32 v[224:225], v184
	v_cvt_pk_f32_fp8_sdwa v[226:227], v184 src0_sel:WORD_1
	v_cvt_pk_f32_fp8_e32 v[228:229], v185
	v_cvt_pk_f32_fp8_sdwa v[230:231], v185 src0_sel:WORD_1
	v_pk_fma_f32 v[80:81], v[224:225], v[254:255], v[80:81] op_sel_hi:[1,0,1]
	v_pk_fma_f32 v[82:83], v[226:227], v[254:255], v[82:83] op_sel_hi:[1,0,1]
	v_pk_fma_f32 v[84:85], v[228:229], v[254:255], v[84:85] op_sel_hi:[1,0,1]
	v_pk_fma_f32 v[86:87], v[230:231], v[254:255], v[86:87] op_sel_hi:[1,0,1]
	v_cvt_pk_f32_fp8_e32 v[224:225], v186
	v_cvt_pk_f32_fp8_sdwa v[226:227], v186 src0_sel:WORD_1
	v_cvt_pk_f32_fp8_e32 v[228:229], v187
	v_cvt_pk_f32_fp8_sdwa v[230:231], v187 src0_sel:WORD_1
	v_pk_fma_f32 v[88:89], v[224:225], v[254:255], v[88:89] op_sel_hi:[1,0,1]
	v_pk_fma_f32 v[90:91], v[226:227], v[254:255], v[90:91] op_sel_hi:[1,0,1]
	v_pk_fma_f32 v[92:93], v[228:229], v[254:255], v[92:93] op_sel_hi:[1,0,1]
	v_pk_fma_f32 v[94:95], v[230:231], v[254:255], v[94:95] op_sel_hi:[1,0,1]
	s_waitcnt vmcnt(16)
	v_cvt_pk_f32_fp8_e32 v[224:225], v188
	v_cvt_pk_f32_fp8_sdwa v[226:227], v188 src0_sel:WORD_1
	v_cvt_pk_f32_fp8_e32 v[228:229], v189
	v_cvt_pk_f32_fp8_sdwa v[230:231], v189 src0_sel:WORD_1
	v_pk_fma_f32 v[80:81], v[224:225], v[254:255], v[80:81] op_sel:[0,1,0] op_sel_hi:[1,1,1]
	v_pk_fma_f32 v[82:83], v[226:227], v[254:255], v[82:83] op_sel:[0,1,0] op_sel_hi:[1,1,1]
	v_pk_fma_f32 v[84:85], v[228:229], v[254:255], v[84:85] op_sel:[0,1,0] op_sel_hi:[1,1,1]
	v_pk_fma_f32 v[86:87], v[230:231], v[254:255], v[86:87] op_sel:[0,1,0] op_sel_hi:[1,1,1]
	v_cvt_pk_f32_fp8_e32 v[224:225], v190
	v_cvt_pk_f32_fp8_sdwa v[226:227], v190 src0_sel:WORD_1
	v_cvt_pk_f32_fp8_e32 v[228:229], v191
	v_cvt_pk_f32_fp8_sdwa v[230:231], v191 src0_sel:WORD_1
	v_pk_fma_f32 v[88:89], v[224:225], v[254:255], v[88:89] op_sel:[0,1,0] op_sel_hi:[1,1,1]
	v_pk_fma_f32 v[90:91], v[226:227], v[254:255], v[90:91] op_sel:[0,1,0] op_sel_hi:[1,1,1]
	v_pk_fma_f32 v[92:93], v[228:229], v[254:255], v[92:93] op_sel:[0,1,0] op_sel_hi:[1,1,1]
	v_pk_fma_f32 v[94:95], v[230:231], v[254:255], v[94:95] op_sel:[0,1,0] op_sel_hi:[1,1,1]
	s_sub_i32 s90, s90, 1
	s_cmp_eq_u32 s90, 0
	s_cbranch_scc1 .LV_sw4
.LV_t5_s4:
	s_waitcnt lgkmcnt(0)
	buffer_load_dwordx4 v[176:179], v[232:233], s[60:63], 0 idxen offen
	buffer_load_dwordx4 v[180:183], v[234:235], s[60:63], 0 idxen offen
	buffer_load_dwordx4 v[184:187], v[236:237], s[60:63], 0 idxen offen
	buffer_load_dwordx4 v[188:191], v[238:239], s[60:63], 0 idxen offen
	ds_read_b32 v232, v213 offset:144
	ds_read_b32 v234, v213 offset:148
	ds_read_b32 v236, v213 offset:152
	ds_read_b32 v238, v213 offset:156
	ds_read_b128 v[248:251], v213 offset:5072
	s_waitcnt vmcnt(19)
	v_cvt_pk_f32_fp8_e32 v[224:225], v192
	v_cvt_pk_f32_fp8_sdwa v[226:227], v192 src0_sel:WORD_1
	v_cvt_pk_f32_fp8_e32 v[228:229], v193
	v_cvt_pk_f32_fp8_sdwa v[230:231], v193 src0_sel:WORD_1
	v_pk_fma_f32 v[80:81], v[224:225], v[208:209], v[80:81] op_sel_hi:[1,0,1]
	v_pk_fma_f32 v[82:83], v[226:227], v[208:209], v[82:83] op_sel_hi:[1,0,1]
	v_pk_fma_f32 v[84:85], v[228:229], v[208:209], v[84:85] op_sel_hi:[1,0,1]
	v_pk_fma_f32 v[86:87], v[230:231], v[208:209], v[86:87] op_sel_hi:[1,0,1]
	v_cvt_pk_f32_fp8_e32 v[224:225], v194
	v_cvt_pk_f32_fp8_sdwa v[226:227], v194 src0_sel:WORD_1
	v_cvt_pk_f32_fp8_e32 v[228:229], v195
	v_cvt_pk_f32_fp8_sdwa v[230:231], v195 src0_sel:WORD_1
	v_pk_fma_f32 v[88:89], v[224:225], v[208:209], v[88:89] op_sel_hi:[1,0,1]
	v_pk_fma_f32 v[90:91], v[226:227], v[208:209], v[90:91] op_sel_hi:[1,0,1]
	v_pk_fma_f32 v[92:93], v[228:229], v[208:209], v[92:93] op_sel_hi:[1,0,1]
	v_pk_fma_f32 v[94:95], v[230:231], v[208:209], v[94:95] op_sel_hi:[1,0,1]
	s_waitcnt vmcnt(18)
	v_cvt_pk_f32_fp8_e32 v[224:225], v196
	v_cvt_pk_f32_fp8_sdwa v[226:227], v196 src0_sel:WORD_1
	v_cvt_pk_f32_fp8_e32 v[228:229], v197
	v_cvt_pk_f32_fp8_sdwa v[230:231], v197 src0_sel:WORD_1
	v_pk_fma_f32 v[80:81], v[224:225], v[208:209], v[80:81] op_sel:[0,1,0] op_sel_hi:[1,1,1]
	v_pk_fma_f32 v[82:83], v[226:227], v[208:209], v[82:83] op_sel:[0,1,0] op_sel_hi:[1,1,1]
	v_pk_fma_f32 v[84:85], v[228:229], v[208:209], v[84:85] op_sel:[0,1,0] op_sel_hi:[1,1,1]
	v_pk_fma_f32 v[86:87], v[230:231], v[208:209], v[86:87] op_sel:[0,1,0] op_sel_hi:[1,1,1]
	v_cvt_pk_f32_fp8_e32 v[224:225], v198
	v_cvt_pk_f32_fp8_sdwa v[226:227], v198 src0_sel:WORD_1
	v_cvt_pk_f32_fp8_e32 v[228:229], v199
	v_cvt_pk_f32_fp8_sdwa v[230:231], v199 src0_sel:WORD_1
	v_pk_fma_f32 v[88:89], v[224:225], v[208:209], v[88:89] op_sel:[0,1,0] op_sel_hi:[1,1,1]
	v_pk_fma_f32 v[90:91], v[226:227], v[208:209], v[90:91] op_sel:[0,1,0] op_sel_hi:[1,1,1]
	v_pk_fma_f32 v[92:93], v[228:229], v[208:209], v[92:93] op_sel:[0,1,0] op_sel_hi:[1,1,1]
	v_pk_fma_f32 v[94:95], v[230:231], v[208:209], v[94:95] op_sel:[0,1,0] op_sel_hi:[1,1,1]
	s_waitcnt vmcnt(17)
	v_cvt_pk_f32_fp8_e32 v[224:225], v200
	v_cvt_pk_f32_fp8_sdwa v[226:227], v200 src0_sel:WORD_1
	v_cvt_pk_f32_fp8_e32 v[228:229], v201
	v_cvt_pk_f32_fp8_sdwa v[230:231], v201 src0_sel:WORD_1
	v_pk_fma_f32 v[80:81], v[224:225], v[210:211], v[80:81] op_sel_hi:[1,0,1]
	v_pk_fma_f32 v[82:83], v[226:227], v[210:211], v[82:83] op_sel_hi:[1,0,1]
	v_pk_fma_f32 v[84:85], v[228:229], v[210:211], v[84:85] op_sel_hi:[1,0,1]
	v_pk_fma_f32 v[86:87], v[230:231], v[210:211], v[86:87] op_sel_hi:[1,0,1]
	v_cvt_pk_f32_fp8_e32 v[224:225], v202
	v_cvt_pk_f32_fp8_sdwa v[226:227], v202 src0_sel:WORD_1
	v_cvt_pk_f32_fp8_e32 v[228:229], v203
	v_cvt_pk_f32_fp8_sdwa v[230:231], v203 src0_sel:WORD_1
	v_pk_fma_f32 v[88:89], v[224:225], v[210:211], v[88:89] op_sel_hi:[1,0,1]
	v_pk_fma_f32 v[90:91], v[226:227], v[210:211], v[90:91] op_sel_hi:[1,0,1]
	v_pk_fma_f32 v[92:93], v[228:229], v[210:211], v[92:93] op_sel_hi:[1,0,1]
	v_pk_fma_f32 v[94:95], v[230:231], v[210:211], v[94:95] op_sel_hi:[1,0,1]
	s_waitcnt vmcnt(16)
	v_cvt_pk_f32_fp8_e32 v[224:225], v204
	v_cvt_pk_f32_fp8_sdwa v[226:227], v204 src0_sel:WORD_1
	v_cvt_pk_f32_fp8_e32 v[228:229], v205
	v_cvt_pk_f32_fp8_sdwa v[230:231], v205 src0_sel:WORD_1
	v_pk_fma_f32 v[80:81], v[224:225], v[210:211], v[80:81] op_sel:[0,1,0] op_sel_hi:[1,1,1]
	v_pk_fma_f32 v[82:83], v[226:227], v[210:211], v[82:83] op_sel:[0,1,0] op_sel_hi:[1,1,1]
	v_pk_fma_f32 v[84:85], v[228:229], v[210:211], v[84:85] op_sel:[0,1,0] op_sel_hi:[1,1,1]
	v_pk_fma_f32 v[86:87], v[230:231], v[210:211], v[86:87] op_sel:[0,1,0] op_sel_hi:[1,1,1]
	v_cvt_pk_f32_fp8_e32 v[224:225], v206
	v_cvt_pk_f32_fp8_sdwa v[226:227], v206 src0_sel:WORD_1
	v_cvt_pk_f32_fp8_e32 v[228:229], v207
	v_cvt_pk_f32_fp8_sdwa v[230:231], v207 src0_sel:WORD_1
	v_pk_fma_f32 v[88:89], v[224:225], v[210:211], v[88:89] op_sel:[0,1,0] op_sel_hi:[1,1,1]
	v_pk_fma_f32 v[90:91], v[226:227], v[210:211], v[90:91] op_sel:[0,1,0] op_sel_hi:[1,1,1]
	v_pk_fma_f32 v[92:93], v[228:229], v[210:211], v[92:93] op_sel:[0,1,0] op_sel_hi:[1,1,1]
	v_pk_fma_f32 v[94:95], v[230:231], v[210:211], v[94:95] op_sel:[0,1,0] op_sel_hi:[1,1,1]
	v_add_u32_e32 v213, 80, v213
	s_add_i32 s21, s21, 5
	s_sub_i32 s90, s90, 1
	s_cmp_eq_u32 s90, 0
	s_cbranch_scc1 .LV_sw0
	s_branch .LV_t5_s0
; #define IT_ADVANCE() do { it_j += 4; while (it_j >= it_end) { if (it_done) break; ++it_tk; if (it_tk == 4) { it_tk = 0; ++it_p; if (it_p == 16) { it_done = true; it_p = 15; it_j = 0; it_end = 1; break; } } \
;             it_j = __builtin_amdgcn_readfirstlane(OFFS[(tb + it_tk) * 17 + it_p]); it_end = __builtin_amdgcn_readfirstlane(OFFS[(tb + it_tk) * 17 + it_p + 1]); } } while (0)
; __device__ __forceinline__ void peer_tile(const Args& A, LAS unsigned char* lds, int tile) {
;     ...
;                 for (int j0 = beg; j0 < end; j0 += 8) {
;                     IT_ADVANCE();
.LV_t6_s0:
	s_cmp_ge_u32 s21, s20
	s_cbranch_scc1 .LV_done
	s_waitcnt lgkmcnt(0)
	buffer_load_dwordx4 v[192:195], v[232:233], s[60:63], 0 idxen offen
	buffer_load_dwordx4 v[196:199], v[234:235], s[60:63], 0 idxen offen
	buffer_load_dwordx4 v[200:203], v[236:237], s[60:63], 0 idxen offen
	buffer_load_dwordx4 v[204:207], v[238:239], s[60:63], 0 idxen offen
	ds_read_b32 v232, v213 offset:80
	ds_read_b32 v234, v213 offset:84
	ds_read_b32 v236, v213 offset:88
	ds_read_b32 v238, v213 offset:92
	ds_read_b128 v[252:255], v213 offset:5008
	s_waitcnt vmcnt(19)
	v_cvt_pk_f32_fp8_e32 v[224:225], v128
	v_cvt_pk_f32_fp8_sdwa v[226:227], v128 src0_sel:WORD_1
	v_cvt_pk_f32_fp8_e32 v[228:229], v129
	v_cvt_pk_f32_fp8_sdwa v[230:231], v129 src0_sel:WORD_1
	v_pk_fma_f32 v[96:97], v[224:225], v[248:249], v[96:97] op_sel_hi:[1,0,1]
	v_pk_fma_f32 v[98:99], v[226:227], v[248:249], v[98:99] op_sel_hi:[1,0,1]
	v_pk_fma_f32 v[100:101], v[228:229], v[248:249], v[100:101] op_sel_hi:[1,0,1]
	v_pk_fma_f32 v[102:103], v[230:231], v[248:249], v[102:103] op_sel_hi:[1,0,1]
	v_cvt_pk_f32_fp8_e32 v[224:225], v130
	v_cvt_pk_f32_fp8_sdwa v[226:227], v130 src0_sel:WORD_1
	v_cvt_pk_f32_fp8_e32 v[228:229], v131
	v_cvt_pk_f32_fp8_sdwa v[230:231], v131 src0_sel:WORD_1
	v_pk_fma_f32 v[104:105], v[224:225], v[248:249], v[104:105] op_sel_hi:[1,0,1]
	v_pk_fma_f32 v[106:107], v[226:227], v[248:249], v[106:107] op_sel_hi:[1,0,1]
	v_pk_fma_f32 v[108:109], v[228:229], v[248:249], v[108:109] op_sel_hi:[1,0,1]
	v_pk_fma_f32 v[110:111], v[230:231], v[248:249], v[110:111] op_sel_hi:[1,0,1]
	s_waitcnt vmcnt(18)
	v_cvt_pk_f32_fp8_e32 v[224:225], v132
	v_cvt_pk_f32_fp8_sdwa v[226:227], v132 src0_sel:WORD_1
	v_cvt_pk_f32_fp8_e32 v[228:229], v133
	v_cvt_pk_f32_fp8_sdwa v[230:231], v133 src0_sel:WORD_1
	v_pk_fma_f32 v[96:97], v[224:225], v[248:249], v[96:97] op_sel:[0,1,0] op_sel_hi:[1,1,1]
	v_pk_fma_f32 v[98:99], v[226:227], v[248:249], v[98:99] op_sel:[0,1,0] op_sel_hi:[1,1,1]
	v_pk_fma_f32 v[100:101], v[228:229], v[248:249], v[100:101] op_sel:[0,1,0] op_sel_hi:[1,1,1]
	v_pk_fma_f32 v[102:103], v[230:231], v[248:249], v[102:103] op_sel:[0,1,0] op_sel_hi:[1,1,1]
	v_cvt_pk_f32_fp8_e32 v[224:225], v134
	v_cvt_pk_f32_fp8_sdwa v[226:227], v134 src0_sel:WORD_1
	v_cvt_pk_f32_fp8_e32 v[228:229], v135
	v_cvt_pk_f32_fp8_sdwa v[230:231], v135 src0_sel:WORD_1
	v_pk_fma_f32 v[104:105], v[224:225], v[248:249], v[104:105] op_sel:[0,1,0] op_sel_hi:[1,1,1]
	v_pk_fma_f32 v[106:107], v[226:227], v[248:249], v[106:107] op_sel:[0,1,0] op_sel_hi:[1,1,1]
	v_pk_fma_f32 v[108:109], v[228:229], v[248:249], v[108:109] op_sel:[0,1,0] op_sel_hi:[1,1,1]
	v_pk_fma_f32 v[110:111], v[230:231], v[248:249], v[110:111] op_sel:[0,1,0] op_sel_hi:[1,1,1]
	s_waitcnt vmcnt(17)
	v_cvt_pk_f32_fp8_e32 v[224:225], v136
	v_cvt_pk_f32_fp8_sdwa v[226:227], v136 src0_sel:WORD_1
	v_cvt_pk_f32_fp8_e32 v[228:229], v137
	v_cvt_pk_f32_fp8_sdwa v[230:231], v137 src0_sel:WORD_1
	v_pk_fma_f32 v[96:97], v[224:225], v[250:251], v[96:97] op_sel_hi:[1,0,1]
	v_pk_fma_f32 v[98:99], v[226:227], v[250:251], v[98:99] op_sel_hi:[1,0,1]
	v_pk_fma_f32 v[100:101], v[228:229], v[250:251], v[100:101] op_sel_hi:[1,0,1]
	v_pk_fma_f32 v[102:103], v[230:231], v[250:251], v[102:103] op_sel_hi:[1,0,1]
	v_cvt_pk_f32_fp8_e32 v[224:225], v138
	v_cvt_pk_f32_fp8_sdwa v[226:227], v138 src0_sel:WORD_1
	v_cvt_pk_f32_fp8_e32 v[228:229], v139
	v_cvt_pk_f32_fp8_sdwa v[230:231], v139 src0_sel:WORD_1
	v_pk_fma_f32 v[104:105], v[224:225], v[250:251], v[104:105] op_sel_hi:[1,0,1]
	v_pk_fma_f32 v[106:107], v[226:227], v[250:251], v[106:107] op_sel_hi:[1,0,1]
	v_pk_fma_f32 v[108:109], v[228:229], v[250:251], v[108:109] op_sel_hi:[1,0,1]
	v_pk_fma_f32 v[110:111], v[230:231], v[250:251], v[110:111] op_sel_hi:[1,0,1]
	s_waitcnt vmcnt(16)
	v_cvt_pk_f32_fp8_e32 v[224:225], v140
	v_cvt_pk_f32_fp8_sdwa v[226:227], v140 src0_sel:WORD_1
	v_cvt_pk_f32_fp8_e32 v[228:229], v141
	v_cvt_pk_f32_fp8_sdwa v[230:231], v141 src0_sel:WORD_1
	v_pk_fma_f32 v[96:97], v[224:225], v[250:251], v[96:97] op_sel:[0,1,0] op_sel_hi:[1,1,1]
	v_pk_fma_f32 v[98:99], v[226:227], v[250:251], v[98:99] op_sel:[0,1,0] op_sel_hi:[1,1,1]
	v_pk_fma_f32 v[100:101], v[228:229], v[250:251], v[100:101] op_sel:[0,1,0] op_sel_hi:[1,1,1]
	v_pk_fma_f32 v[102:103], v[230:231], v[250:251], v[102:103] op_sel:[0,1,0] op_sel_hi:[1,1,1]
	v_cvt_pk_f32_fp8_e32 v[224:225], v142
	v_cvt_pk_f32_fp8_sdwa v[226:227], v142 src0_sel:WORD_1
	v_cvt_pk_f32_fp8_e32 v[228:229], v143
	v_cvt_pk_f32_fp8_sdwa v[230:231], v143 src0_sel:WORD_1
	v_pk_fma_f32 v[104:105], v[224:225], v[250:251], v[104:105] op_sel:[0,1,0] op_sel_hi:[1,1,1]
	v_pk_fma_f32 v[106:107], v[226:227], v[250:251], v[106:107] op_sel:[0,1,0] op_sel_hi:[1,1,1]
	v_pk_fma_f32 v[108:109], v[228:229], v[250:251], v[108:109] op_sel:[0,1,0] op_sel_hi:[1,1,1]
	v_pk_fma_f32 v[110:111], v[230:231], v[250:251], v[110:111] op_sel:[0,1,0] op_sel_hi:[1,1,1]
	s_sub_i32 s90, s90, 1
	s_cmp_eq_u32 s90, 0
	s_cbranch_scc1 .LV_sw1
.LV_t6_s1:
	s_waitcnt lgkmcnt(0)
	buffer_load_dwordx4 v[128:131], v[232:233], s[60:63], 0 idxen offen
	buffer_load_dwordx4 v[132:135], v[234:235], s[60:63], 0 idxen offen
	buffer_load_dwordx4 v[136:139], v[236:237], s[60:63], 0 idxen offen
	buffer_load_dwordx4 v[140:143], v[238:239], s[60:63], 0 idxen offen
	ds_read_b32 v232, v213 offset:96
	ds_read_b32 v234, v213 offset:100
	ds_read_b32 v236, v213 offset:104
	ds_read_b32 v238, v213 offset:108
	ds_read_b128 v[248:251], v213 offset:5024
	s_waitcnt vmcnt(19)
	v_cvt_pk_f32_fp8_e32 v[224:225], v144
	v_cvt_pk_f32_fp8_sdwa v[226:227], v144 src0_sel:WORD_1
	v_cvt_pk_f32_fp8_e32 v[228:229], v145
	v_cvt_pk_f32_fp8_sdwa v[230:231], v145 src0_sel:WORD_1
	v_pk_fma_f32 v[96:97], v[224:225], v[252:253], v[96:97] op_sel_hi:[1,0,1]
	v_pk_fma_f32 v[98:99], v[226:227], v[252:253], v[98:99] op_sel_hi:[1,0,1]
	v_pk_fma_f32 v[100:101], v[228:229], v[252:253], v[100:101] op_sel_hi:[1,0,1]
	v_pk_fma_f32 v[102:103], v[230:231], v[252:253], v[102:103] op_sel_hi:[1,0,1]
	v_cvt_pk_f32_fp8_e32 v[224:225], v146
	v_cvt_pk_f32_fp8_sdwa v[226:227], v146 src0_sel:WORD_1
	v_cvt_pk_f32_fp8_e32 v[228:229], v147
	v_cvt_pk_f32_fp8_sdwa v[230:231], v147 src0_sel:WORD_1
	v_pk_fma_f32 v[104:105], v[224:225], v[252:253], v[104:105] op_sel_hi:[1,0,1]
	v_pk_fma_f32 v[106:107], v[226:227], v[252:253], v[106:107] op_sel_hi:[1,0,1]
	v_pk_fma_f32 v[108:109], v[228:229], v[252:253], v[108:109] op_sel_hi:[1,0,1]
	v_pk_fma_f32 v[110:111], v[230:231], v[252:253], v[110:111] op_sel_hi:[1,0,1]
	s_waitcnt vmcnt(18)
	v_cvt_pk_f32_fp8_e32 v[224:225], v148
	v_cvt_pk_f32_fp8_sdwa v[226:227], v148 src0_sel:WORD_1
	v_cvt_pk_f32_fp8_e32 v[228:229], v149
	v_cvt_pk_f32_fp8_sdwa v[230:231], v149 src0_sel:WORD_1
	v_pk_fma_f32 v[96:97], v[224:225], v[252:253], v[96:97] op_sel:[0,1,0] op_sel_hi:[1,1,1]
	v_pk_fma_f32 v[98:99], v[226:227], v[252:253], v[98:99] op_sel:[0,1,0] op_sel_hi:[1,1,1]
	v_pk_fma_f32 v[100:101], v[228:229], v[252:253], v[100:101] op_sel:[0,1,0] op_sel_hi:[1,1,1]
	v_pk_fma_f32 v[102:103], v[230:231], v[252:253], v[102:103] op_sel:[0,1,0] op_sel_hi:[1,1,1]
	v_cvt_pk_f32_fp8_e32 v[224:225], v150
	v_cvt_pk_f32_fp8_sdwa v[226:227], v150 src0_sel:WORD_1
	v_cvt_pk_f32_fp8_e32 v[228:229], v151
	v_cvt_pk_f32_fp8_sdwa v[230:231], v151 src0_sel:WORD_1
	v_pk_fma_f32 v[104:105], v[224:225], v[252:253], v[104:105] op_sel:[0,1,0] op_sel_hi:[1,1,1]
	v_pk_fma_f32 v[106:107], v[226:227], v[252:253], v[106:107] op_sel:[0,1,0] op_sel_hi:[1,1,1]
	v_pk_fma_f32 v[108:109], v[228:229], v[252:253], v[108:109] op_sel:[0,1,0] op_sel_hi:[1,1,1]
	v_pk_fma_f32 v[110:111], v[230:231], v[252:253], v[110:111] op_sel:[0,1,0] op_sel_hi:[1,1,1]
	s_waitcnt vmcnt(17)
	v_cvt_pk_f32_fp8_e32 v[224:225], v152
	v_cvt_pk_f32_fp8_sdwa v[226:227], v152 src0_sel:WORD_1
	v_cvt_pk_f32_fp8_e32 v[228:229], v153
	v_cvt_pk_f32_fp8_sdwa v[230:231], v153 src0_sel:WORD_1
	v_pk_fma_f32 v[96:97], v[224:225], v[254:255], v[96:97] op_sel_hi:[1,0,1]
	v_pk_fma_f32 v[98:99], v[226:227], v[254:255], v[98:99] op_sel_hi:[1,0,1]
	v_pk_fma_f32 v[100:101], v[228:229], v[254:255], v[100:101] op_sel_hi:[1,0,1]
	v_pk_fma_f32 v[102:103], v[230:231], v[254:255], v[102:103] op_sel_hi:[1,0,1]
	v_cvt_pk_f32_fp8_e32 v[224:225], v154
	v_cvt_pk_f32_fp8_sdwa v[226:227], v154 src0_sel:WORD_1
	v_cvt_pk_f32_fp8_e32 v[228:229], v155
	v_cvt_pk_f32_fp8_sdwa v[230:231], v155 src0_sel:WORD_1
	v_pk_fma_f32 v[104:105], v[224:225], v[254:255], v[104:105] op_sel_hi:[1,0,1]
	v_pk_fma_f32 v[106:107], v[226:227], v[254:255], v[106:107] op_sel_hi:[1,0,1]
	v_pk_fma_f32 v[108:109], v[228:229], v[254:255], v[108:109] op_sel_hi:[1,0,1]
	v_pk_fma_f32 v[110:111], v[230:231], v[254:255], v[110:111] op_sel_hi:[1,0,1]
	s_waitcnt vmcnt(16)
	v_cvt_pk_f32_fp8_e32 v[224:225], v156
	v_cvt_pk_f32_fp8_sdwa v[226:227], v156 src0_sel:WORD_1
	v_cvt_pk_f32_fp8_e32 v[228:229], v157
	v_cvt_pk_f32_fp8_sdwa v[230:231], v157 src0_sel:WORD_1
	v_pk_fma_f32 v[96:97], v[224:225], v[254:255], v[96:97] op_sel:[0,1,0] op_sel_hi:[1,1,1]
	v_pk_fma_f32 v[98:99], v[226:227], v[254:255], v[98:99] op_sel:[0,1,0] op_sel_hi:[1,1,1]
	v_pk_fma_f32 v[100:101], v[228:229], v[254:255], v[100:101] op_sel:[0,1,0] op_sel_hi:[1,1,1]
	v_pk_fma_f32 v[102:103], v[230:231], v[254:255], v[102:103] op_sel:[0,1,0] op_sel_hi:[1,1,1]
	v_cvt_pk_f32_fp8_e32 v[224:225], v158
	v_cvt_pk_f32_fp8_sdwa v[226:227], v158 src0_sel:WORD_1
	v_cvt_pk_f32_fp8_e32 v[228:229], v159
	v_cvt_pk_f32_fp8_sdwa v[230:231], v159 src0_sel:WORD_1
	v_pk_fma_f32 v[104:105], v[224:225], v[254:255], v[104:105] op_sel:[0,1,0] op_sel_hi:[1,1,1]
	v_pk_fma_f32 v[106:107], v[226:227], v[254:255], v[106:107] op_sel:[0,1,0] op_sel_hi:[1,1,1]
	v_pk_fma_f32 v[108:109], v[228:229], v[254:255], v[108:109] op_sel:[0,1,0] op_sel_hi:[1,1,1]
	v_pk_fma_f32 v[110:111], v[230:231], v[254:255], v[110:111] op_sel:[0,1,0] op_sel_hi:[1,1,1]
	s_sub_i32 s90, s90, 1
	s_cmp_eq_u32 s90, 0
	s_cbranch_scc1 .LV_sw2
.LV_t6_s2:
	s_waitcnt lgkmcnt(0)
	buffer_load_dwordx4 v[144:147], v[232:233], s[60:63], 0 idxen offen
	buffer_load_dwordx4 v[148:151], v[234:235], s[60:63], 0 idxen offen
	buffer_load_dwordx4 v[152:155], v[236:237], s[60:63], 0 idxen offen
	buffer_load_dwordx4 v[156:159], v[238:239], s[60:63], 0 idxen offen
	ds_read_b32 v232, v213 offset:112
	ds_read_b32 v234, v213 offset:116
	ds_read_b32 v236, v213 offset:120
	ds_read_b32 v238, v213 offset:124
	ds_read_b128 v[252:255], v213 offset:5040
	s_waitcnt vmcnt(19)
	v_cvt_pk_f32_fp8_e32 v[224:225], v160
	v_cvt_pk_f32_fp8_sdwa v[226:227], v160 src0_sel:WORD_1
	v_cvt_pk_f32_fp8_e32 v[228:229], v161
	v_cvt_pk_f32_fp8_sdwa v[230:231], v161 src0_sel:WORD_1
	v_pk_fma_f32 v[96:97], v[224:225], v[248:249], v[96:97] op_sel_hi:[1,0,1]
	v_pk_fma_f32 v[98:99], v[226:227], v[248:249], v[98:99] op_sel_hi:[1,0,1]
	v_pk_fma_f32 v[100:101], v[228:229], v[248:249], v[100:101] op_sel_hi:[1,0,1]
	v_pk_fma_f32 v[102:103], v[230:231], v[248:249], v[102:103] op_sel_hi:[1,0,1]
	v_cvt_pk_f32_fp8_e32 v[224:225], v162
	v_cvt_pk_f32_fp8_sdwa v[226:227], v162 src0_sel:WORD_1
	v_cvt_pk_f32_fp8_e32 v[228:229], v163
	v_cvt_pk_f32_fp8_sdwa v[230:231], v163 src0_sel:WORD_1
	v_pk_fma_f32 v[104:105], v[224:225], v[248:249], v[104:105] op_sel_hi:[1,0,1]
	v_pk_fma_f32 v[106:107], v[226:227], v[248:249], v[106:107] op_sel_hi:[1,0,1]
	v_pk_fma_f32 v[108:109], v[228:229], v[248:249], v[108:109] op_sel_hi:[1,0,1]
	v_pk_fma_f32 v[110:111], v[230:231], v[248:249], v[110:111] op_sel_hi:[1,0,1]
	s_waitcnt vmcnt(18)
	v_cvt_pk_f32_fp8_e32 v[224:225], v164
	v_cvt_pk_f32_fp8_sdwa v[226:227], v164 src0_sel:WORD_1
	v_cvt_pk_f32_fp8_e32 v[228:229], v165
	v_cvt_pk_f32_fp8_sdwa v[230:231], v165 src0_sel:WORD_1
	v_pk_fma_f32 v[96:97], v[224:225], v[248:249], v[96:97] op_sel:[0,1,0] op_sel_hi:[1,1,1]
	v_pk_fma_f32 v[98:99], v[226:227], v[248:249], v[98:99] op_sel:[0,1,0] op_sel_hi:[1,1,1]
	v_pk_fma_f32 v[100:101], v[228:229], v[248:249], v[100:101] op_sel:[0,1,0] op_sel_hi:[1,1,1]
	v_pk_fma_f32 v[102:103], v[230:231], v[248:249], v[102:103] op_sel:[0,1,0] op_sel_hi:[1,1,1]
	v_cvt_pk_f32_fp8_e32 v[224:225], v166
	v_cvt_pk_f32_fp8_sdwa v[226:227], v166 src0_sel:WORD_1
	v_cvt_pk_f32_fp8_e32 v[228:229], v167
	v_cvt_pk_f32_fp8_sdwa v[230:231], v167 src0_sel:WORD_1
	v_pk_fma_f32 v[104:105], v[224:225], v[248:249], v[104:105] op_sel:[0,1,0] op_sel_hi:[1,1,1]
	v_pk_fma_f32 v[106:107], v[226:227], v[248:249], v[106:107] op_sel:[0,1,0] op_sel_hi:[1,1,1]
	v_pk_fma_f32 v[108:109], v[228:229], v[248:249], v[108:109] op_sel:[0,1,0] op_sel_hi:[1,1,1]
	v_pk_fma_f32 v[110:111], v[230:231], v[248:249], v[110:111] op_sel:[0,1,0] op_sel_hi:[1,1,1]
	s_waitcnt vmcnt(17)
	v_cvt_pk_f32_fp8_e32 v[224:225], v168
	v_cvt_pk_f32_fp8_sdwa v[226:227], v168 src0_sel:WORD_1
	v_cvt_pk_f32_fp8_e32 v[228:229], v169
	v_cvt_pk_f32_fp8_sdwa v[230:231], v169 src0_sel:WORD_1
	v_pk_fma_f32 v[96:97], v[224:225], v[250:251], v[96:97] op_sel_hi:[1,0,1]
	v_pk_fma_f32 v[98:99], v[226:227], v[250:251], v[98:99] op_sel_hi:[1,0,1]
	v_pk_fma_f32 v[100:101], v[228:229], v[250:251], v[100:101] op_sel_hi:[1,0,1]
	v_pk_fma_f32 v[102:103], v[230:231], v[250:251], v[102:103] op_sel_hi:[1,0,1]
	v_cvt_pk_f32_fp8_e32 v[224:225], v170
	v_cvt_pk_f32_fp8_sdwa v[226:227], v170 src0_sel:WORD_1
	v_cvt_pk_f32_fp8_e32 v[228:229], v171
	v_cvt_pk_f32_fp8_sdwa v[230:231], v171 src0_sel:WORD_1
	v_pk_fma_f32 v[104:105], v[224:225], v[250:251], v[104:105] op_sel_hi:[1,0,1]
	v_pk_fma_f32 v[106:107], v[226:227], v[250:251], v[106:107] op_sel_hi:[1,0,1]
	v_pk_fma_f32 v[108:109], v[228:229], v[250:251], v[108:109] op_sel_hi:[1,0,1]
	v_pk_fma_f32 v[110:111], v[230:231], v[250:251], v[110:111] op_sel_hi:[1,0,1]
	s_waitcnt vmcnt(16)
	v_cvt_pk_f32_fp8_e32 v[224:225], v172
	v_cvt_pk_f32_fp8_sdwa v[226:227], v172 src0_sel:WORD_1
	v_cvt_pk_f32_fp8_e32 v[228:229], v173
	v_cvt_pk_f32_fp8_sdwa v[230:231], v173 src0_sel:WORD_1
	v_pk_fma_f32 v[96:97], v[224:225], v[250:251], v[96:97] op_sel:[0,1,0] op_sel_hi:[1,1,1]
	v_pk_fma_f32 v[98:99], v[226:227], v[250:251], v[98:99] op_sel:[0,1,0] op_sel_hi:[1,1,1]
	v_pk_fma_f32 v[100:101], v[228:229], v[250:251], v[100:101] op_sel:[0,1,0] op_sel_hi:[1,1,1]
	v_pk_fma_f32 v[102:103], v[230:231], v[250:251], v[102:103] op_sel:[0,1,0] op_sel_hi:[1,1,1]
	v_cvt_pk_f32_fp8_e32 v[224:225], v174
	v_cvt_pk_f32_fp8_sdwa v[226:227], v174 src0_sel:WORD_1
	v_cvt_pk_f32_fp8_e32 v[228:229], v175
	v_cvt_pk_f32_fp8_sdwa v[230:231], v175 src0_sel:WORD_1
	v_pk_fma_f32 v[104:105], v[224:225], v[250:251], v[104:105] op_sel:[0,1,0] op_sel_hi:[1,1,1]
	v_pk_fma_f32 v[106:107], v[226:227], v[250:251], v[106:107] op_sel:[0,1,0] op_sel_hi:[1,1,1]
	v_pk_fma_f32 v[108:109], v[228:229], v[250:251], v[108:109] op_sel:[0,1,0] op_sel_hi:[1,1,1]
	v_pk_fma_f32 v[110:111], v[230:231], v[250:251], v[110:111] op_sel:[0,1,0] op_sel_hi:[1,1,1]
	s_sub_i32 s90, s90, 1
	s_cmp_eq_u32 s90, 0
	s_cbranch_scc1 .LV_sw3
.LV_t6_s3:
	s_waitcnt lgkmcnt(0)
	buffer_load_dwordx4 v[160:163], v[232:233], s[60:63], 0 idxen offen
	buffer_load_dwordx4 v[164:167], v[234:235], s[60:63], 0 idxen offen
	buffer_load_dwordx4 v[168:171], v[236:237], s[60:63], 0 idxen offen
	buffer_load_dwordx4 v[172:175], v[238:239], s[60:63], 0 idxen offen
	ds_read_b32 v232, v213 offset:128
	ds_read_b32 v234, v213 offset:132
	ds_read_b32 v236, v213 offset:136
	ds_read_b32 v238, v213 offset:140
	ds_read_b128 v[208:211], v213 offset:5056
	s_waitcnt vmcnt(19)
	v_cvt_pk_f32_fp8_e32 v[224:225], v176
	v_cvt_pk_f32_fp8_sdwa v[226:227], v176 src0_sel:WORD_1
	v_cvt_pk_f32_fp8_e32 v[228:229], v177
	v_cvt_pk_f32_fp8_sdwa v[230:231], v177 src0_sel:WORD_1
	v_pk_fma_f32 v[96:97], v[224:225], v[252:253], v[96:97] op_sel_hi:[1,0,1]
	v_pk_fma_f32 v[98:99], v[226:227], v[252:253], v[98:99] op_sel_hi:[1,0,1]
	v_pk_fma_f32 v[100:101], v[228:229], v[252:253], v[100:101] op_sel_hi:[1,0,1]
	v_pk_fma_f32 v[102:103], v[230:231], v[252:253], v[102:103] op_sel_hi:[1,0,1]
	v_cvt_pk_f32_fp8_e32 v[224:225], v178
	v_cvt_pk_f32_fp8_sdwa v[226:227], v178 src0_sel:WORD_1
	v_cvt_pk_f32_fp8_e32 v[228:229], v179
	v_cvt_pk_f32_fp8_sdwa v[230:231], v179 src0_sel:WORD_1
	v_pk_fma_f32 v[104:105], v[224:225], v[252:253], v[104:105] op_sel_hi:[1,0,1]
	v_pk_fma_f32 v[106:107], v[226:227], v[252:253], v[106:107] op_sel_hi:[1,0,1]
	v_pk_fma_f32 v[108:109], v[228:229], v[252:253], v[108:109] op_sel_hi:[1,0,1]
	v_pk_fma_f32 v[110:111], v[230:231], v[252:253], v[110:111] op_sel_hi:[1,0,1]
	s_waitcnt vmcnt(18)
	v_cvt_pk_f32_fp8_e32 v[224:225], v180
	v_cvt_pk_f32_fp8_sdwa v[226:227], v180 src0_sel:WORD_1
	v_cvt_pk_f32_fp8_e32 v[228:229], v181
	v_cvt_pk_f32_fp8_sdwa v[230:231], v181 src0_sel:WORD_1
	v_pk_fma_f32 v[96:97], v[224:225], v[252:253], v[96:97] op_sel:[0,1,0] op_sel_hi:[1,1,1]
	v_pk_fma_f32 v[98:99], v[226:227], v[252:253], v[98:99] op_sel:[0,1,0] op_sel_hi:[1,1,1]
	v_pk_fma_f32 v[100:101], v[228:229], v[252:253], v[100:101] op_sel:[0,1,0] op_sel_hi:[1,1,1]
	v_pk_fma_f32 v[102:103], v[230:231], v[252:253], v[102:103] op_sel:[0,1,0] op_sel_hi:[1,1,1]
	v_cvt_pk_f32_fp8_e32 v[224:225], v182
	v_cvt_pk_f32_fp8_sdwa v[226:227], v182 src0_sel:WORD_1
	v_cvt_pk_f32_fp8_e32 v[228:229], v183
	v_cvt_pk_f32_fp8_sdwa v[230:231], v183 src0_sel:WORD_1
	v_pk_fma_f32 v[104:105], v[224:225], v[252:253], v[104:105] op_sel:[0,1,0] op_sel_hi:[1,1,1]
	v_pk_fma_f32 v[106:107], v[226:227], v[252:253], v[106:107] op_sel:[0,1,0] op_sel_hi:[1,1,1]
	v_pk_fma_f32 v[108:109], v[228:229], v[252:253], v[108:109] op_sel:[0,1,0] op_sel_hi:[1,1,1]
	v_pk_fma_f32 v[110:111], v[230:231], v[252:253], v[110:111] op_sel:[0,1,0] op_sel_hi:[1,1,1]
	s_waitcnt vmcnt(17)
	v_cvt_pk_f32_fp8_e32 v[224:225], v184
	v_cvt_pk_f32_fp8_sdwa v[226:227], v184 src0_sel:WORD_1
	v_cvt_pk_f32_fp8_e32 v[228:229], v185
	v_cvt_pk_f32_fp8_sdwa v[230:231], v185 src0_sel:WORD_1
	v_pk_fma_f32 v[96:97], v[224:225], v[254:255], v[96:97] op_sel_hi:[1,0,1]
	v_pk_fma_f32 v[98:99], v[226:227], v[254:255], v[98:99] op_sel_hi:[1,0,1]
	v_pk_fma_f32 v[100:101], v[228:229], v[254:255], v[100:101] op_sel_hi:[1,0,1]
	v_pk_fma_f32 v[102:103], v[230:231], v[254:255], v[102:103] op_sel_hi:[1,0,1]
	v_cvt_pk_f32_fp8_e32 v[224:225], v186
	v_cvt_pk_f32_fp8_sdwa v[226:227], v186 src0_sel:WORD_1
	v_cvt_pk_f32_fp8_e32 v[228:229], v187
	v_cvt_pk_f32_fp8_sdwa v[230:231], v187 src0_sel:WORD_1
	v_pk_fma_f32 v[104:105], v[224:225], v[254:255], v[104:105] op_sel_hi:[1,0,1]
	v_pk_fma_f32 v[106:107], v[226:227], v[254:255], v[106:107] op_sel_hi:[1,0,1]
	v_pk_fma_f32 v[108:109], v[228:229], v[254:255], v[108:109] op_sel_hi:[1,0,1]
	v_pk_fma_f32 v[110:111], v[230:231], v[254:255], v[110:111] op_sel_hi:[1,0,1]
	s_waitcnt vmcnt(16)
	v_cvt_pk_f32_fp8_e32 v[224:225], v188
	v_cvt_pk_f32_fp8_sdwa v[226:227], v188 src0_sel:WORD_1
	v_cvt_pk_f32_fp8_e32 v[228:229], v189
	v_cvt_pk_f32_fp8_sdwa v[230:231], v189 src0_sel:WORD_1
	v_pk_fma_f32 v[96:97], v[224:225], v[254:255], v[96:97] op_sel:[0,1,0] op_sel_hi:[1,1,1]
	v_pk_fma_f32 v[98:99], v[226:227], v[254:255], v[98:99] op_sel:[0,1,0] op_sel_hi:[1,1,1]
	v_pk_fma_f32 v[100:101], v[228:229], v[254:255], v[100:101] op_sel:[0,1,0] op_sel_hi:[1,1,1]
	v_pk_fma_f32 v[102:103], v[230:231], v[254:255], v[102:103] op_sel:[0,1,0] op_sel_hi:[1,1,1]
	v_cvt_pk_f32_fp8_e32 v[224:225], v190
	v_cvt_pk_f32_fp8_sdwa v[226:227], v190 src0_sel:WORD_1
	v_cvt_pk_f32_fp8_e32 v[228:229], v191
	v_cvt_pk_f32_fp8_sdwa v[230:231], v191 src0_sel:WORD_1
	v_pk_fma_f32 v[104:105], v[224:225], v[254:255], v[104:105] op_sel:[0,1,0] op_sel_hi:[1,1,1]
	v_pk_fma_f32 v[106:107], v[226:227], v[254:255], v[106:107] op_sel:[0,1,0] op_sel_hi:[1,1,1]
	v_pk_fma_f32 v[108:109], v[228:229], v[254:255], v[108:109] op_sel:[0,1,0] op_sel_hi:[1,1,1]
	v_pk_fma_f32 v[110:111], v[230:231], v[254:255], v[110:111] op_sel:[0,1,0] op_sel_hi:[1,1,1]
	s_sub_i32 s90, s90, 1
	s_cmp_eq_u32 s90, 0
	s_cbranch_scc1 .LV_sw4
.LV_t6_s4:
	s_waitcnt lgkmcnt(0)
	buffer_load_dwordx4 v[176:179], v[232:233], s[60:63], 0 idxen offen
	buffer_load_dwordx4 v[180:183], v[234:235], s[60:63], 0 idxen offen
	buffer_load_dwordx4 v[184:187], v[236:237], s[60:63], 0 idxen offen
	buffer_load_dwordx4 v[188:191], v[238:239], s[60:63], 0 idxen offen
	ds_read_b32 v232, v213 offset:144
	ds_read_b32 v234, v213 offset:148
	ds_read_b32 v236, v213 offset:152
	ds_read_b32 v238, v213 offset:156
	ds_read_b128 v[248:251], v213 offset:5072
	s_waitcnt vmcnt(19)
	v_cvt_pk_f32_fp8_e32 v[224:225], v192
	v_cvt_pk_f32_fp8_sdwa v[226:227], v192 src0_sel:WORD_1
	v_cvt_pk_f32_fp8_e32 v[228:229], v193
	v_cvt_pk_f32_fp8_sdwa v[230:231], v193 src0_sel:WORD_1
	v_pk_fma_f32 v[96:97], v[224:225], v[208:209], v[96:97] op_sel_hi:[1,0,1]
	v_pk_fma_f32 v[98:99], v[226:227], v[208:209], v[98:99] op_sel_hi:[1,0,1]
	v_pk_fma_f32 v[100:101], v[228:229], v[208:209], v[100:101] op_sel_hi:[1,0,1]
	v_pk_fma_f32 v[102:103], v[230:231], v[208:209], v[102:103] op_sel_hi:[1,0,1]
	v_cvt_pk_f32_fp8_e32 v[224:225], v194
	v_cvt_pk_f32_fp8_sdwa v[226:227], v194 src0_sel:WORD_1
	v_cvt_pk_f32_fp8_e32 v[228:229], v195
	v_cvt_pk_f32_fp8_sdwa v[230:231], v195 src0_sel:WORD_1
	v_pk_fma_f32 v[104:105], v[224:225], v[208:209], v[104:105] op_sel_hi:[1,0,1]
	v_pk_fma_f32 v[106:107], v[226:227], v[208:209], v[106:107] op_sel_hi:[1,0,1]
	v_pk_fma_f32 v[108:109], v[228:229], v[208:209], v[108:109] op_sel_hi:[1,0,1]
	v_pk_fma_f32 v[110:111], v[230:231], v[208:209], v[110:111] op_sel_hi:[1,0,1]
	s_waitcnt vmcnt(18)
	v_cvt_pk_f32_fp8_e32 v[224:225], v196
	v_cvt_pk_f32_fp8_sdwa v[226:227], v196 src0_sel:WORD_1
	v_cvt_pk_f32_fp8_e32 v[228:229], v197
	v_cvt_pk_f32_fp8_sdwa v[230:231], v197 src0_sel:WORD_1
	v_pk_fma_f32 v[96:97], v[224:225], v[208:209], v[96:97] op_sel:[0,1,0] op_sel_hi:[1,1,1]
	v_pk_fma_f32 v[98:99], v[226:227], v[208:209], v[98:99] op_sel:[0,1,0] op_sel_hi:[1,1,1]
	v_pk_fma_f32 v[100:101], v[228:229], v[208:209], v[100:101] op_sel:[0,1,0] op_sel_hi:[1,1,1]
	v_pk_fma_f32 v[102:103], v[230:231], v[208:209], v[102:103] op_sel:[0,1,0] op_sel_hi:[1,1,1]
	v_cvt_pk_f32_fp8_e32 v[224:225], v198
	v_cvt_pk_f32_fp8_sdwa v[226:227], v198 src0_sel:WORD_1
	v_cvt_pk_f32_fp8_e32 v[228:229], v199
	v_cvt_pk_f32_fp8_sdwa v[230:231], v199 src0_sel:WORD_1
	v_pk_fma_f32 v[104:105], v[224:225], v[208:209], v[104:105] op_sel:[0,1,0] op_sel_hi:[1,1,1]
	v_pk_fma_f32 v[106:107], v[226:227], v[208:209], v[106:107] op_sel:[0,1,0] op_sel_hi:[1,1,1]
	v_pk_fma_f32 v[108:109], v[228:229], v[208:209], v[108:109] op_sel:[0,1,0] op_sel_hi:[1,1,1]
	v_pk_fma_f32 v[110:111], v[230:231], v[208:209], v[110:111] op_sel:[0,1,0] op_sel_hi:[1,1,1]
	s_waitcnt vmcnt(17)
	v_cvt_pk_f32_fp8_e32 v[224:225], v200
	v_cvt_pk_f32_fp8_sdwa v[226:227], v200 src0_sel:WORD_1
	v_cvt_pk_f32_fp8_e32 v[228:229], v201
	v_cvt_pk_f32_fp8_sdwa v[230:231], v201 src0_sel:WORD_1
	v_pk_fma_f32 v[96:97], v[224:225], v[210:211], v[96:97] op_sel_hi:[1,0,1]
	v_pk_fma_f32 v[98:99], v[226:227], v[210:211], v[98:99] op_sel_hi:[1,0,1]
	v_pk_fma_f32 v[100:101], v[228:229], v[210:211], v[100:101] op_sel_hi:[1,0,1]
	v_pk_fma_f32 v[102:103], v[230:231], v[210:211], v[102:103] op_sel_hi:[1,0,1]
	v_cvt_pk_f32_fp8_e32 v[224:225], v202
	v_cvt_pk_f32_fp8_sdwa v[226:227], v202 src0_sel:WORD_1
	v_cvt_pk_f32_fp8_e32 v[228:229], v203
	v_cvt_pk_f32_fp8_sdwa v[230:231], v203 src0_sel:WORD_1
	v_pk_fma_f32 v[104:105], v[224:225], v[210:211], v[104:105] op_sel_hi:[1,0,1]
	v_pk_fma_f32 v[106:107], v[226:227], v[210:211], v[106:107] op_sel_hi:[1,0,1]
	v_pk_fma_f32 v[108:109], v[228:229], v[210:211], v[108:109] op_sel_hi:[1,0,1]
	v_pk_fma_f32 v[110:111], v[230:231], v[210:211], v[110:111] op_sel_hi:[1,0,1]
	s_waitcnt vmcnt(16)
	v_cvt_pk_f32_fp8_e32 v[224:225], v204
	v_cvt_pk_f32_fp8_sdwa v[226:227], v204 src0_sel:WORD_1
	v_cvt_pk_f32_fp8_e32 v[228:229], v205
	v_cvt_pk_f32_fp8_sdwa v[230:231], v205 src0_sel:WORD_1
	v_pk_fma_f32 v[96:97], v[224:225], v[210:211], v[96:97] op_sel:[0,1,0] op_sel_hi:[1,1,1]
	v_pk_fma_f32 v[98:99], v[226:227], v[210:211], v[98:99] op_sel:[0,1,0] op_sel_hi:[1,1,1]
	v_pk_fma_f32 v[100:101], v[228:229], v[210:211], v[100:101] op_sel:[0,1,0] op_sel_hi:[1,1,1]
	v_pk_fma_f32 v[102:103], v[230:231], v[210:211], v[102:103] op_sel:[0,1,0] op_sel_hi:[1,1,1]
	v_cvt_pk_f32_fp8_e32 v[224:225], v206
	v_cvt_pk_f32_fp8_sdwa v[226:227], v206 src0_sel:WORD_1
	v_cvt_pk_f32_fp8_e32 v[228:229], v207
	v_cvt_pk_f32_fp8_sdwa v[230:231], v207 src0_sel:WORD_1
	v_pk_fma_f32 v[104:105], v[224:225], v[210:211], v[104:105] op_sel:[0,1,0] op_sel_hi:[1,1,1]
	v_pk_fma_f32 v[106:107], v[226:227], v[210:211], v[106:107] op_sel:[0,1,0] op_sel_hi:[1,1,1]
	v_pk_fma_f32 v[108:109], v[228:229], v[210:211], v[108:109] op_sel:[0,1,0] op_sel_hi:[1,1,1]
	v_pk_fma_f32 v[110:111], v[230:231], v[210:211], v[110:111] op_sel:[0,1,0] op_sel_hi:[1,1,1]
	v_add_u32_e32 v213, 80, v213
	s_add_i32 s21, s21, 5
	s_sub_i32 s90, s90, 1
	s_cmp_eq_u32 s90, 0
	s_cbranch_scc1 .LV_sw0
	s_branch .LV_t6_s0
; #define IT_ADVANCE() do { it_j += 4; while (it_j >= it_end) { if (it_done) break; ++it_tk; if (it_tk == 4) { it_tk = 0; ++it_p; if (it_p == 16) { it_done = true; it_p = 15; it_j = 0; it_end = 1; break; } } \
;             it_j = __builtin_amdgcn_readfirstlane(OFFS[(tb + it_tk) * 17 + it_p]); it_end = __builtin_amdgcn_readfirstlane(OFFS[(tb + it_tk) * 17 + it_p + 1]); } } while (0)
; __device__ __forceinline__ void peer_tile(const Args& A, LAS unsigned char* lds, int tile) {
;     ...
;                 for (int j0 = beg; j0 < end; j0 += 8) {
;                     IT_ADVANCE();
.LV_t7_s0:
	s_cmp_ge_u32 s21, s20
	s_cbranch_scc1 .LV_done
	s_waitcnt lgkmcnt(0)
	buffer_load_dwordx4 v[192:195], v[232:233], s[60:63], 0 idxen offen
	buffer_load_dwordx4 v[196:199], v[234:235], s[60:63], 0 idxen offen
	buffer_load_dwordx4 v[200:203], v[236:237], s[60:63], 0 idxen offen
	buffer_load_dwordx4 v[204:207], v[238:239], s[60:63], 0 idxen offen
	ds_read_b32 v232, v213 offset:80
	ds_read_b32 v234, v213 offset:84
	ds_read_b32 v236, v213 offset:88
	ds_read_b32 v238, v213 offset:92
	ds_read_b128 v[252:255], v213 offset:5008
	s_waitcnt vmcnt(19)
	v_cvt_pk_f32_fp8_e32 v[224:225], v128
	v_cvt_pk_f32_fp8_sdwa v[226:227], v128 src0_sel:WORD_1
	v_cvt_pk_f32_fp8_e32 v[228:229], v129
	v_cvt_pk_f32_fp8_sdwa v[230:231], v129 src0_sel:WORD_1
	v_pk_fma_f32 v[112:113], v[224:225], v[248:249], v[112:113] op_sel_hi:[1,0,1]
	v_pk_fma_f32 v[114:115], v[226:227], v[248:249], v[114:115] op_sel_hi:[1,0,1]
	v_pk_fma_f32 v[116:117], v[228:229], v[248:249], v[116:117] op_sel_hi:[1,0,1]
	v_pk_fma_f32 v[118:119], v[230:231], v[248:249], v[118:119] op_sel_hi:[1,0,1]
	v_cvt_pk_f32_fp8_e32 v[224:225], v130
	v_cvt_pk_f32_fp8_sdwa v[226:227], v130 src0_sel:WORD_1
	v_cvt_pk_f32_fp8_e32 v[228:229], v131
	v_cvt_pk_f32_fp8_sdwa v[230:231], v131 src0_sel:WORD_1
	v_pk_fma_f32 v[120:121], v[224:225], v[248:249], v[120:121] op_sel_hi:[1,0,1]
	v_pk_fma_f32 v[122:123], v[226:227], v[248:249], v[122:123] op_sel_hi:[1,0,1]
	v_pk_fma_f32 v[124:125], v[228:229], v[248:249], v[124:125] op_sel_hi:[1,0,1]
	v_pk_fma_f32 v[126:127], v[230:231], v[248:249], v[126:127] op_sel_hi:[1,0,1]
	s_waitcnt vmcnt(18)
	v_cvt_pk_f32_fp8_e32 v[224:225], v132
	v_cvt_pk_f32_fp8_sdwa v[226:227], v132 src0_sel:WORD_1
	v_cvt_pk_f32_fp8_e32 v[228:229], v133
	v_cvt_pk_f32_fp8_sdwa v[230:231], v133 src0_sel:WORD_1
	v_pk_fma_f32 v[112:113], v[224:225], v[248:249], v[112:113] op_sel:[0,1,0] op_sel_hi:[1,1,1]
	v_pk_fma_f32 v[114:115], v[226:227], v[248:249], v[114:115] op_sel:[0,1,0] op_sel_hi:[1,1,1]
	v_pk_fma_f32 v[116:117], v[228:229], v[248:249], v[116:117] op_sel:[0,1,0] op_sel_hi:[1,1,1]
	v_pk_fma_f32 v[118:119], v[230:231], v[248:249], v[118:119] op_sel:[0,1,0] op_sel_hi:[1,1,1]
	v_cvt_pk_f32_fp8_e32 v[224:225], v134
	v_cvt_pk_f32_fp8_sdwa v[226:227], v134 src0_sel:WORD_1
	v_cvt_pk_f32_fp8_e32 v[228:229], v135
	v_cvt_pk_f32_fp8_sdwa v[230:231], v135 src0_sel:WORD_1
	v_pk_fma_f32 v[120:121], v[224:225], v[248:249], v[120:121] op_sel:[0,1,0] op_sel_hi:[1,1,1]
	v_pk_fma_f32 v[122:123], v[226:227], v[248:249], v[122:123] op_sel:[0,1,0] op_sel_hi:[1,1,1]
	v_pk_fma_f32 v[124:125], v[228:229], v[248:249], v[124:125] op_sel:[0,1,0] op_sel_hi:[1,1,1]
	v_pk_fma_f32 v[126:127], v[230:231], v[248:249], v[126:127] op_sel:[0,1,0] op_sel_hi:[1,1,1]
	s_waitcnt vmcnt(17)
	v_cvt_pk_f32_fp8_e32 v[224:225], v136
	v_cvt_pk_f32_fp8_sdwa v[226:227], v136 src0_sel:WORD_1
	v_cvt_pk_f32_fp8_e32 v[228:229], v137
	v_cvt_pk_f32_fp8_sdwa v[230:231], v137 src0_sel:WORD_1
	v_pk_fma_f32 v[112:113], v[224:225], v[250:251], v[112:113] op_sel_hi:[1,0,1]
	v_pk_fma_f32 v[114:115], v[226:227], v[250:251], v[114:115] op_sel_hi:[1,0,1]
	v_pk_fma_f32 v[116:117], v[228:229], v[250:251], v[116:117] op_sel_hi:[1,0,1]
	v_pk_fma_f32 v[118:119], v[230:231], v[250:251], v[118:119] op_sel_hi:[1,0,1]
	v_cvt_pk_f32_fp8_e32 v[224:225], v138
	v_cvt_pk_f32_fp8_sdwa v[226:227], v138 src0_sel:WORD_1
	v_cvt_pk_f32_fp8_e32 v[228:229], v139
	v_cvt_pk_f32_fp8_sdwa v[230:231], v139 src0_sel:WORD_1
	v_pk_fma_f32 v[120:121], v[224:225], v[250:251], v[120:121] op_sel_hi:[1,0,1]
	v_pk_fma_f32 v[122:123], v[226:227], v[250:251], v[122:123] op_sel_hi:[1,0,1]
	v_pk_fma_f32 v[124:125], v[228:229], v[250:251], v[124:125] op_sel_hi:[1,0,1]
	v_pk_fma_f32 v[126:127], v[230:231], v[250:251], v[126:127] op_sel_hi:[1,0,1]
	s_waitcnt vmcnt(16)
	v_cvt_pk_f32_fp8_e32 v[224:225], v140
	v_cvt_pk_f32_fp8_sdwa v[226:227], v140 src0_sel:WORD_1
	v_cvt_pk_f32_fp8_e32 v[228:229], v141
	v_cvt_pk_f32_fp8_sdwa v[230:231], v141 src0_sel:WORD_1
	v_pk_fma_f32 v[112:113], v[224:225], v[250:251], v[112:113] op_sel:[0,1,0] op_sel_hi:[1,1,1]
	v_pk_fma_f32 v[114:115], v[226:227], v[250:251], v[114:115] op_sel:[0,1,0] op_sel_hi:[1,1,1]
	v_pk_fma_f32 v[116:117], v[228:229], v[250:251], v[116:117] op_sel:[0,1,0] op_sel_hi:[1,1,1]
	v_pk_fma_f32 v[118:119], v[230:231], v[250:251], v[118:119] op_sel:[0,1,0] op_sel_hi:[1,1,1]
	v_cvt_pk_f32_fp8_e32 v[224:225], v142
	v_cvt_pk_f32_fp8_sdwa v[226:227], v142 src0_sel:WORD_1
	v_cvt_pk_f32_fp8_e32 v[228:229], v143
	v_cvt_pk_f32_fp8_sdwa v[230:231], v143 src0_sel:WORD_1
	v_pk_fma_f32 v[120:121], v[224:225], v[250:251], v[120:121] op_sel:[0,1,0] op_sel_hi:[1,1,1]
	v_pk_fma_f32 v[122:123], v[226:227], v[250:251], v[122:123] op_sel:[0,1,0] op_sel_hi:[1,1,1]
	v_pk_fma_f32 v[124:125], v[228:229], v[250:251], v[124:125] op_sel:[0,1,0] op_sel_hi:[1,1,1]
	v_pk_fma_f32 v[126:127], v[230:231], v[250:251], v[126:127] op_sel:[0,1,0] op_sel_hi:[1,1,1]
	s_sub_i32 s90, s90, 1
	s_cmp_eq_u32 s90, 0
	s_cbranch_scc1 .LV_sw1
.LV_t7_s1:
	s_waitcnt lgkmcnt(0)
	buffer_load_dwordx4 v[128:131], v[232:233], s[60:63], 0 idxen offen
	buffer_load_dwordx4 v[132:135], v[234:235], s[60:63], 0 idxen offen
	buffer_load_dwordx4 v[136:139], v[236:237], s[60:63], 0 idxen offen
	buffer_load_dwordx4 v[140:143], v[238:239], s[60:63], 0 idxen offen
	ds_read_b32 v232, v213 offset:96
	ds_read_b32 v234, v213 offset:100
	ds_read_b32 v236, v213 offset:104
	ds_read_b32 v238, v213 offset:108
	ds_read_b128 v[248:251], v213 offset:5024
	s_waitcnt vmcnt(19)
	v_cvt_pk_f32_fp8_e32 v[224:225], v144
	v_cvt_pk_f32_fp8_sdwa v[226:227], v144 src0_sel:WORD_1
	v_cvt_pk_f32_fp8_e32 v[228:229], v145
	v_cvt_pk_f32_fp8_sdwa v[230:231], v145 src0_sel:WORD_1
	v_pk_fma_f32 v[112:113], v[224:225], v[252:253], v[112:113] op_sel_hi:[1,0,1]
	v_pk_fma_f32 v[114:115], v[226:227], v[252:253], v[114:115] op_sel_hi:[1,0,1]
	v_pk_fma_f32 v[116:117], v[228:229], v[252:253], v[116:117] op_sel_hi:[1,0,1]
	v_pk_fma_f32 v[118:119], v[230:231], v[252:253], v[118:119] op_sel_hi:[1,0,1]
	v_cvt_pk_f32_fp8_e32 v[224:225], v146
	v_cvt_pk_f32_fp8_sdwa v[226:227], v146 src0_sel:WORD_1
	v_cvt_pk_f32_fp8_e32 v[228:229], v147
	v_cvt_pk_f32_fp8_sdwa v[230:231], v147 src0_sel:WORD_1
	v_pk_fma_f32 v[120:121], v[224:225], v[252:253], v[120:121] op_sel_hi:[1,0,1]
	v_pk_fma_f32 v[122:123], v[226:227], v[252:253], v[122:123] op_sel_hi:[1,0,1]
	v_pk_fma_f32 v[124:125], v[228:229], v[252:253], v[124:125] op_sel_hi:[1,0,1]
	v_pk_fma_f32 v[126:127], v[230:231], v[252:253], v[126:127] op_sel_hi:[1,0,1]
	s_waitcnt vmcnt(18)
	v_cvt_pk_f32_fp8_e32 v[224:225], v148
	v_cvt_pk_f32_fp8_sdwa v[226:227], v148 src0_sel:WORD_1
	v_cvt_pk_f32_fp8_e32 v[228:229], v149
	v_cvt_pk_f32_fp8_sdwa v[230:231], v149 src0_sel:WORD_1
	v_pk_fma_f32 v[112:113], v[224:225], v[252:253], v[112:113] op_sel:[0,1,0] op_sel_hi:[1,1,1]
	v_pk_fma_f32 v[114:115], v[226:227], v[252:253], v[114:115] op_sel:[0,1,0] op_sel_hi:[1,1,1]
	v_pk_fma_f32 v[116:117], v[228:229], v[252:253], v[116:117] op_sel:[0,1,0] op_sel_hi:[1,1,1]
	v_pk_fma_f32 v[118:119], v[230:231], v[252:253], v[118:119] op_sel:[0,1,0] op_sel_hi:[1,1,1]
	v_cvt_pk_f32_fp8_e32 v[224:225], v150
	v_cvt_pk_f32_fp8_sdwa v[226:227], v150 src0_sel:WORD_1
	v_cvt_pk_f32_fp8_e32 v[228:229], v151
	v_cvt_pk_f32_fp8_sdwa v[230:231], v151 src0_sel:WORD_1
	v_pk_fma_f32 v[120:121], v[224:225], v[252:253], v[120:121] op_sel:[0,1,0] op_sel_hi:[1,1,1]
	v_pk_fma_f32 v[122:123], v[226:227], v[252:253], v[122:123] op_sel:[0,1,0] op_sel_hi:[1,1,1]
	v_pk_fma_f32 v[124:125], v[228:229], v[252:253], v[124:125] op_sel:[0,1,0] op_sel_hi:[1,1,1]
	v_pk_fma_f32 v[126:127], v[230:231], v[252:253], v[126:127] op_sel:[0,1,0] op_sel_hi:[1,1,1]
	s_waitcnt vmcnt(17)
	v_cvt_pk_f32_fp8_e32 v[224:225], v152
	v_cvt_pk_f32_fp8_sdwa v[226:227], v152 src0_sel:WORD_1
	v_cvt_pk_f32_fp8_e32 v[228:229], v153
	v_cvt_pk_f32_fp8_sdwa v[230:231], v153 src0_sel:WORD_1
	v_pk_fma_f32 v[112:113], v[224:225], v[254:255], v[112:113] op_sel_hi:[1,0,1]
	v_pk_fma_f32 v[114:115], v[226:227], v[254:255], v[114:115] op_sel_hi:[1,0,1]
	v_pk_fma_f32 v[116:117], v[228:229], v[254:255], v[116:117] op_sel_hi:[1,0,1]
	v_pk_fma_f32 v[118:119], v[230:231], v[254:255], v[118:119] op_sel_hi:[1,0,1]
	v_cvt_pk_f32_fp8_e32 v[224:225], v154
	v_cvt_pk_f32_fp8_sdwa v[226:227], v154 src0_sel:WORD_1
	v_cvt_pk_f32_fp8_e32 v[228:229], v155
	v_cvt_pk_f32_fp8_sdwa v[230:231], v155 src0_sel:WORD_1
	v_pk_fma_f32 v[120:121], v[224:225], v[254:255], v[120:121] op_sel_hi:[1,0,1]
	v_pk_fma_f32 v[122:123], v[226:227], v[254:255], v[122:123] op_sel_hi:[1,0,1]
	v_pk_fma_f32 v[124:125], v[228:229], v[254:255], v[124:125] op_sel_hi:[1,0,1]
	v_pk_fma_f32 v[126:127], v[230:231], v[254:255], v[126:127] op_sel_hi:[1,0,1]
	s_waitcnt vmcnt(16)
	v_cvt_pk_f32_fp8_e32 v[224:225], v156
	v_cvt_pk_f32_fp8_sdwa v[226:227], v156 src0_sel:WORD_1
	v_cvt_pk_f32_fp8_e32 v[228:229], v157
	v_cvt_pk_f32_fp8_sdwa v[230:231], v157 src0_sel:WORD_1
	v_pk_fma_f32 v[112:113], v[224:225], v[254:255], v[112:113] op_sel:[0,1,0] op_sel_hi:[1,1,1]
	v_pk_fma_f32 v[114:115], v[226:227], v[254:255], v[114:115] op_sel:[0,1,0] op_sel_hi:[1,1,1]
	v_pk_fma_f32 v[116:117], v[228:229], v[254:255], v[116:117] op_sel:[0,1,0] op_sel_hi:[1,1,1]
	v_pk_fma_f32 v[118:119], v[230:231], v[254:255], v[118:119] op_sel:[0,1,0] op_sel_hi:[1,1,1]
	v_cvt_pk_f32_fp8_e32 v[224:225], v158
	v_cvt_pk_f32_fp8_sdwa v[226:227], v158 src0_sel:WORD_1
	v_cvt_pk_f32_fp8_e32 v[228:229], v159
	v_cvt_pk_f32_fp8_sdwa v[230:231], v159 src0_sel:WORD_1
	v_pk_fma_f32 v[120:121], v[224:225], v[254:255], v[120:121] op_sel:[0,1,0] op_sel_hi:[1,1,1]
	v_pk_fma_f32 v[122:123], v[226:227], v[254:255], v[122:123] op_sel:[0,1,0] op_sel_hi:[1,1,1]
	v_pk_fma_f32 v[124:125], v[228:229], v[254:255], v[124:125] op_sel:[0,1,0] op_sel_hi:[1,1,1]
	v_pk_fma_f32 v[126:127], v[230:231], v[254:255], v[126:127] op_sel:[0,1,0] op_sel_hi:[1,1,1]
	s_sub_i32 s90, s90, 1
	s_cmp_eq_u32 s90, 0
	s_cbranch_scc1 .LV_sw2
.LV_t7_s2:
	s_waitcnt lgkmcnt(0)
	buffer_load_dwordx4 v[144:147], v[232:233], s[60:63], 0 idxen offen
	buffer_load_dwordx4 v[148:151], v[234:235], s[60:63], 0 idxen offen
	buffer_load_dwordx4 v[152:155], v[236:237], s[60:63], 0 idxen offen
	buffer_load_dwordx4 v[156:159], v[238:239], s[60:63], 0 idxen offen
	ds_read_b32 v232, v213 offset:112
	ds_read_b32 v234, v213 offset:116
	ds_read_b32 v236, v213 offset:120
	ds_read_b32 v238, v213 offset:124
	ds_read_b128 v[252:255], v213 offset:5040
	s_waitcnt vmcnt(19)
	v_cvt_pk_f32_fp8_e32 v[224:225], v160
	v_cvt_pk_f32_fp8_sdwa v[226:227], v160 src0_sel:WORD_1
	v_cvt_pk_f32_fp8_e32 v[228:229], v161
	v_cvt_pk_f32_fp8_sdwa v[230:231], v161 src0_sel:WORD_1
	v_pk_fma_f32 v[112:113], v[224:225], v[248:249], v[112:113] op_sel_hi:[1,0,1]
	v_pk_fma_f32 v[114:115], v[226:227], v[248:249], v[114:115] op_sel_hi:[1,0,1]
	v_pk_fma_f32 v[116:117], v[228:229], v[248:249], v[116:117] op_sel_hi:[1,0,1]
	v_pk_fma_f32 v[118:119], v[230:231], v[248:249], v[118:119] op_sel_hi:[1,0,1]
	v_cvt_pk_f32_fp8_e32 v[224:225], v162
	v_cvt_pk_f32_fp8_sdwa v[226:227], v162 src0_sel:WORD_1
	v_cvt_pk_f32_fp8_e32 v[228:229], v163
	v_cvt_pk_f32_fp8_sdwa v[230:231], v163 src0_sel:WORD_1
	v_pk_fma_f32 v[120:121], v[224:225], v[248:249], v[120:121] op_sel_hi:[1,0,1]
	v_pk_fma_f32 v[122:123], v[226:227], v[248:249], v[122:123] op_sel_hi:[1,0,1]
	v_pk_fma_f32 v[124:125], v[228:229], v[248:249], v[124:125] op_sel_hi:[1,0,1]
	v_pk_fma_f32 v[126:127], v[230:231], v[248:249], v[126:127] op_sel_hi:[1,0,1]
	s_waitcnt vmcnt(18)
	v_cvt_pk_f32_fp8_e32 v[224:225], v164
	v_cvt_pk_f32_fp8_sdwa v[226:227], v164 src0_sel:WORD_1
	v_cvt_pk_f32_fp8_e32 v[228:229], v165
	v_cvt_pk_f32_fp8_sdwa v[230:231], v165 src0_sel:WORD_1
	v_pk_fma_f32 v[112:113], v[224:225], v[248:249], v[112:113] op_sel:[0,1,0] op_sel_hi:[1,1,1]
	v_pk_fma_f32 v[114:115], v[226:227], v[248:249], v[114:115] op_sel:[0,1,0] op_sel_hi:[1,1,1]
	v_pk_fma_f32 v[116:117], v[228:229], v[248:249], v[116:117] op_sel:[0,1,0] op_sel_hi:[1,1,1]
	v_pk_fma_f32 v[118:119], v[230:231], v[248:249], v[118:119] op_sel:[0,1,0] op_sel_hi:[1,1,1]
	v_cvt_pk_f32_fp8_e32 v[224:225], v166
	v_cvt_pk_f32_fp8_sdwa v[226:227], v166 src0_sel:WORD_1
	v_cvt_pk_f32_fp8_e32 v[228:229], v167
	v_cvt_pk_f32_fp8_sdwa v[230:231], v167 src0_sel:WORD_1
	v_pk_fma_f32 v[120:121], v[224:225], v[248:249], v[120:121] op_sel:[0,1,0] op_sel_hi:[1,1,1]
	v_pk_fma_f32 v[122:123], v[226:227], v[248:249], v[122:123] op_sel:[0,1,0] op_sel_hi:[1,1,1]
	v_pk_fma_f32 v[124:125], v[228:229], v[248:249], v[124:125] op_sel:[0,1,0] op_sel_hi:[1,1,1]
	v_pk_fma_f32 v[126:127], v[230:231], v[248:249], v[126:127] op_sel:[0,1,0] op_sel_hi:[1,1,1]
	s_waitcnt vmcnt(17)
	v_cvt_pk_f32_fp8_e32 v[224:225], v168
	v_cvt_pk_f32_fp8_sdwa v[226:227], v168 src0_sel:WORD_1
	v_cvt_pk_f32_fp8_e32 v[228:229], v169
	v_cvt_pk_f32_fp8_sdwa v[230:231], v169 src0_sel:WORD_1
	v_pk_fma_f32 v[112:113], v[224:225], v[250:251], v[112:113] op_sel_hi:[1,0,1]
	v_pk_fma_f32 v[114:115], v[226:227], v[250:251], v[114:115] op_sel_hi:[1,0,1]
	v_pk_fma_f32 v[116:117], v[228:229], v[250:251], v[116:117] op_sel_hi:[1,0,1]
	v_pk_fma_f32 v[118:119], v[230:231], v[250:251], v[118:119] op_sel_hi:[1,0,1]
	v_cvt_pk_f32_fp8_e32 v[224:225], v170
	v_cvt_pk_f32_fp8_sdwa v[226:227], v170 src0_sel:WORD_1
	v_cvt_pk_f32_fp8_e32 v[228:229], v171
	v_cvt_pk_f32_fp8_sdwa v[230:231], v171 src0_sel:WORD_1
	v_pk_fma_f32 v[120:121], v[224:225], v[250:251], v[120:121] op_sel_hi:[1,0,1]
	v_pk_fma_f32 v[122:123], v[226:227], v[250:251], v[122:123] op_sel_hi:[1,0,1]
	v_pk_fma_f32 v[124:125], v[228:229], v[250:251], v[124:125] op_sel_hi:[1,0,1]
	v_pk_fma_f32 v[126:127], v[230:231], v[250:251], v[126:127] op_sel_hi:[1,0,1]
	s_waitcnt vmcnt(16)
	v_cvt_pk_f32_fp8_e32 v[224:225], v172
	v_cvt_pk_f32_fp8_sdwa v[226:227], v172 src0_sel:WORD_1
	v_cvt_pk_f32_fp8_e32 v[228:229], v173
	v_cvt_pk_f32_fp8_sdwa v[230:231], v173 src0_sel:WORD_1
	v_pk_fma_f32 v[112:113], v[224:225], v[250:251], v[112:113] op_sel:[0,1,0] op_sel_hi:[1,1,1]
	v_pk_fma_f32 v[114:115], v[226:227], v[250:251], v[114:115] op_sel:[0,1,0] op_sel_hi:[1,1,1]
	v_pk_fma_f32 v[116:117], v[228:229], v[250:251], v[116:117] op_sel:[0,1,0] op_sel_hi:[1,1,1]
	v_pk_fma_f32 v[118:119], v[230:231], v[250:251], v[118:119] op_sel:[0,1,0] op_sel_hi:[1,1,1]
	v_cvt_pk_f32_fp8_e32 v[224:225], v174
	v_cvt_pk_f32_fp8_sdwa v[226:227], v174 src0_sel:WORD_1
	v_cvt_pk_f32_fp8_e32 v[228:229], v175
	v_cvt_pk_f32_fp8_sdwa v[230:231], v175 src0_sel:WORD_1
	v_pk_fma_f32 v[120:121], v[224:225], v[250:251], v[120:121] op_sel:[0,1,0] op_sel_hi:[1,1,1]
	v_pk_fma_f32 v[122:123], v[226:227], v[250:251], v[122:123] op_sel:[0,1,0] op_sel_hi:[1,1,1]
	v_pk_fma_f32 v[124:125], v[228:229], v[250:251], v[124:125] op_sel:[0,1,0] op_sel_hi:[1,1,1]
	v_pk_fma_f32 v[126:127], v[230:231], v[250:251], v[126:127] op_sel:[0,1,0] op_sel_hi:[1,1,1]
	s_sub_i32 s90, s90, 1
	s_cmp_eq_u32 s90, 0
	s_cbranch_scc1 .LV_sw3
.LV_t7_s3:
	s_waitcnt lgkmcnt(0)
	buffer_load_dwordx4 v[160:163], v[232:233], s[60:63], 0 idxen offen
	buffer_load_dwordx4 v[164:167], v[234:235], s[60:63], 0 idxen offen
	buffer_load_dwordx4 v[168:171], v[236:237], s[60:63], 0 idxen offen
	buffer_load_dwordx4 v[172:175], v[238:239], s[60:63], 0 idxen offen
	ds_read_b32 v232, v213 offset:128
	ds_read_b32 v234, v213 offset:132
	ds_read_b32 v236, v213 offset:136
	ds_read_b32 v238, v213 offset:140
	ds_read_b128 v[208:211], v213 offset:5056
	s_waitcnt vmcnt(19)
	v_cvt_pk_f32_fp8_e32 v[224:225], v176
	v_cvt_pk_f32_fp8_sdwa v[226:227], v176 src0_sel:WORD_1
	v_cvt_pk_f32_fp8_e32 v[228:229], v177
	v_cvt_pk_f32_fp8_sdwa v[230:231], v177 src0_sel:WORD_1
	v_pk_fma_f32 v[112:113], v[224:225], v[252:253], v[112:113] op_sel_hi:[1,0,1]
	v_pk_fma_f32 v[114:115], v[226:227], v[252:253], v[114:115] op_sel_hi:[1,0,1]
	v_pk_fma_f32 v[116:117], v[228:229], v[252:253], v[116:117] op_sel_hi:[1,0,1]
	v_pk_fma_f32 v[118:119], v[230:231], v[252:253], v[118:119] op_sel_hi:[1,0,1]
	v_cvt_pk_f32_fp8_e32 v[224:225], v178
	v_cvt_pk_f32_fp8_sdwa v[226:227], v178 src0_sel:WORD_1
	v_cvt_pk_f32_fp8_e32 v[228:229], v179
	v_cvt_pk_f32_fp8_sdwa v[230:231], v179 src0_sel:WORD_1
	v_pk_fma_f32 v[120:121], v[224:225], v[252:253], v[120:121] op_sel_hi:[1,0,1]
	v_pk_fma_f32 v[122:123], v[226:227], v[252:253], v[122:123] op_sel_hi:[1,0,1]
	v_pk_fma_f32 v[124:125], v[228:229], v[252:253], v[124:125] op_sel_hi:[1,0,1]
	v_pk_fma_f32 v[126:127], v[230:231], v[252:253], v[126:127] op_sel_hi:[1,0,1]
	s_waitcnt vmcnt(18)
	v_cvt_pk_f32_fp8_e32 v[224:225], v180
	v_cvt_pk_f32_fp8_sdwa v[226:227], v180 src0_sel:WORD_1
	v_cvt_pk_f32_fp8_e32 v[228:229], v181
	v_cvt_pk_f32_fp8_sdwa v[230:231], v181 src0_sel:WORD_1
	v_pk_fma_f32 v[112:113], v[224:225], v[252:253], v[112:113] op_sel:[0,1,0] op_sel_hi:[1,1,1]
	v_pk_fma_f32 v[114:115], v[226:227], v[252:253], v[114:115] op_sel:[0,1,0] op_sel_hi:[1,1,1]
	v_pk_fma_f32 v[116:117], v[228:229], v[252:253], v[116:117] op_sel:[0,1,0] op_sel_hi:[1,1,1]
	v_pk_fma_f32 v[118:119], v[230:231], v[252:253], v[118:119] op_sel:[0,1,0] op_sel_hi:[1,1,1]
	v_cvt_pk_f32_fp8_e32 v[224:225], v182
	v_cvt_pk_f32_fp8_sdwa v[226:227], v182 src0_sel:WORD_1
	v_cvt_pk_f32_fp8_e32 v[228:229], v183
	v_cvt_pk_f32_fp8_sdwa v[230:231], v183 src0_sel:WORD_1
	v_pk_fma_f32 v[120:121], v[224:225], v[252:253], v[120:121] op_sel:[0,1,0] op_sel_hi:[1,1,1]
	v_pk_fma_f32 v[122:123], v[226:227], v[252:253], v[122:123] op_sel:[0,1,0] op_sel_hi:[1,1,1]
	v_pk_fma_f32 v[124:125], v[228:229], v[252:253], v[124:125] op_sel:[0,1,0] op_sel_hi:[1,1,1]
	v_pk_fma_f32 v[126:127], v[230:231], v[252:253], v[126:127] op_sel:[0,1,0] op_sel_hi:[1,1,1]
	s_waitcnt vmcnt(17)
	v_cvt_pk_f32_fp8_e32 v[224:225], v184
	v_cvt_pk_f32_fp8_sdwa v[226:227], v184 src0_sel:WORD_1
	v_cvt_pk_f32_fp8_e32 v[228:229], v185
	v_cvt_pk_f32_fp8_sdwa v[230:231], v185 src0_sel:WORD_1
	v_pk_fma_f32 v[112:113], v[224:225], v[254:255], v[112:113] op_sel_hi:[1,0,1]
	v_pk_fma_f32 v[114:115], v[226:227], v[254:255], v[114:115] op_sel_hi:[1,0,1]
	v_pk_fma_f32 v[116:117], v[228:229], v[254:255], v[116:117] op_sel_hi:[1,0,1]
	v_pk_fma_f32 v[118:119], v[230:231], v[254:255], v[118:119] op_sel_hi:[1,0,1]
	v_cvt_pk_f32_fp8_e32 v[224:225], v186
	v_cvt_pk_f32_fp8_sdwa v[226:227], v186 src0_sel:WORD_1
	v_cvt_pk_f32_fp8_e32 v[228:229], v187
	v_cvt_pk_f32_fp8_sdwa v[230:231], v187 src0_sel:WORD_1
	v_pk_fma_f32 v[120:121], v[224:225], v[254:255], v[120:121] op_sel_hi:[1,0,1]
	v_pk_fma_f32 v[122:123], v[226:227], v[254:255], v[122:123] op_sel_hi:[1,0,1]
	v_pk_fma_f32 v[124:125], v[228:229], v[254:255], v[124:125] op_sel_hi:[1,0,1]
	v_pk_fma_f32 v[126:127], v[230:231], v[254:255], v[126:127] op_sel_hi:[1,0,1]
	s_waitcnt vmcnt(16)
	v_cvt_pk_f32_fp8_e32 v[224:225], v188
	v_cvt_pk_f32_fp8_sdwa v[226:227], v188 src0_sel:WORD_1
	v_cvt_pk_f32_fp8_e32 v[228:229], v189
	v_cvt_pk_f32_fp8_sdwa v[230:231], v189 src0_sel:WORD_1
	v_pk_fma_f32 v[112:113], v[224:225], v[254:255], v[112:113] op_sel:[0,1,0] op_sel_hi:[1,1,1]
	v_pk_fma_f32 v[114:115], v[226:227], v[254:255], v[114:115] op_sel:[0,1,0] op_sel_hi:[1,1,1]
	v_pk_fma_f32 v[116:117], v[228:229], v[254:255], v[116:117] op_sel:[0,1,0] op_sel_hi:[1,1,1]
	v_pk_fma_f32 v[118:119], v[230:231], v[254:255], v[118:119] op_sel:[0,1,0] op_sel_hi:[1,1,1]
	v_cvt_pk_f32_fp8_e32 v[224:225], v190
	v_cvt_pk_f32_fp8_sdwa v[226:227], v190 src0_sel:WORD_1
	v_cvt_pk_f32_fp8_e32 v[228:229], v191
	v_cvt_pk_f32_fp8_sdwa v[230:231], v191 src0_sel:WORD_1
	v_pk_fma_f32 v[120:121], v[224:225], v[254:255], v[120:121] op_sel:[0,1,0] op_sel_hi:[1,1,1]
	v_pk_fma_f32 v[122:123], v[226:227], v[254:255], v[122:123] op_sel:[0,1,0] op_sel_hi:[1,1,1]
	v_pk_fma_f32 v[124:125], v[228:229], v[254:255], v[124:125] op_sel:[0,1,0] op_sel_hi:[1,1,1]
	v_pk_fma_f32 v[126:127], v[230:231], v[254:255], v[126:127] op_sel:[0,1,0] op_sel_hi:[1,1,1]
	s_sub_i32 s90, s90, 1
	s_cmp_eq_u32 s90, 0
	s_cbranch_scc1 .LV_sw4
.LV_t7_s4:
	s_waitcnt lgkmcnt(0)
	buffer_load_dwordx4 v[176:179], v[232:233], s[60:63], 0 idxen offen
	buffer_load_dwordx4 v[180:183], v[234:235], s[60:63], 0 idxen offen
	buffer_load_dwordx4 v[184:187], v[236:237], s[60:63], 0 idxen offen
	buffer_load_dwordx4 v[188:191], v[238:239], s[60:63], 0 idxen offen
	ds_read_b32 v232, v213 offset:144
	ds_read_b32 v234, v213 offset:148
	ds_read_b32 v236, v213 offset:152
	ds_read_b32 v238, v213 offset:156
	ds_read_b128 v[248:251], v213 offset:5072
	s_waitcnt vmcnt(19)
	v_cvt_pk_f32_fp8_e32 v[224:225], v192
	v_cvt_pk_f32_fp8_sdwa v[226:227], v192 src0_sel:WORD_1
	v_cvt_pk_f32_fp8_e32 v[228:229], v193
	v_cvt_pk_f32_fp8_sdwa v[230:231], v193 src0_sel:WORD_1
	v_pk_fma_f32 v[112:113], v[224:225], v[208:209], v[112:113] op_sel_hi:[1,0,1]
	v_pk_fma_f32 v[114:115], v[226:227], v[208:209], v[114:115] op_sel_hi:[1,0,1]
	v_pk_fma_f32 v[116:117], v[228:229], v[208:209], v[116:117] op_sel_hi:[1,0,1]
	v_pk_fma_f32 v[118:119], v[230:231], v[208:209], v[118:119] op_sel_hi:[1,0,1]
	v_cvt_pk_f32_fp8_e32 v[224:225], v194
	v_cvt_pk_f32_fp8_sdwa v[226:227], v194 src0_sel:WORD_1
	v_cvt_pk_f32_fp8_e32 v[228:229], v195
	v_cvt_pk_f32_fp8_sdwa v[230:231], v195 src0_sel:WORD_1
	v_pk_fma_f32 v[120:121], v[224:225], v[208:209], v[120:121] op_sel_hi:[1,0,1]
	v_pk_fma_f32 v[122:123], v[226:227], v[208:209], v[122:123] op_sel_hi:[1,0,1]
	v_pk_fma_f32 v[124:125], v[228:229], v[208:209], v[124:125] op_sel_hi:[1,0,1]
	v_pk_fma_f32 v[126:127], v[230:231], v[208:209], v[126:127] op_sel_hi:[1,0,1]
	s_waitcnt vmcnt(18)
	v_cvt_pk_f32_fp8_e32 v[224:225], v196
	v_cvt_pk_f32_fp8_sdwa v[226:227], v196 src0_sel:WORD_1
	v_cvt_pk_f32_fp8_e32 v[228:229], v197
	v_cvt_pk_f32_fp8_sdwa v[230:231], v197 src0_sel:WORD_1
	v_pk_fma_f32 v[112:113], v[224:225], v[208:209], v[112:113] op_sel:[0,1,0] op_sel_hi:[1,1,1]
	v_pk_fma_f32 v[114:115], v[226:227], v[208:209], v[114:115] op_sel:[0,1,0] op_sel_hi:[1,1,1]
	v_pk_fma_f32 v[116:117], v[228:229], v[208:209], v[116:117] op_sel:[0,1,0] op_sel_hi:[1,1,1]
	v_pk_fma_f32 v[118:119], v[230:231], v[208:209], v[118:119] op_sel:[0,1,0] op_sel_hi:[1,1,1]
	v_cvt_pk_f32_fp8_e32 v[224:225], v198
	v_cvt_pk_f32_fp8_sdwa v[226:227], v198 src0_sel:WORD_1
	v_cvt_pk_f32_fp8_e32 v[228:229], v199
	v_cvt_pk_f32_fp8_sdwa v[230:231], v199 src0_sel:WORD_1
	v_pk_fma_f32 v[120:121], v[224:225], v[208:209], v[120:121] op_sel:[0,1,0] op_sel_hi:[1,1,1]
	v_pk_fma_f32 v[122:123], v[226:227], v[208:209], v[122:123] op_sel:[0,1,0] op_sel_hi:[1,1,1]
	v_pk_fma_f32 v[124:125], v[228:229], v[208:209], v[124:125] op_sel:[0,1,0] op_sel_hi:[1,1,1]
	v_pk_fma_f32 v[126:127], v[230:231], v[208:209], v[126:127] op_sel:[0,1,0] op_sel_hi:[1,1,1]
	s_waitcnt vmcnt(17)
	v_cvt_pk_f32_fp8_e32 v[224:225], v200
	v_cvt_pk_f32_fp8_sdwa v[226:227], v200 src0_sel:WORD_1
	v_cvt_pk_f32_fp8_e32 v[228:229], v201
	v_cvt_pk_f32_fp8_sdwa v[230:231], v201 src0_sel:WORD_1
	v_pk_fma_f32 v[112:113], v[224:225], v[210:211], v[112:113] op_sel_hi:[1,0,1]
	v_pk_fma_f32 v[114:115], v[226:227], v[210:211], v[114:115] op_sel_hi:[1,0,1]
	v_pk_fma_f32 v[116:117], v[228:229], v[210:211], v[116:117] op_sel_hi:[1,0,1]
	v_pk_fma_f32 v[118:119], v[230:231], v[210:211], v[118:119] op_sel_hi:[1,0,1]
	v_cvt_pk_f32_fp8_e32 v[224:225], v202
	v_cvt_pk_f32_fp8_sdwa v[226:227], v202 src0_sel:WORD_1
	v_cvt_pk_f32_fp8_e32 v[228:229], v203
	v_cvt_pk_f32_fp8_sdwa v[230:231], v203 src0_sel:WORD_1
	v_pk_fma_f32 v[120:121], v[224:225], v[210:211], v[120:121] op_sel_hi:[1,0,1]
	v_pk_fma_f32 v[122:123], v[226:227], v[210:211], v[122:123] op_sel_hi:[1,0,1]
	v_pk_fma_f32 v[124:125], v[228:229], v[210:211], v[124:125] op_sel_hi:[1,0,1]
	v_pk_fma_f32 v[126:127], v[230:231], v[210:211], v[126:127] op_sel_hi:[1,0,1]
	s_waitcnt vmcnt(16)
	v_cvt_pk_f32_fp8_e32 v[224:225], v204
	v_cvt_pk_f32_fp8_sdwa v[226:227], v204 src0_sel:WORD_1
	v_cvt_pk_f32_fp8_e32 v[228:229], v205
	v_cvt_pk_f32_fp8_sdwa v[230:231], v205 src0_sel:WORD_1
	v_pk_fma_f32 v[112:113], v[224:225], v[210:211], v[112:113] op_sel:[0,1,0] op_sel_hi:[1,1,1]
	v_pk_fma_f32 v[114:115], v[226:227], v[210:211], v[114:115] op_sel:[0,1,0] op_sel_hi:[1,1,1]
	v_pk_fma_f32 v[116:117], v[228:229], v[210:211], v[116:117] op_sel:[0,1,0] op_sel_hi:[1,1,1]
	v_pk_fma_f32 v[118:119], v[230:231], v[210:211], v[118:119] op_sel:[0,1,0] op_sel_hi:[1,1,1]
	v_cvt_pk_f32_fp8_e32 v[224:225], v206
	v_cvt_pk_f32_fp8_sdwa v[226:227], v206 src0_sel:WORD_1
	v_cvt_pk_f32_fp8_e32 v[228:229], v207
	v_cvt_pk_f32_fp8_sdwa v[230:231], v207 src0_sel:WORD_1
	v_pk_fma_f32 v[120:121], v[224:225], v[210:211], v[120:121] op_sel:[0,1,0] op_sel_hi:[1,1,1]
	v_pk_fma_f32 v[122:123], v[226:227], v[210:211], v[122:123] op_sel:[0,1,0] op_sel_hi:[1,1,1]
	v_pk_fma_f32 v[124:125], v[228:229], v[210:211], v[124:125] op_sel:[0,1,0] op_sel_hi:[1,1,1]
	v_pk_fma_f32 v[126:127], v[230:231], v[210:211], v[126:127] op_sel:[0,1,0] op_sel_hi:[1,1,1]
	v_add_u32_e32 v213, 80, v213
	s_add_i32 s21, s21, 5
	s_sub_i32 s90, s90, 1
	s_cmp_eq_u32 s90, 0
	s_cbranch_scc1 .LV_sw0
	s_branch .LV_t7_s0
